# strategy 4: one static s_setprio 1 for the younger half (waves 4-7) at kernel entry, all 160 per-MFMA-block s_setprio flips of the GEMM loops deleted
# baseline (speedup 1.0000x reference)
; #define LAS __attribute__((address_space(3)))
; __global__ void __launch_bounds__(512, 2) mk_fwd(Args a) {
;     ...
;     const int tid = threadIdx.x, lane = tid & 63, wid = __builtin_amdgcn_readfirstlane(tid >> 6);
;     const int G = gridDim.x, bid = blockIdx.x;
;     unsigned char* ws = a.ws;
;     float* SSQ0 = (float*)(ws + WS_SSQ0); float* SSQ1 = (float*)(ws + WS_SSQ1); float* SSQ2 = (float*)(ws + WS_SSQ2); float* SSQ3 = (float*)(ws + WS_SSQ3);
;     float* SSQ4 = (float*)(ws + WS_SSQ4); float* SSQM = (float*)(ws + WS_SSQM);
;     float* C128 = (float*)(ws + WS_C128); float* S128 = (float*)(ws + WS_S128); float* C64 = (float*)(ws + WS_C64); float* S64 = (float*)(ws + WS_S64);
;     bf16_t* MEMB = (bf16_t*)(ws + WS_MEMB); bf16_t* XK = (bf16_t*)(ws + WS_XK); bf16_t* XVT = (bf16_t*)(ws + WS_XVT);
;     bf16_t* W1GU = (bf16_t*)(ws + WS_W1GU); bf16_t* W1D = (bf16_t*)(ws + WS_W1D); bf16_t* WIN = (bf16_t*)(ws + WS_WIN); bf16_t* WOUT = (bf16_t*)(ws + WS_WOUT);
;     bf16_t* WQ = (bf16_t*)(ws + WS_WQ); bf16_t* WKV = (bf16_t*)(ws + WS_WKV); bf16_t* WO = (bf16_t*)(ws + WS_WO); bf16_t* W2GU = (bf16_t*)(ws + WS_W2GU); bf16_t* W2D = (bf16_t*)(ws + WS_W2D);
;     bf16_t* XB = (bf16_t*)(ws + WS_XB); bf16_t* MIX = (bf16_t*)(ws + WS_MIX);
;     unsigned char* r1 = ws + WS_R1;
;     bf16_t* ACT = (bf16_t*)(r1 + R1_ACT); bf16_t* RQ = (bf16_t*)(r1 + R1_RQ); bf16_t* RK = (bf16_t*)(r1 + R1_RK); bf16_t* RV = (bf16_t*)(r1 + R1_RV); bf16_t* RG = (bf16_t*)(r1 + R1_RG);
;     bf16_t* SQ = (bf16_t*)(r1 + R1_SQ); bf16_t* SK = (bf16_t*)(r1 + R1_SK); bf16_t* SV = (bf16_t*)(r1 + R1_SV); float* STATE = (float*)(r1 + R1_STATE); bf16_t* SPREV = (bf16_t*)(r1 + R1_SPREV);
;     bf16_t* XQ = (bf16_t*)(r1 + R1_XQ); bf16_t* XO = (bf16_t*)(r1 + R1_XO);
;     const int lo = a.ph_lo, hi_ph = a.ph_hi;
;     ...
;     XcdBarrier xbar; xbar.bar = (unsigned*)(ws + WS_CTL); xbar.x = 0; xbar.st = nullptr;
;     if (hi_ph - lo > 1) {
;         volatile LAS unsigned* bst = (volatile LAS unsigned*)(lds + LDS_BAR_OFF);
;         if (tid < 2) bst[tid] = 0u;
;         __syncthreads();
;         xbar = xcd_barrier_post((unsigned*)(ws + WS_CTL), bst);
;     }
_Z6mk_fwd4Args:
	s_load_dwordx2 s[84:85], s[0:1], 0xb0
	s_load_dwordx4 s[4:7], s[0:1], 0xa0
	s_load_dwordx4 s[88:91], s[0:1], 0xb8
	s_load_dword s86, s[0:1], 0xc8
	s_add_u32 s92, s0, 0xc8
	s_addc_u32 s93, s1, 0
	s_waitcnt lgkmcnt(0)
	v_writelane_b32 v254, s4, 0
	s_mov_b32 s87, s2
	s_add_u32 s2, s84, 0x30000
	v_writelane_b32 v254, s5, 1
	v_writelane_b32 v254, s6, 2
	v_writelane_b32 v254, s7, 3
	s_load_dwordx8 s[4:11], s[0:1], 0x80
	s_addc_u32 s3, s85, 0
	v_and_b32_e32 v1, 0x3ff, v0
	s_waitcnt lgkmcnt(0)
	v_writelane_b32 v254, s4, 4
	s_nop 1
	v_writelane_b32 v254, s5, 5
	v_writelane_b32 v254, s6, 6
	v_writelane_b32 v254, s7, 7
	v_writelane_b32 v254, s8, 8
	v_writelane_b32 v254, s9, 9
	v_writelane_b32 v254, s10, 10
	v_writelane_b32 v254, s11, 11
	v_writelane_b32 v254, s2, 12
	v_readfirstlane_b32 s64, v1
	s_nop 0
	v_writelane_b32 v254, s3, 13
	s_lshr_b32 s98, s64, 6
	s_cmp_lt_u32 s98, 4
	s_cbranch_scc1 .Lprio_done
	s_setprio 1
.Lprio_done:
	s_sub_i32 s2, s89, s88
	s_cmp_lt_i32 s2, 2
	s_cselect_b64 s[4:5], -1, 0
	v_writelane_b32 v254, s4, 14
	s_mov_b32 s2, 0
	s_mov_b32 s3, 0
	v_writelane_b32 v254, s5, 15
	s_and_b64 vcc, exec, s[4:5]
	v_writelane_b32 v254, s2, 16
	s_cbranch_vccnz .LBB0_7
	v_cmp_gt_u32_e32 vcc, 2, v1
	s_and_saveexec_b64 s[2:3], vcc
	v_lshl_add_u32 v2, v1, 2, 0
	v_add_u32_e32 v2, 0x22000, v2
	v_mov_b32_e32 v3, 0
	ds_write_b32 v2, v3
	s_or_b64 exec, exec, s[2:3]
	s_waitcnt lgkmcnt(0)
	s_barrier
	s_getreg_b32 s2, hwreg(HW_REG_XCC_ID, 0, 4)
	s_and_b32 s2, s2, 15
	v_writelane_b32 v254, s2, 16
	v_cmp_eq_u32_e32 vcc, 0, v1
	s_and_saveexec_b64 s[2:3], vcc
	s_cbranch_execz .LBB0_6
	s_mov_b64 s[4:5], exec
	v_mbcnt_lo_u32_b32 v2, s4, 0
	v_mbcnt_hi_u32_b32 v2, s5, v2
	v_cmp_eq_u32_e32 vcc, 0, v2
	s_and_b64 s[6:7], exec, vcc
	s_mov_b64 exec, s[6:7]
	s_cbranch_execz .LBB0_6
	v_readlane_b32 s6, v254, 16
	s_bcnt1_i32_b64 s4, s[4:5]
	s_lshl_b32 s6, s6, 8
	v_mov_b32_e32 v3, s4
	v_readlane_b32 s4, v254, 12
	v_mov_b32_e32 v2, s6
	v_readlane_b32 s5, v254, 13
	s_nop 4
	global_atomic_add v2, v3, s[4:5] offset:1024

; #define PG8_STAGE(bufoff, gbase, voff) do { _Pragma("unroll") for (int _i = 0; _i < 2; ++_i) \
;         __builtin_amdgcn_global_load_lds((const unsigned*)((const char*)(gbase) + (voff)[_i]), (PG8_LAS unsigned*)(lds + (bufoff) + ldsw + _i * 8192), 16, 0, 0); } while (0)
; #define PG8_STAGEB(bufoff, gbase, voff) do { _Pragma("unroll") for (int _i = 0; _i < 2; ++_i) \
;         __builtin_amdgcn_global_load_lds((const unsigned*)((const char*)(gbase) + (voff)[_i]), (PG8_LAS unsigned*)(lds + (bufoff) + ldsw + _i * 8192), 16, 0, PG8_BAUX); } while (0)
; #define PG8_LDA(dst, b, h) do { _Pragma("unroll") for (int m = 0; m < 4; ++m) _Pragma("unroll") for (int k = 0; k < 2; ++k) dst[m][k] = *(const PG8_LAS bf16x8*)(lds + PG8_SA(b, h) + aoff + m * 2048 + k * 1024); } while (0)
; #define PG8_LDB(dst, b, h) do { _Pragma("unroll") for (int n = 0; n < 2; ++n) _Pragma("unroll") for (int k = 0; k < 2; ++k) dst[n][k] = *(const PG8_LAS bf16x8*)(lds + PG8_SB(b, h) + boff + n * 2048 + k * 1024); } while (0)
; #define PG8_MMA(ai, bj, At, Bt) do { __builtin_amdgcn_s_setprio(1); _Pragma("unroll") for (int m = 0; m < 4; ++m) _Pragma("unroll") for (int n = 0; n < 2; ++n) _Pragma("unroll") for (int k = 0; k < 2; ++k) \
;         acc[ai][bj][m][n] = __builtin_amdgcn_mfma_f32_16x16x32_bf16(Bt[n][k], At[m][k], acc[ai][bj][m][n], 0, 0, 0); __builtin_amdgcn_s_setprio(0); } while (0)
; #define PG8_WAIT_V(n) asm volatile("s_waitcnt vmcnt(" #n ")" ::: "memory")
; #define PG8_WAIT_L(n) asm volatile("s_waitcnt lgkmcnt(" #n ")" ::: "memory")
; #define PG8_BAR __builtin_amdgcn_s_barrier()
; #define PG8_SCHED __builtin_amdgcn_sched_barrier(0)
; template <class Epi, class Sched, bool ALIGN_EPI = false, bool SP2 = false>
; __device__ __forceinline__ void gemm_phase(PG8_LAS unsigned char* lds, const Gemm g, const Sched& S, const Epi& E) {
;     ...
;             PG8_LDB(B0, 0, 0); PG8_LDB(B1, 0, 1); PG8_SCHED; PG8_LDA(At, 0, 0); PG8_STAGE(PG8_SA(1, 1), a1 + hstep, voffA);
;             PG8_WAIT_V(8); PG8_WAIT_L(0); PG8_BAR; PG8_MMA(0, 0, At, B0); PG8_MMA(0, 1, At, B1); PG8_BAR; PG8_SCHED;
;             PG8_LDA(At, 0, 1); PG8_STAGEB(PG8_SB(0, 0), b2, voffB); PG8_STAGEB(PG8_SB(0, 1), b2 + hstep, voffB); PG8_STAGE(PG8_SA(0, 0), a2, voffA);
;             PG8_WAIT_V(8); PG8_WAIT_L(0); PG8_BAR; PG8_MMA(1, 0, At, B0); PG8_MMA(1, 1, At, B1); PG8_BAR; PG8_SCHED;
.LBB0_365:
	ds_read_b128 v[162:165], v158
	ds_read_b128 v[166:169], v158 offset:1024
	ds_read_b128 v[170:173], v158 offset:2048
	ds_read_b128 v[174:177], v158 offset:3072
	ds_read_b128 v[178:181], v159
	ds_read_b128 v[182:185], v159 offset:1024
	ds_read_b128 v[186:189], v159 offset:2048
	ds_read_b128 v[192:195], v159 offset:3072
	s_add_u32 s30, s28, 0xfff80080
	s_addc_u32 s31, s29, -1
	s_cmp_eq_u32 s55, 28
	s_cselect_b32 s35, s21, s31
	s_cselect_b32 s34, s51, s30
	s_cselect_b32 s31, s19, s54
	s_cselect_b32 s30, s52, s53
	v_lshl_add_u64 v[228:229], s[28:29], 0, v[138:139]
	s_add_i32 m0, s40, 0xc000
	ds_read_b128 v[196:199], v160
	ds_read_b128 v[200:203], v160 offset:1024
	ds_read_b128 v[204:207], v160 offset:2048
	ds_read_b128 v[208:211], v160 offset:3072
	ds_read_b128 v[212:215], v160 offset:4096
	ds_read_b128 v[216:219], v160 offset:5120
	ds_read_b128 v[220:223], v160 offset:6144
	ds_read_b128 v[224:227], v160 offset:7168
	global_load_lds_dwordx4 v[228:229], off
	v_lshl_add_u64 v[228:229], s[28:29], 0, v[140:141]
	s_add_i32 m0, s40, 0xe000
	s_nop 0
	global_load_lds_dwordx4 v[228:229], off
	s_waitcnt vmcnt(8)
	s_waitcnt lgkmcnt(0)
	s_barrier
	s_waitcnt lgkmcnt(0)
	v_mfma_f32_16x16x32_bf16 v[122:125], v[162:165], v[196:199], v[122:125]
	v_mfma_f32_16x16x32_bf16 v[118:121], v[170:173], v[196:199], v[118:121]
	v_mfma_f32_16x16x32_bf16 v[110:113], v[162:165], v[204:207], v[110:113]
	v_mfma_f32_16x16x32_bf16 v[102:105], v[170:173], v[204:207], v[102:105]
	v_mfma_f32_16x16x32_bf16 v[94:97], v[162:165], v[212:215], v[94:97]
	v_mfma_f32_16x16x32_bf16 v[86:89], v[170:173], v[212:215], v[86:89]
	v_mfma_f32_16x16x32_bf16 v[78:81], v[162:165], v[220:223], v[78:81]
	v_mfma_f32_16x16x32_bf16 v[70:73], v[170:173], v[220:223], v[70:73]
	v_mfma_f32_16x16x32_bf16 v[122:125], v[166:169], v[200:203], v[122:125]
	v_mfma_f32_16x16x32_bf16 v[118:121], v[174:177], v[200:203], v[118:121]
	v_mfma_f32_16x16x32_bf16 v[110:113], v[166:169], v[208:211], v[110:113]
	v_mfma_f32_16x16x32_bf16 v[102:105], v[174:177], v[208:211], v[102:105]
	v_mfma_f32_16x16x32_bf16 v[94:97], v[166:169], v[216:219], v[94:97]
	v_mfma_f32_16x16x32_bf16 v[86:89], v[174:177], v[216:219], v[86:89]
	v_mfma_f32_16x16x32_bf16 v[78:81], v[166:169], v[224:227], v[78:81]
	v_mfma_f32_16x16x32_bf16 v[70:73], v[174:177], v[224:227], v[70:73]
	v_mfma_f32_16x16x32_bf16 v[126:129], v[178:181], v[196:199], v[126:129]
	v_mfma_f32_16x16x32_bf16 v[114:117], v[186:189], v[196:199], v[114:117]
	v_mfma_f32_16x16x32_bf16 v[106:109], v[178:181], v[204:207], v[106:109]
	v_mfma_f32_16x16x32_bf16 v[98:101], v[186:189], v[204:207], v[98:101]
	v_mfma_f32_16x16x32_bf16 v[90:93], v[178:181], v[212:215], v[90:93]
	v_mfma_f32_16x16x32_bf16 v[82:85], v[186:189], v[212:215], v[82:85]
	v_mfma_f32_16x16x32_bf16 v[74:77], v[178:181], v[220:223], v[74:77]
	v_mfma_f32_16x16x32_bf16 v[66:69], v[186:189], v[220:223], v[66:69]
	v_mfma_f32_16x16x32_bf16 v[126:129], v[182:185], v[200:203], v[126:129]
	v_mfma_f32_16x16x32_bf16 v[114:117], v[192:195], v[200:203], v[114:117]
	v_mfma_f32_16x16x32_bf16 v[106:109], v[182:185], v[208:211], v[106:109]
	v_mfma_f32_16x16x32_bf16 v[98:101], v[192:195], v[208:211], v[98:101]
	v_mfma_f32_16x16x32_bf16 v[90:93], v[182:185], v[216:219], v[90:93]
	v_mfma_f32_16x16x32_bf16 v[82:85], v[192:195], v[216:219], v[82:85]
	v_mfma_f32_16x16x32_bf16 v[74:77], v[182:185], v[224:227], v[74:77]
	v_mfma_f32_16x16x32_bf16 v[66:69], v[192:195], v[224:227], v[66:69]
	s_barrier
	s_add_i32 s56, s48, s33
	v_lshl_add_u64 v[228:229], s[30:31], 0, v[132:133]
	s_mov_b32 m0, s56
	ds_read_b128 v[196:199], v160 offset:16384
	ds_read_b128 v[200:203], v160 offset:17408
	ds_read_b128 v[204:207], v160 offset:18432
	ds_read_b128 v[208:211], v160 offset:19456
	ds_read_b128 v[212:215], v160 offset:20480
	ds_read_b128 v[216:219], v160 offset:21504
	ds_read_b128 v[220:223], v160 offset:22528
	ds_read_b128 v[224:227], v160 offset:23552
	global_load_lds_dwordx4 v[228:229], off
	s_add_i32 m0, s56, 0x2000
	s_add_u32 s56, s30, 0x80000
	v_lshl_add_u64 v[230:231], s[30:31], 0, v[136:137]
	s_addc_u32 s57, s31, 0
	s_add_i32 s58, s49, s33
	global_load_lds_dwordx4 v[230:231], off
	v_lshl_add_u64 v[232:233], s[56:57], 0, v[132:133]
	s_mov_b32 m0, s58
	v_lshl_add_u64 v[234:235], s[34:35], 0, v[134:135]
	global_load_lds_dwordx4 v[232:233], off
	v_lshl_add_u64 v[232:233], s[56:57], 0, v[136:137]
	s_add_i32 m0, s58, 0x2000
	s_nop 0
	global_load_lds_dwordx4 v[232:233], off
	v_lshl_add_u64 v[232:233], s[34:35], 0, v[130:131]
	s_mov_b32 m0, s40
	s_nop 0
	global_load_lds_dwordx4 v[232:233], off
	s_mov_b32 m0, s41
	s_nop 0
	global_load_lds_dwordx4 v[234:235], off
	s_waitcnt vmcnt(8)
	s_waitcnt lgkmcnt(0)
	s_barrier
; #define PG8_STAGE(bufoff, gbase, voff) do { _Pragma("unroll") for (int _i = 0; _i < 2; ++_i) \
;         __builtin_amdgcn_global_load_lds((const unsigned*)((const char*)(gbase) + (voff)[_i]), (PG8_LAS unsigned*)(lds + (bufoff) + ldsw + _i * 8192), 16, 0, 0); } while (0)
; #define PG8_LDA(dst, b, h) do { _Pragma("unroll") for (int m = 0; m < 4; ++m) _Pragma("unroll") for (int k = 0; k < 2; ++k) dst[m][k] = *(const PG8_LAS bf16x8*)(lds + PG8_SA(b, h) + aoff + m * 2048 + k * 1024); } while (0)
; #define PG8_LDB(dst, b, h) do { _Pragma("unroll") for (int n = 0; n < 2; ++n) _Pragma("unroll") for (int k = 0; k < 2; ++k) dst[n][k] = *(const PG8_LAS bf16x8*)(lds + PG8_SB(b, h) + boff + n * 2048 + k * 1024); } while (0)
; #define PG8_MMA(ai, bj, At, Bt) do { __builtin_amdgcn_s_setprio(1); _Pragma("unroll") for (int m = 0; m < 4; ++m) _Pragma("unroll") for (int n = 0; n < 2; ++n) _Pragma("unroll") for (int k = 0; k < 2; ++k) \
;         acc[ai][bj][m][n] = __builtin_amdgcn_mfma_f32_16x16x32_bf16(Bt[n][k], At[m][k], acc[ai][bj][m][n], 0, 0, 0); __builtin_amdgcn_s_setprio(0); } while (0)
; #define PG8_WAIT_V(n) asm volatile("s_waitcnt vmcnt(" #n ")" ::: "memory")
; #define PG8_WAIT_L(n) asm volatile("s_waitcnt lgkmcnt(" #n ")" ::: "memory")
; #define PG8_BAR __builtin_amdgcn_s_barrier()
; #define PG8_SCHED __builtin_amdgcn_sched_barrier(0)
; template <class Epi, class Sched, bool ALIGN_EPI = false, bool SP2 = false>
; __device__ __forceinline__ void gemm_phase(PG8_LAS unsigned char* lds, const Gemm g, const Sched& S, const Epi& E) {
;     ...
;             PG8_WAIT_V(8); PG8_WAIT_L(0); PG8_BAR; PG8_MMA(1, 0, At, B0); PG8_MMA(1, 1, At, B1); PG8_BAR; PG8_SCHED;
;             PG8_LDB(B0, 1, 0); PG8_LDB(B1, 1, 1); PG8_SCHED; PG8_LDA(At, 1, 0); PG8_STAGE(PG8_SA(0, 1), a2 + hstep, voffA);
;             PG8_WAIT_V(8); PG8_WAIT_L(0); PG8_BAR; PG8_MMA(0, 0, At, B0); PG8_MMA(0, 1, At, B1); PG8_BAR; PG8_SCHED;
	s_waitcnt lgkmcnt(0)
	v_mfma_f32_16x16x32_bf16 v[62:65], v[162:165], v[196:199], v[62:65]
	v_mfma_f32_16x16x32_bf16 v[54:57], v[170:173], v[196:199], v[54:57]
	v_mfma_f32_16x16x32_bf16 v[46:49], v[162:165], v[204:207], v[46:49]
	v_mfma_f32_16x16x32_bf16 v[38:41], v[170:173], v[204:207], v[38:41]
	v_mfma_f32_16x16x32_bf16 v[30:33], v[162:165], v[212:215], v[30:33]
	v_mfma_f32_16x16x32_bf16 v[22:25], v[170:173], v[212:215], v[22:25]
	v_mfma_f32_16x16x32_bf16 v[14:17], v[162:165], v[220:223], v[14:17]
	v_mfma_f32_16x16x32_bf16 v[6:9], v[170:173], v[220:223], v[6:9]
	v_mfma_f32_16x16x32_bf16 v[62:65], v[166:169], v[200:203], v[62:65]
	v_mfma_f32_16x16x32_bf16 v[54:57], v[174:177], v[200:203], v[54:57]
	v_mfma_f32_16x16x32_bf16 v[46:49], v[166:169], v[208:211], v[46:49]
	v_mfma_f32_16x16x32_bf16 v[38:41], v[174:177], v[208:211], v[38:41]
	v_mfma_f32_16x16x32_bf16 v[30:33], v[166:169], v[216:219], v[30:33]
	v_mfma_f32_16x16x32_bf16 v[22:25], v[174:177], v[216:219], v[22:25]
	v_mfma_f32_16x16x32_bf16 v[14:17], v[166:169], v[224:227], v[14:17]
	v_mfma_f32_16x16x32_bf16 v[6:9], v[174:177], v[224:227], v[6:9]
	v_mfma_f32_16x16x32_bf16 v[58:61], v[178:181], v[196:199], v[58:61]
	v_mfma_f32_16x16x32_bf16 v[50:53], v[186:189], v[196:199], v[50:53]
	v_mfma_f32_16x16x32_bf16 v[42:45], v[178:181], v[204:207], v[42:45]
	v_mfma_f32_16x16x32_bf16 v[34:37], v[186:189], v[204:207], v[34:37]
	v_mfma_f32_16x16x32_bf16 v[26:29], v[178:181], v[212:215], v[26:29]
	v_mfma_f32_16x16x32_bf16 v[18:21], v[186:189], v[212:215], v[18:21]
	v_mfma_f32_16x16x32_bf16 v[10:13], v[178:181], v[220:223], v[10:13]
	v_mfma_f32_16x16x32_bf16 v[2:5], v[186:189], v[220:223], v[2:5]
	v_mfma_f32_16x16x32_bf16 v[58:61], v[182:185], v[200:203], v[58:61]
	v_mfma_f32_16x16x32_bf16 v[50:53], v[192:195], v[200:203], v[50:53]
	v_mfma_f32_16x16x32_bf16 v[42:45], v[182:185], v[208:211], v[42:45]
	v_mfma_f32_16x16x32_bf16 v[34:37], v[192:195], v[208:211], v[34:37]
	v_mfma_f32_16x16x32_bf16 v[26:29], v[182:185], v[216:219], v[26:29]
	v_mfma_f32_16x16x32_bf16 v[18:21], v[192:195], v[216:219], v[18:21]
	v_mfma_f32_16x16x32_bf16 v[10:13], v[182:185], v[224:227], v[10:13]
	v_mfma_f32_16x16x32_bf16 v[2:5], v[192:195], v[224:227], v[2:5]
	s_barrier
	s_add_i32 s56, 0, 0x18000
	v_add_u32_e32 v161, s56, v155
	s_add_i32 s57, 0, 0x1c000
	ds_read_b128 v[162:165], v161
	ds_read_b128 v[166:169], v161 offset:1024
	ds_read_b128 v[170:173], v161 offset:2048
	ds_read_b128 v[174:177], v161 offset:3072
	v_add_u32_e32 v161, s57, v155
	ds_read_b128 v[178:181], v161
	ds_read_b128 v[182:185], v161 offset:1024
	ds_read_b128 v[186:189], v161 offset:2048
	ds_read_b128 v[192:195], v161 offset:3072
	s_add_u32 s34, s34, 0x80000
	s_addc_u32 s35, s35, 0
	s_mov_b32 m0, s42
	v_lshl_add_u64 v[236:237], s[34:35], 0, v[130:131]
	ds_read_b128 v[196:199], v160 offset:32768
	ds_read_b128 v[200:203], v160 offset:33792
	ds_read_b128 v[204:207], v160 offset:34816
	ds_read_b128 v[208:211], v160 offset:35840
	ds_read_b128 v[212:215], v160 offset:36864
	ds_read_b128 v[216:219], v160 offset:37888
	ds_read_b128 v[220:223], v160 offset:38912
	ds_read_b128 v[224:227], v160 offset:39936
	global_load_lds_dwordx4 v[236:237], off
	v_lshl_add_u64 v[236:237], s[34:35], 0, v[134:135]
	s_mov_b32 m0, s43
	s_nop 0
	global_load_lds_dwordx4 v[236:237], off
	s_waitcnt vmcnt(8)
	s_waitcnt lgkmcnt(0)
	s_barrier
	s_waitcnt lgkmcnt(0)
	v_mfma_f32_16x16x32_bf16 v[122:125], v[162:165], v[196:199], v[122:125]
	v_mfma_f32_16x16x32_bf16 v[118:121], v[170:173], v[196:199], v[118:121]
	v_mfma_f32_16x16x32_bf16 v[110:113], v[162:165], v[204:207], v[110:113]
	v_mfma_f32_16x16x32_bf16 v[102:105], v[170:173], v[204:207], v[102:105]
	v_mfma_f32_16x16x32_bf16 v[94:97], v[162:165], v[212:215], v[94:97]
	v_mfma_f32_16x16x32_bf16 v[86:89], v[170:173], v[212:215], v[86:89]
	v_mfma_f32_16x16x32_bf16 v[78:81], v[162:165], v[220:223], v[78:81]
	v_mfma_f32_16x16x32_bf16 v[70:73], v[170:173], v[220:223], v[70:73]
	v_mfma_f32_16x16x32_bf16 v[122:125], v[166:169], v[200:203], v[122:125]
	v_mfma_f32_16x16x32_bf16 v[118:121], v[174:177], v[200:203], v[118:121]
	v_mfma_f32_16x16x32_bf16 v[110:113], v[166:169], v[208:211], v[110:113]
	v_mfma_f32_16x16x32_bf16 v[102:105], v[174:177], v[208:211], v[102:105]
	v_mfma_f32_16x16x32_bf16 v[94:97], v[166:169], v[216:219], v[94:97]
	v_mfma_f32_16x16x32_bf16 v[86:89], v[174:177], v[216:219], v[86:89]
	v_mfma_f32_16x16x32_bf16 v[78:81], v[166:169], v[224:227], v[78:81]
	v_mfma_f32_16x16x32_bf16 v[70:73], v[174:177], v[224:227], v[70:73]
	v_mfma_f32_16x16x32_bf16 v[126:129], v[178:181], v[196:199], v[126:129]
	v_mfma_f32_16x16x32_bf16 v[114:117], v[186:189], v[196:199], v[114:117]
	v_mfma_f32_16x16x32_bf16 v[106:109], v[178:181], v[204:207], v[106:109]
	v_mfma_f32_16x16x32_bf16 v[98:101], v[186:189], v[204:207], v[98:101]
	v_mfma_f32_16x16x32_bf16 v[90:93], v[178:181], v[212:215], v[90:93]
	v_mfma_f32_16x16x32_bf16 v[82:85], v[186:189], v[212:215], v[82:85]
	v_mfma_f32_16x16x32_bf16 v[74:77], v[178:181], v[220:223], v[74:77]
	v_mfma_f32_16x16x32_bf16 v[66:69], v[186:189], v[220:223], v[66:69]
	v_mfma_f32_16x16x32_bf16 v[126:129], v[182:185], v[200:203], v[126:129]
	v_mfma_f32_16x16x32_bf16 v[114:117], v[192:195], v[200:203], v[114:117]
	v_mfma_f32_16x16x32_bf16 v[106:109], v[182:185], v[208:211], v[106:109]
	v_mfma_f32_16x16x32_bf16 v[98:101], v[192:195], v[208:211], v[98:101]
	v_mfma_f32_16x16x32_bf16 v[90:93], v[182:185], v[216:219], v[90:93]
	v_mfma_f32_16x16x32_bf16 v[82:85], v[192:195], v[216:219], v[82:85]
	v_mfma_f32_16x16x32_bf16 v[74:77], v[182:185], v[224:227], v[74:77]
	v_mfma_f32_16x16x32_bf16 v[66:69], v[192:195], v[224:227], v[66:69]
	s_barrier
; #define PG8_STAGE(bufoff, gbase, voff) do { _Pragma("unroll") for (int _i = 0; _i < 2; ++_i) \
;         __builtin_amdgcn_global_load_lds((const unsigned*)((const char*)(gbase) + (voff)[_i]), (PG8_LAS unsigned*)(lds + (bufoff) + ldsw + _i * 8192), 16, 0, 0); } while (0)
; #define PG8_STAGEB(bufoff, gbase, voff) do { _Pragma("unroll") for (int _i = 0; _i < 2; ++_i) \
;         __builtin_amdgcn_global_load_lds((const unsigned*)((const char*)(gbase) + (voff)[_i]), (PG8_LAS unsigned*)(lds + (bufoff) + ldsw + _i * 8192), 16, 0, PG8_BAUX); } while (0)
; #define PG8_LDA(dst, b, h) do { _Pragma("unroll") for (int m = 0; m < 4; ++m) _Pragma("unroll") for (int k = 0; k < 2; ++k) dst[m][k] = *(const PG8_LAS bf16x8*)(lds + PG8_SA(b, h) + aoff + m * 2048 + k * 1024); } while (0)
; #define PG8_MMA(ai, bj, At, Bt) do { __builtin_amdgcn_s_setprio(1); _Pragma("unroll") for (int m = 0; m < 4; ++m) _Pragma("unroll") for (int n = 0; n < 2; ++n) _Pragma("unroll") for (int k = 0; k < 2; ++k) \
;         acc[ai][bj][m][n] = __builtin_amdgcn_mfma_f32_16x16x32_bf16(Bt[n][k], At[m][k], acc[ai][bj][m][n], 0, 0, 0); __builtin_amdgcn_s_setprio(0); } while (0)
; #define PG8_WAIT_V(n) asm volatile("s_waitcnt vmcnt(" #n ")" ::: "memory")
; #define PG8_WAIT_L(n) asm volatile("s_waitcnt lgkmcnt(" #n ")" ::: "memory")
; #define PG8_BAR __builtin_amdgcn_s_barrier()
; #define PG8_SCHED __builtin_amdgcn_sched_barrier(0)
; template <class Epi, class Sched, bool ALIGN_EPI = false, bool SP2 = false>
; __device__ __forceinline__ void gemm_phase(PG8_LAS unsigned char* lds, const Gemm g, const Sched& S, const Epi& E) {
;     ...
;             PG8_LDA(At, 1, 1); PG8_STAGEB(PG8_SB(1, 0), b3, voffB); PG8_STAGEB(PG8_SB(1, 1), b3 + hstep, voffB); PG8_STAGE(PG8_SA(1, 0), a3, voffA);
;             PG8_WAIT_V(8); PG8_WAIT_L(0); PG8_BAR; PG8_MMA(1, 0, At, B0); PG8_MMA(1, 1, At, B1); PG8_BAR; PG8_SCHED;
	s_add_i32 s34, s56, s33
	v_lshl_add_u64 v[228:229], v[228:229], 0, s[14:15]
	s_mov_b32 m0, s34
	ds_read_b128 v[196:199], v160 offset:49152
	ds_read_b128 v[200:203], v160 offset:50176
	ds_read_b128 v[204:207], v160 offset:51200
	ds_read_b128 v[208:211], v160 offset:52224
	ds_read_b128 v[212:215], v160 offset:53248
	ds_read_b128 v[216:219], v160 offset:54272
	ds_read_b128 v[220:223], v160 offset:55296
	ds_read_b128 v[224:227], v160 offset:56320
	global_load_lds_dwordx4 v[228:229], off
	s_add_i32 m0, s34, 0x2000
	s_add_u32 s30, s30, 0x80080
	v_lshl_add_u64 v[228:229], v[230:231], 0, s[14:15]
	s_addc_u32 s31, s31, 0
	s_add_i32 s34, s57, s33
	global_load_lds_dwordx4 v[228:229], off
	v_lshl_add_u64 v[228:229], s[30:31], 0, v[132:133]
	s_mov_b32 m0, s34
	s_nop 0
	global_load_lds_dwordx4 v[228:229], off
	v_lshl_add_u64 v[228:229], s[30:31], 0, v[136:137]
	s_add_i32 m0, s34, 0x2000
	s_nop 0
	global_load_lds_dwordx4 v[228:229], off
	v_lshl_add_u64 v[228:229], v[232:233], 0, s[14:15]
	s_mov_b32 m0, s45
	s_nop 0
	global_load_lds_dwordx4 v[228:229], off
	v_lshl_add_u64 v[228:229], v[234:235], 0, s[14:15]
	s_mov_b32 m0, s46
	s_nop 0
	global_load_lds_dwordx4 v[228:229], off
	s_waitcnt vmcnt(8)
	s_waitcnt lgkmcnt(0)
	s_barrier
	s_waitcnt lgkmcnt(0)
	v_mfma_f32_16x16x32_bf16 v[62:65], v[162:165], v[196:199], v[62:65]
	v_mfma_f32_16x16x32_bf16 v[54:57], v[170:173], v[196:199], v[54:57]
	v_mfma_f32_16x16x32_bf16 v[46:49], v[162:165], v[204:207], v[46:49]
	v_mfma_f32_16x16x32_bf16 v[38:41], v[170:173], v[204:207], v[38:41]
	v_mfma_f32_16x16x32_bf16 v[30:33], v[162:165], v[212:215], v[30:33]
	v_mfma_f32_16x16x32_bf16 v[22:25], v[170:173], v[212:215], v[22:25]
	v_mfma_f32_16x16x32_bf16 v[14:17], v[162:165], v[220:223], v[14:17]
	v_mfma_f32_16x16x32_bf16 v[6:9], v[170:173], v[220:223], v[6:9]
	v_mfma_f32_16x16x32_bf16 v[62:65], v[166:169], v[200:203], v[62:65]
	v_mfma_f32_16x16x32_bf16 v[54:57], v[174:177], v[200:203], v[54:57]
	v_mfma_f32_16x16x32_bf16 v[46:49], v[166:169], v[208:211], v[46:49]
	v_mfma_f32_16x16x32_bf16 v[38:41], v[174:177], v[208:211], v[38:41]
	v_mfma_f32_16x16x32_bf16 v[30:33], v[166:169], v[216:219], v[30:33]
	v_mfma_f32_16x16x32_bf16 v[22:25], v[174:177], v[216:219], v[22:25]
	v_mfma_f32_16x16x32_bf16 v[14:17], v[166:169], v[224:227], v[14:17]
	v_mfma_f32_16x16x32_bf16 v[6:9], v[174:177], v[224:227], v[6:9]
	v_mfma_f32_16x16x32_bf16 v[58:61], v[178:181], v[196:199], v[58:61]
	v_mfma_f32_16x16x32_bf16 v[50:53], v[186:189], v[196:199], v[50:53]
	v_mfma_f32_16x16x32_bf16 v[42:45], v[178:181], v[204:207], v[42:45]
	v_mfma_f32_16x16x32_bf16 v[34:37], v[186:189], v[204:207], v[34:37]
	v_mfma_f32_16x16x32_bf16 v[26:29], v[178:181], v[212:215], v[26:29]
	v_mfma_f32_16x16x32_bf16 v[18:21], v[186:189], v[212:215], v[18:21]
	v_mfma_f32_16x16x32_bf16 v[10:13], v[178:181], v[220:223], v[10:13]
	v_mfma_f32_16x16x32_bf16 v[2:5], v[186:189], v[220:223], v[2:5]
	v_mfma_f32_16x16x32_bf16 v[58:61], v[182:185], v[200:203], v[58:61]
	v_mfma_f32_16x16x32_bf16 v[50:53], v[192:195], v[200:203], v[50:53]
	v_mfma_f32_16x16x32_bf16 v[42:45], v[182:185], v[208:211], v[42:45]
	v_mfma_f32_16x16x32_bf16 v[34:37], v[192:195], v[208:211], v[34:37]
	v_mfma_f32_16x16x32_bf16 v[26:29], v[182:185], v[216:219], v[26:29]
	v_mfma_f32_16x16x32_bf16 v[18:21], v[192:195], v[216:219], v[18:21]
	v_mfma_f32_16x16x32_bf16 v[10:13], v[182:185], v[224:227], v[10:13]
	v_mfma_f32_16x16x32_bf16 v[2:5], v[192:195], v[224:227], v[2:5]
	s_barrier
	s_add_i32 s55, s55, 2
	s_add_u32 s28, s28, 0x100
	s_addc_u32 s29, s29, 0
	s_add_u32 s53, s53, 0x100
	s_addc_u32 s54, s54, 0
	s_cmp_gt_u32 s55, 29
	s_cbranch_scc0 .LBB0_365
	s_and_b64 vcc, exec, s[16:17]
	s_cbranch_vccz .LBB0_368
	s_barrier

; #define PG8_STAGE(bufoff, gbase, voff) do { _Pragma("unroll") for (int _i = 0; _i < 2; ++_i) \
;         __builtin_amdgcn_global_load_lds((const unsigned*)((const char*)(gbase) + (voff)[_i]), (PG8_LAS unsigned*)(lds + (bufoff) + ldsw + _i * 8192), 16, 0, 0); } while (0)
; #define PG8_STAGEB(bufoff, gbase, voff) do { _Pragma("unroll") for (int _i = 0; _i < 2; ++_i) \
;         __builtin_amdgcn_global_load_lds((const unsigned*)((const char*)(gbase) + (voff)[_i]), (PG8_LAS unsigned*)(lds + (bufoff) + ldsw + _i * 8192), 16, 0, PG8_BAUX); } while (0)
; #define PG8_LDA(dst, b, h) do { _Pragma("unroll") for (int m = 0; m < 4; ++m) _Pragma("unroll") for (int k = 0; k < 2; ++k) dst[m][k] = *(const PG8_LAS bf16x8*)(lds + PG8_SA(b, h) + aoff + m * 2048 + k * 1024); } while (0)
; #define PG8_LDB(dst, b, h) do { _Pragma("unroll") for (int n = 0; n < 2; ++n) _Pragma("unroll") for (int k = 0; k < 2; ++k) dst[n][k] = *(const PG8_LAS bf16x8*)(lds + PG8_SB(b, h) + boff + n * 2048 + k * 1024); } while (0)
; #define PG8_MMA(ai, bj, At, Bt) do { __builtin_amdgcn_s_setprio(1); _Pragma("unroll") for (int m = 0; m < 4; ++m) _Pragma("unroll") for (int n = 0; n < 2; ++n) _Pragma("unroll") for (int k = 0; k < 2; ++k) \
;         acc[ai][bj][m][n] = __builtin_amdgcn_mfma_f32_16x16x32_bf16(Bt[n][k], At[m][k], acc[ai][bj][m][n], 0, 0, 0); __builtin_amdgcn_s_setprio(0); } while (0)
; #define PG8_WAIT_V(n) asm volatile("s_waitcnt vmcnt(" #n ")" ::: "memory")
; #define PG8_WAIT_L(n) asm volatile("s_waitcnt lgkmcnt(" #n ")" ::: "memory")
; #define PG8_BAR __builtin_amdgcn_s_barrier()
; #define PG8_SCHED __builtin_amdgcn_sched_barrier(0)
; template <class Epi, class Sched, bool ALIGN_EPI = false, bool SP2 = false>
; __device__ __forceinline__ void gemm_phase(PG8_LAS unsigned char* lds, const Gemm g, const Sched& S, const Epi& E) {
;     ...
;             PG8_LDB(B0, 0, 0); PG8_LDB(B1, 0, 1); PG8_SCHED; PG8_LDA(At, 0, 0); PG8_STAGE(PG8_SA(1, 1), a1 + hstep, voffA);
;             PG8_WAIT_V(8); PG8_WAIT_L(0); PG8_BAR; PG8_MMA(0, 0, At, B0); PG8_MMA(0, 1, At, B1); PG8_BAR; PG8_SCHED;
;             PG8_LDA(At, 0, 1); PG8_STAGEB(PG8_SB(0, 0), b2, voffB); PG8_STAGEB(PG8_SB(0, 1), b2 + hstep, voffB); PG8_STAGE(PG8_SA(0, 0), a2, voffA);
;             PG8_WAIT_V(8); PG8_WAIT_L(0); PG8_BAR; PG8_MMA(1, 0, At, B0); PG8_MMA(1, 1, At, B1); PG8_BAR; PG8_SCHED;
.LBB0_391:
	ds_read_b128 v[144:147], v155
	ds_read_b128 v[148:151], v155 offset:1024
	ds_read_b128 v[160:163], v155 offset:2048
	ds_read_b128 v[164:167], v155 offset:3072
	ds_read_b128 v[168:171], v156
	ds_read_b128 v[172:175], v156 offset:1024
	ds_read_b128 v[176:179], v156 offset:2048
	ds_read_b128 v[180:183], v156 offset:3072
	s_add_u32 s38, s34, 0xfff80080
	s_addc_u32 s39, s35, -1
	s_cmp_eq_u32 s65, 28
	s_cselect_b32 s41, s1, s39
	s_cselect_b32 s40, s25, s38
	s_cselect_b32 s39, s23, s64
	s_cselect_b32 s38, s31, s63
	v_lshl_add_u64 v[188:189], s[34:35], 0, v[140:141]
	s_add_i32 m0, s47, 0xc000
	ds_read_b128 v[184:187], v157
	ds_read_b128 v[192:195], v157 offset:1024
	ds_read_b128 v[196:199], v157 offset:2048
	ds_read_b128 v[200:203], v157 offset:3072
	ds_read_b128 v[204:207], v157 offset:4096
	ds_read_b128 v[208:211], v157 offset:5120
	ds_read_b128 v[212:215], v157 offset:6144
	ds_read_b128 v[216:219], v157 offset:7168
	global_load_lds_dwordx4 v[188:189], off
	v_lshl_add_u64 v[188:189], s[34:35], 0, v[142:143]
	s_add_i32 m0, s47, 0xe000
	s_nop 0
	global_load_lds_dwordx4 v[188:189], off
	s_waitcnt vmcnt(8)
	s_waitcnt lgkmcnt(0)
	s_barrier
	s_waitcnt lgkmcnt(0)
	v_mfma_f32_16x16x32_bf16 v[126:129], v[144:147], v[184:187], v[126:129]
	v_mfma_f32_16x16x32_bf16 v[122:125], v[160:163], v[184:187], v[122:125]
	v_mfma_f32_16x16x32_bf16 v[110:113], v[144:147], v[196:199], v[110:113]
	v_mfma_f32_16x16x32_bf16 v[106:109], v[160:163], v[196:199], v[106:109]
	v_mfma_f32_16x16x32_bf16 v[94:97], v[144:147], v[204:207], v[94:97]
	v_mfma_f32_16x16x32_bf16 v[90:93], v[160:163], v[204:207], v[90:93]
	v_mfma_f32_16x16x32_bf16 v[78:81], v[144:147], v[212:215], v[78:81]
	v_mfma_f32_16x16x32_bf16 v[74:77], v[160:163], v[212:215], v[74:77]
	v_mfma_f32_16x16x32_bf16 v[126:129], v[148:151], v[192:195], v[126:129]
	v_mfma_f32_16x16x32_bf16 v[122:125], v[164:167], v[192:195], v[122:125]
	v_mfma_f32_16x16x32_bf16 v[110:113], v[148:151], v[200:203], v[110:113]
	v_mfma_f32_16x16x32_bf16 v[106:109], v[164:167], v[200:203], v[106:109]
	v_mfma_f32_16x16x32_bf16 v[94:97], v[148:151], v[208:211], v[94:97]
	v_mfma_f32_16x16x32_bf16 v[90:93], v[164:167], v[208:211], v[90:93]
	v_mfma_f32_16x16x32_bf16 v[78:81], v[148:151], v[216:219], v[78:81]
	v_mfma_f32_16x16x32_bf16 v[74:77], v[164:167], v[216:219], v[74:77]
	v_mfma_f32_16x16x32_bf16 v[118:121], v[168:171], v[184:187], v[118:121]
	v_mfma_f32_16x16x32_bf16 v[114:117], v[176:179], v[184:187], v[114:117]
	v_mfma_f32_16x16x32_bf16 v[102:105], v[168:171], v[196:199], v[102:105]
	v_mfma_f32_16x16x32_bf16 v[98:101], v[176:179], v[196:199], v[98:101]
	v_mfma_f32_16x16x32_bf16 v[86:89], v[168:171], v[204:207], v[86:89]
	v_mfma_f32_16x16x32_bf16 v[82:85], v[176:179], v[204:207], v[82:85]
	v_mfma_f32_16x16x32_bf16 v[70:73], v[168:171], v[212:215], v[70:73]
	v_mfma_f32_16x16x32_bf16 v[66:69], v[176:179], v[212:215], v[66:69]
	v_mfma_f32_16x16x32_bf16 v[118:121], v[172:175], v[192:195], v[118:121]
	v_mfma_f32_16x16x32_bf16 v[114:117], v[180:183], v[192:195], v[114:117]
	v_mfma_f32_16x16x32_bf16 v[102:105], v[172:175], v[200:203], v[102:105]
	v_mfma_f32_16x16x32_bf16 v[98:101], v[180:183], v[200:203], v[98:101]
	v_mfma_f32_16x16x32_bf16 v[86:89], v[172:175], v[208:211], v[86:89]
	v_mfma_f32_16x16x32_bf16 v[82:85], v[180:183], v[208:211], v[82:85]
	v_mfma_f32_16x16x32_bf16 v[70:73], v[172:175], v[216:219], v[70:73]
	v_mfma_f32_16x16x32_bf16 v[66:69], v[180:183], v[216:219], v[66:69]
	s_barrier
	s_add_i32 s66, s57, s42
	v_lshl_add_u64 v[188:189], s[38:39], 0, v[132:133]
	s_mov_b32 m0, s66
	ds_read_b128 v[184:187], v157 offset:16384
	ds_read_b128 v[192:195], v157 offset:17408
	ds_read_b128 v[196:199], v157 offset:18432
	ds_read_b128 v[200:203], v157 offset:19456
	ds_read_b128 v[204:207], v157 offset:20480
	ds_read_b128 v[208:211], v157 offset:21504
	ds_read_b128 v[212:215], v157 offset:22528
	ds_read_b128 v[216:219], v157 offset:23552
	global_load_lds_dwordx4 v[188:189], off
	s_add_i32 m0, s66, 0x2000
	s_add_u32 s66, s38, 0x80000
	v_lshl_add_u64 v[220:221], s[38:39], 0, v[136:137]
	s_addc_u32 s67, s39, 0
	s_add_i32 s68, s58, s42
	global_load_lds_dwordx4 v[220:221], off
	v_lshl_add_u64 v[222:223], s[66:67], 0, v[132:133]
	s_mov_b32 m0, s68
	v_lshl_add_u64 v[224:225], s[40:41], 0, v[134:135]
	global_load_lds_dwordx4 v[222:223], off
	v_lshl_add_u64 v[222:223], s[66:67], 0, v[136:137]
	s_add_i32 m0, s68, 0x2000
	s_nop 0
	global_load_lds_dwordx4 v[222:223], off
	v_lshl_add_u64 v[222:223], s[40:41], 0, v[130:131]
	s_mov_b32 m0, s47
	s_nop 0
	global_load_lds_dwordx4 v[222:223], off
	s_mov_b32 m0, s48
	s_nop 0
	global_load_lds_dwordx4 v[224:225], off
	s_waitcnt vmcnt(8)
	s_waitcnt lgkmcnt(0)
	s_barrier
; #define PG8_STAGE(bufoff, gbase, voff) do { _Pragma("unroll") for (int _i = 0; _i < 2; ++_i) \
;         __builtin_amdgcn_global_load_lds((const unsigned*)((const char*)(gbase) + (voff)[_i]), (PG8_LAS unsigned*)(lds + (bufoff) + ldsw + _i * 8192), 16, 0, 0); } while (0)
; #define PG8_LDA(dst, b, h) do { _Pragma("unroll") for (int m = 0; m < 4; ++m) _Pragma("unroll") for (int k = 0; k < 2; ++k) dst[m][k] = *(const PG8_LAS bf16x8*)(lds + PG8_SA(b, h) + aoff + m * 2048 + k * 1024); } while (0)
; #define PG8_LDB(dst, b, h) do { _Pragma("unroll") for (int n = 0; n < 2; ++n) _Pragma("unroll") for (int k = 0; k < 2; ++k) dst[n][k] = *(const PG8_LAS bf16x8*)(lds + PG8_SB(b, h) + boff + n * 2048 + k * 1024); } while (0)
; #define PG8_MMA(ai, bj, At, Bt) do { __builtin_amdgcn_s_setprio(1); _Pragma("unroll") for (int m = 0; m < 4; ++m) _Pragma("unroll") for (int n = 0; n < 2; ++n) _Pragma("unroll") for (int k = 0; k < 2; ++k) \
;         acc[ai][bj][m][n] = __builtin_amdgcn_mfma_f32_16x16x32_bf16(Bt[n][k], At[m][k], acc[ai][bj][m][n], 0, 0, 0); __builtin_amdgcn_s_setprio(0); } while (0)
; #define PG8_WAIT_V(n) asm volatile("s_waitcnt vmcnt(" #n ")" ::: "memory")
; #define PG8_WAIT_L(n) asm volatile("s_waitcnt lgkmcnt(" #n ")" ::: "memory")
; #define PG8_BAR __builtin_amdgcn_s_barrier()
; #define PG8_SCHED __builtin_amdgcn_sched_barrier(0)
; template <class Epi, class Sched, bool ALIGN_EPI = false, bool SP2 = false>
; __device__ __forceinline__ void gemm_phase(PG8_LAS unsigned char* lds, const Gemm g, const Sched& S, const Epi& E) {
;     ...
;             PG8_WAIT_V(8); PG8_WAIT_L(0); PG8_BAR; PG8_MMA(1, 0, At, B0); PG8_MMA(1, 1, At, B1); PG8_BAR; PG8_SCHED;
;             PG8_LDB(B0, 1, 0); PG8_LDB(B1, 1, 1); PG8_SCHED; PG8_LDA(At, 1, 0); PG8_STAGE(PG8_SA(0, 1), a2 + hstep, voffA);
;             PG8_WAIT_V(8); PG8_WAIT_L(0); PG8_BAR; PG8_MMA(0, 0, At, B0); PG8_MMA(0, 1, At, B1); PG8_BAR; PG8_SCHED;
	s_waitcnt lgkmcnt(0)
	v_mfma_f32_16x16x32_bf16 v[62:65], v[144:147], v[184:187], v[62:65]
	v_mfma_f32_16x16x32_bf16 v[58:61], v[160:163], v[184:187], v[58:61]
	v_mfma_f32_16x16x32_bf16 v[46:49], v[144:147], v[196:199], v[46:49]
	v_mfma_f32_16x16x32_bf16 v[42:45], v[160:163], v[196:199], v[42:45]
	v_mfma_f32_16x16x32_bf16 v[30:33], v[144:147], v[204:207], v[30:33]
	v_mfma_f32_16x16x32_bf16 v[26:29], v[160:163], v[204:207], v[26:29]
	v_mfma_f32_16x16x32_bf16 v[14:17], v[144:147], v[212:215], v[14:17]
	v_mfma_f32_16x16x32_bf16 v[10:13], v[160:163], v[212:215], v[10:13]
	v_mfma_f32_16x16x32_bf16 v[62:65], v[148:151], v[192:195], v[62:65]
	v_mfma_f32_16x16x32_bf16 v[58:61], v[164:167], v[192:195], v[58:61]
	v_mfma_f32_16x16x32_bf16 v[46:49], v[148:151], v[200:203], v[46:49]
	v_mfma_f32_16x16x32_bf16 v[42:45], v[164:167], v[200:203], v[42:45]
	v_mfma_f32_16x16x32_bf16 v[30:33], v[148:151], v[208:211], v[30:33]
	v_mfma_f32_16x16x32_bf16 v[26:29], v[164:167], v[208:211], v[26:29]
	v_mfma_f32_16x16x32_bf16 v[14:17], v[148:151], v[216:219], v[14:17]
	v_mfma_f32_16x16x32_bf16 v[10:13], v[164:167], v[216:219], v[10:13]
	v_mfma_f32_16x16x32_bf16 v[54:57], v[168:171], v[184:187], v[54:57]
	v_mfma_f32_16x16x32_bf16 v[50:53], v[176:179], v[184:187], v[50:53]
	v_mfma_f32_16x16x32_bf16 v[38:41], v[168:171], v[196:199], v[38:41]
	v_mfma_f32_16x16x32_bf16 v[34:37], v[176:179], v[196:199], v[34:37]
	v_mfma_f32_16x16x32_bf16 v[22:25], v[168:171], v[204:207], v[22:25]
	v_mfma_f32_16x16x32_bf16 v[18:21], v[176:179], v[204:207], v[18:21]
	v_mfma_f32_16x16x32_bf16 v[6:9], v[168:171], v[212:215], v[6:9]
	v_mfma_f32_16x16x32_bf16 v[2:5], v[176:179], v[212:215], v[2:5]
	v_mfma_f32_16x16x32_bf16 v[54:57], v[172:175], v[192:195], v[54:57]
	v_mfma_f32_16x16x32_bf16 v[50:53], v[180:183], v[192:195], v[50:53]
	v_mfma_f32_16x16x32_bf16 v[38:41], v[172:175], v[200:203], v[38:41]
	v_mfma_f32_16x16x32_bf16 v[34:37], v[180:183], v[200:203], v[34:37]
	v_mfma_f32_16x16x32_bf16 v[22:25], v[172:175], v[208:211], v[22:25]
	v_mfma_f32_16x16x32_bf16 v[18:21], v[180:183], v[208:211], v[18:21]
	v_mfma_f32_16x16x32_bf16 v[6:9], v[172:175], v[216:219], v[6:9]
	v_mfma_f32_16x16x32_bf16 v[2:5], v[180:183], v[216:219], v[2:5]
	s_barrier
	s_add_i32 s66, 0, 0x18000
	v_add_u32_e32 v138, s66, v153
	s_add_i32 s67, 0, 0x1c000
	ds_read_b128 v[144:147], v138
	ds_read_b128 v[148:151], v138 offset:1024
	ds_read_b128 v[160:163], v138 offset:2048
	ds_read_b128 v[164:167], v138 offset:3072
	v_add_u32_e32 v138, s67, v153
	ds_read_b128 v[168:171], v138
	ds_read_b128 v[172:175], v138 offset:1024
	ds_read_b128 v[176:179], v138 offset:2048
	ds_read_b128 v[180:183], v138 offset:3072
	s_add_u32 s40, s40, 0x80000
	s_addc_u32 s41, s41, 0
	s_mov_b32 m0, s49
	v_lshl_add_u64 v[226:227], s[40:41], 0, v[130:131]
	ds_read_b128 v[184:187], v157 offset:32768
	ds_read_b128 v[192:195], v157 offset:33792
	ds_read_b128 v[196:199], v157 offset:34816
	ds_read_b128 v[200:203], v157 offset:35840
	ds_read_b128 v[204:207], v157 offset:36864
	ds_read_b128 v[208:211], v157 offset:37888
	ds_read_b128 v[212:215], v157 offset:38912
	ds_read_b128 v[216:219], v157 offset:39936
	global_load_lds_dwordx4 v[226:227], off
	v_lshl_add_u64 v[226:227], s[40:41], 0, v[134:135]
	s_mov_b32 m0, s50
	s_nop 0
	global_load_lds_dwordx4 v[226:227], off
	s_waitcnt vmcnt(8)
	s_waitcnt lgkmcnt(0)
	s_barrier
	s_waitcnt lgkmcnt(0)
	v_mfma_f32_16x16x32_bf16 v[126:129], v[144:147], v[184:187], v[126:129]
	v_mfma_f32_16x16x32_bf16 v[122:125], v[160:163], v[184:187], v[122:125]
	v_mfma_f32_16x16x32_bf16 v[110:113], v[144:147], v[196:199], v[110:113]
	v_mfma_f32_16x16x32_bf16 v[106:109], v[160:163], v[196:199], v[106:109]
	v_mfma_f32_16x16x32_bf16 v[94:97], v[144:147], v[204:207], v[94:97]
	v_mfma_f32_16x16x32_bf16 v[90:93], v[160:163], v[204:207], v[90:93]
	v_mfma_f32_16x16x32_bf16 v[78:81], v[144:147], v[212:215], v[78:81]
	v_mfma_f32_16x16x32_bf16 v[74:77], v[160:163], v[212:215], v[74:77]
	v_mfma_f32_16x16x32_bf16 v[126:129], v[148:151], v[192:195], v[126:129]
	v_mfma_f32_16x16x32_bf16 v[122:125], v[164:167], v[192:195], v[122:125]
	v_mfma_f32_16x16x32_bf16 v[110:113], v[148:151], v[200:203], v[110:113]
	v_mfma_f32_16x16x32_bf16 v[106:109], v[164:167], v[200:203], v[106:109]
	v_mfma_f32_16x16x32_bf16 v[94:97], v[148:151], v[208:211], v[94:97]
	v_mfma_f32_16x16x32_bf16 v[90:93], v[164:167], v[208:211], v[90:93]
	v_mfma_f32_16x16x32_bf16 v[78:81], v[148:151], v[216:219], v[78:81]
	v_mfma_f32_16x16x32_bf16 v[74:77], v[164:167], v[216:219], v[74:77]
	v_mfma_f32_16x16x32_bf16 v[118:121], v[168:171], v[184:187], v[118:121]
	v_mfma_f32_16x16x32_bf16 v[114:117], v[176:179], v[184:187], v[114:117]
	v_mfma_f32_16x16x32_bf16 v[102:105], v[168:171], v[196:199], v[102:105]
	v_mfma_f32_16x16x32_bf16 v[98:101], v[176:179], v[196:199], v[98:101]
	v_mfma_f32_16x16x32_bf16 v[86:89], v[168:171], v[204:207], v[86:89]
	v_mfma_f32_16x16x32_bf16 v[82:85], v[176:179], v[204:207], v[82:85]
	v_mfma_f32_16x16x32_bf16 v[70:73], v[168:171], v[212:215], v[70:73]
	v_mfma_f32_16x16x32_bf16 v[66:69], v[176:179], v[212:215], v[66:69]
	v_mfma_f32_16x16x32_bf16 v[118:121], v[172:175], v[192:195], v[118:121]
	v_mfma_f32_16x16x32_bf16 v[114:117], v[180:183], v[192:195], v[114:117]
	v_mfma_f32_16x16x32_bf16 v[102:105], v[172:175], v[200:203], v[102:105]
	v_mfma_f32_16x16x32_bf16 v[98:101], v[180:183], v[200:203], v[98:101]
	v_mfma_f32_16x16x32_bf16 v[86:89], v[172:175], v[208:211], v[86:89]
	v_mfma_f32_16x16x32_bf16 v[82:85], v[180:183], v[208:211], v[82:85]
	v_mfma_f32_16x16x32_bf16 v[70:73], v[172:175], v[216:219], v[70:73]
	v_mfma_f32_16x16x32_bf16 v[66:69], v[180:183], v[216:219], v[66:69]
	s_barrier
; #define PG8_STAGE(bufoff, gbase, voff) do { _Pragma("unroll") for (int _i = 0; _i < 2; ++_i) \
;         __builtin_amdgcn_global_load_lds((const unsigned*)((const char*)(gbase) + (voff)[_i]), (PG8_LAS unsigned*)(lds + (bufoff) + ldsw + _i * 8192), 16, 0, 0); } while (0)
; #define PG8_STAGEB(bufoff, gbase, voff) do { _Pragma("unroll") for (int _i = 0; _i < 2; ++_i) \
;         __builtin_amdgcn_global_load_lds((const unsigned*)((const char*)(gbase) + (voff)[_i]), (PG8_LAS unsigned*)(lds + (bufoff) + ldsw + _i * 8192), 16, 0, PG8_BAUX); } while (0)
; #define PG8_LDA(dst, b, h) do { _Pragma("unroll") for (int m = 0; m < 4; ++m) _Pragma("unroll") for (int k = 0; k < 2; ++k) dst[m][k] = *(const PG8_LAS bf16x8*)(lds + PG8_SA(b, h) + aoff + m * 2048 + k * 1024); } while (0)
; #define PG8_MMA(ai, bj, At, Bt) do { __builtin_amdgcn_s_setprio(1); _Pragma("unroll") for (int m = 0; m < 4; ++m) _Pragma("unroll") for (int n = 0; n < 2; ++n) _Pragma("unroll") for (int k = 0; k < 2; ++k) \
;         acc[ai][bj][m][n] = __builtin_amdgcn_mfma_f32_16x16x32_bf16(Bt[n][k], At[m][k], acc[ai][bj][m][n], 0, 0, 0); __builtin_amdgcn_s_setprio(0); } while (0)
; #define PG8_WAIT_V(n) asm volatile("s_waitcnt vmcnt(" #n ")" ::: "memory")
; #define PG8_WAIT_L(n) asm volatile("s_waitcnt lgkmcnt(" #n ")" ::: "memory")
; #define PG8_BAR __builtin_amdgcn_s_barrier()
; #define PG8_SCHED __builtin_amdgcn_sched_barrier(0)
; template <class Epi, class Sched, bool ALIGN_EPI = false, bool SP2 = false>
; __device__ __forceinline__ void gemm_phase(PG8_LAS unsigned char* lds, const Gemm g, const Sched& S, const Epi& E) {
;     ...
;             PG8_LDA(At, 1, 1); PG8_STAGEB(PG8_SB(1, 0), b3, voffB); PG8_STAGEB(PG8_SB(1, 1), b3 + hstep, voffB); PG8_STAGE(PG8_SA(1, 0), a3, voffA);
;             PG8_WAIT_V(8); PG8_WAIT_L(0); PG8_BAR; PG8_MMA(1, 0, At, B0); PG8_MMA(1, 1, At, B1); PG8_BAR; PG8_SCHED;
	s_add_i32 s40, s66, s42
	v_lshl_add_u64 v[188:189], v[188:189], 0, s[16:17]
	s_mov_b32 m0, s40
	ds_read_b128 v[184:187], v157 offset:49152
	ds_read_b128 v[192:195], v157 offset:50176
	ds_read_b128 v[196:199], v157 offset:51200
	ds_read_b128 v[200:203], v157 offset:52224
	ds_read_b128 v[204:207], v157 offset:53248
	ds_read_b128 v[208:211], v157 offset:54272
	ds_read_b128 v[212:215], v157 offset:55296
	ds_read_b128 v[216:219], v157 offset:56320
	global_load_lds_dwordx4 v[188:189], off
	s_add_i32 m0, s40, 0x2000
	s_add_u32 s38, s38, 0x80080
	v_lshl_add_u64 v[188:189], v[220:221], 0, s[16:17]
	s_addc_u32 s39, s39, 0
	s_add_i32 s40, s67, s42
	global_load_lds_dwordx4 v[188:189], off
	v_lshl_add_u64 v[188:189], s[38:39], 0, v[132:133]
	s_mov_b32 m0, s40
	s_nop 0
	global_load_lds_dwordx4 v[188:189], off
	v_lshl_add_u64 v[188:189], s[38:39], 0, v[136:137]
	s_add_i32 m0, s40, 0x2000
	s_nop 0
	global_load_lds_dwordx4 v[188:189], off
	v_lshl_add_u64 v[188:189], v[222:223], 0, s[16:17]
	s_mov_b32 m0, s53
	s_nop 0
	global_load_lds_dwordx4 v[188:189], off
	v_lshl_add_u64 v[188:189], v[224:225], 0, s[16:17]
	s_mov_b32 m0, s54
	s_nop 0
	global_load_lds_dwordx4 v[188:189], off
	s_waitcnt vmcnt(8)
	s_waitcnt lgkmcnt(0)
	s_barrier
	s_waitcnt lgkmcnt(0)
	v_mfma_f32_16x16x32_bf16 v[62:65], v[144:147], v[184:187], v[62:65]
	v_mfma_f32_16x16x32_bf16 v[58:61], v[160:163], v[184:187], v[58:61]
	v_mfma_f32_16x16x32_bf16 v[46:49], v[144:147], v[196:199], v[46:49]
	v_mfma_f32_16x16x32_bf16 v[42:45], v[160:163], v[196:199], v[42:45]
	v_mfma_f32_16x16x32_bf16 v[30:33], v[144:147], v[204:207], v[30:33]
	v_mfma_f32_16x16x32_bf16 v[26:29], v[160:163], v[204:207], v[26:29]
	v_mfma_f32_16x16x32_bf16 v[14:17], v[144:147], v[212:215], v[14:17]
	v_mfma_f32_16x16x32_bf16 v[10:13], v[160:163], v[212:215], v[10:13]
	v_mfma_f32_16x16x32_bf16 v[62:65], v[148:151], v[192:195], v[62:65]
	v_mfma_f32_16x16x32_bf16 v[58:61], v[164:167], v[192:195], v[58:61]
	v_mfma_f32_16x16x32_bf16 v[46:49], v[148:151], v[200:203], v[46:49]
	v_mfma_f32_16x16x32_bf16 v[42:45], v[164:167], v[200:203], v[42:45]
	v_mfma_f32_16x16x32_bf16 v[30:33], v[148:151], v[208:211], v[30:33]
	v_mfma_f32_16x16x32_bf16 v[26:29], v[164:167], v[208:211], v[26:29]
	v_mfma_f32_16x16x32_bf16 v[14:17], v[148:151], v[216:219], v[14:17]
	v_mfma_f32_16x16x32_bf16 v[10:13], v[164:167], v[216:219], v[10:13]
	v_mfma_f32_16x16x32_bf16 v[54:57], v[168:171], v[184:187], v[54:57]
	v_mfma_f32_16x16x32_bf16 v[50:53], v[176:179], v[184:187], v[50:53]
	v_mfma_f32_16x16x32_bf16 v[38:41], v[168:171], v[196:199], v[38:41]
	v_mfma_f32_16x16x32_bf16 v[34:37], v[176:179], v[196:199], v[34:37]
	v_mfma_f32_16x16x32_bf16 v[22:25], v[168:171], v[204:207], v[22:25]
	v_mfma_f32_16x16x32_bf16 v[18:21], v[176:179], v[204:207], v[18:21]
	v_mfma_f32_16x16x32_bf16 v[6:9], v[168:171], v[212:215], v[6:9]
	v_mfma_f32_16x16x32_bf16 v[2:5], v[176:179], v[212:215], v[2:5]
	v_mfma_f32_16x16x32_bf16 v[54:57], v[172:175], v[192:195], v[54:57]
	v_mfma_f32_16x16x32_bf16 v[50:53], v[180:183], v[192:195], v[50:53]
	v_mfma_f32_16x16x32_bf16 v[38:41], v[172:175], v[200:203], v[38:41]
	v_mfma_f32_16x16x32_bf16 v[34:37], v[180:183], v[200:203], v[34:37]
	v_mfma_f32_16x16x32_bf16 v[22:25], v[172:175], v[208:211], v[22:25]
	v_mfma_f32_16x16x32_bf16 v[18:21], v[180:183], v[208:211], v[18:21]
	v_mfma_f32_16x16x32_bf16 v[6:9], v[172:175], v[216:219], v[6:9]
	v_mfma_f32_16x16x32_bf16 v[2:5], v[180:183], v[216:219], v[2:5]
	s_barrier
	s_add_i32 s65, s65, 2
	s_add_u32 s34, s34, 0x100
	s_addc_u32 s35, s35, 0
	s_add_u32 s63, s63, 0x100
	s_addc_u32 s64, s64, 0
	s_cmp_gt_u32 s65, 29
	s_cbranch_scc0 .LBB0_391
	s_and_b64 vcc, exec, s[18:19]
	s_cbranch_vccz .LBB0_394
	s_barrier

; #define PG8_STAGE(bufoff, gbase, voff) do { _Pragma("unroll") for (int _i = 0; _i < 2; ++_i) \
;         __builtin_amdgcn_global_load_lds((const unsigned*)((const char*)(gbase) + (voff)[_i]), (PG8_LAS unsigned*)(lds + (bufoff) + ldsw + _i * 8192), 16, 0, 0); } while (0)
; #define PG8_STAGEB(bufoff, gbase, voff) do { _Pragma("unroll") for (int _i = 0; _i < 2; ++_i) \
;         __builtin_amdgcn_global_load_lds((const unsigned*)((const char*)(gbase) + (voff)[_i]), (PG8_LAS unsigned*)(lds + (bufoff) + ldsw + _i * 8192), 16, 0, PG8_BAUX); } while (0)
; #define PG8_LDA(dst, b, h) do { _Pragma("unroll") for (int m = 0; m < 4; ++m) _Pragma("unroll") for (int k = 0; k < 2; ++k) dst[m][k] = *(const PG8_LAS bf16x8*)(lds + PG8_SA(b, h) + aoff + m * 2048 + k * 1024); } while (0)
; #define PG8_LDB(dst, b, h) do { _Pragma("unroll") for (int n = 0; n < 2; ++n) _Pragma("unroll") for (int k = 0; k < 2; ++k) dst[n][k] = *(const PG8_LAS bf16x8*)(lds + PG8_SB(b, h) + boff + n * 2048 + k * 1024); } while (0)
; #define PG8_MMA(ai, bj, At, Bt) do { __builtin_amdgcn_s_setprio(1); _Pragma("unroll") for (int m = 0; m < 4; ++m) _Pragma("unroll") for (int n = 0; n < 2; ++n) _Pragma("unroll") for (int k = 0; k < 2; ++k) \
;         acc[ai][bj][m][n] = __builtin_amdgcn_mfma_f32_16x16x32_bf16(Bt[n][k], At[m][k], acc[ai][bj][m][n], 0, 0, 0); __builtin_amdgcn_s_setprio(0); } while (0)
; #define PG8_WAIT_V(n) asm volatile("s_waitcnt vmcnt(" #n ")" ::: "memory")
; #define PG8_WAIT_L(n) asm volatile("s_waitcnt lgkmcnt(" #n ")" ::: "memory")
; #define PG8_BAR __builtin_amdgcn_s_barrier()
; #define PG8_SCHED __builtin_amdgcn_sched_barrier(0)
; template <class Epi, class Sched, bool ALIGN_EPI = false, bool SP2 = false>
; __device__ __forceinline__ void gemm_phase(PG8_LAS unsigned char* lds, const Gemm g, const Sched& S, const Epi& E) {
;     ...
;             PG8_LDB(B0, 0, 0); PG8_LDB(B1, 0, 1); PG8_SCHED; PG8_LDA(At, 0, 0); PG8_STAGE(PG8_SA(1, 1), a1 + hstep, voffA);
;             PG8_WAIT_V(8); PG8_WAIT_L(0); PG8_BAR; PG8_MMA(0, 0, At, B0); PG8_MMA(0, 1, At, B1); PG8_BAR; PG8_SCHED;
;             PG8_LDA(At, 0, 1); PG8_STAGEB(PG8_SB(0, 0), b2, voffB); PG8_STAGEB(PG8_SB(0, 1), b2 + hstep, voffB); PG8_STAGE(PG8_SA(0, 0), a2, voffA);
;             PG8_WAIT_V(8); PG8_WAIT_L(0); PG8_BAR; PG8_MMA(1, 0, At, B0); PG8_MMA(1, 1, At, B1); PG8_BAR; PG8_SCHED;
.LBB0_608:
	ds_read_b128 v[146:149], v153
	ds_read_b128 v[158:161], v153 offset:1024
	ds_read_b128 v[162:165], v153 offset:2048
	ds_read_b128 v[166:169], v153 offset:3072
	ds_read_b128 v[170:173], v154
	ds_read_b128 v[174:177], v154 offset:1024
	ds_read_b128 v[178:181], v154 offset:2048
	ds_read_b128 v[182:185], v154 offset:3072
	s_add_u32 s28, s26, 0xffea0080
	s_addc_u32 s29, s27, -1
	s_cmpk_eq_i32 s55, 0x54
	s_cselect_b32 s31, s5, s29
	s_cselect_b32 s30, s4, s28
	s_cselect_b32 s29, s25, s54
	s_cselect_b32 s28, s24, s53
	v_lshl_add_u64 v[220:221], s[26:27], 0, v[138:139]
	s_add_i32 m0, s39, 0xc000
	ds_read_b128 v[186:189], v155
	ds_read_b128 v[192:195], v155 offset:1024
	ds_read_b128 v[196:199], v155 offset:2048
	ds_read_b128 v[200:203], v155 offset:3072
	ds_read_b128 v[204:207], v155 offset:4096
	ds_read_b128 v[208:211], v155 offset:5120
	ds_read_b128 v[212:215], v155 offset:6144
	ds_read_b128 v[216:219], v155 offset:7168
	global_load_lds_dwordx4 v[220:221], off
	v_lshl_add_u64 v[220:221], s[26:27], 0, v[140:141]
	s_add_i32 m0, s39, 0xe000
	s_nop 0
	global_load_lds_dwordx4 v[220:221], off
	s_waitcnt vmcnt(8)
	s_waitcnt lgkmcnt(0)
	s_barrier
	s_waitcnt lgkmcnt(0)
	v_mfma_f32_16x16x32_bf16 v[126:129], v[146:149], v[186:189], v[126:129]
	v_mfma_f32_16x16x32_bf16 v[122:125], v[162:165], v[186:189], v[122:125]
	v_mfma_f32_16x16x32_bf16 v[110:113], v[146:149], v[196:199], v[110:113]
	v_mfma_f32_16x16x32_bf16 v[106:109], v[162:165], v[196:199], v[106:109]
	v_mfma_f32_16x16x32_bf16 v[94:97], v[146:149], v[204:207], v[94:97]
	v_mfma_f32_16x16x32_bf16 v[90:93], v[162:165], v[204:207], v[90:93]
	v_mfma_f32_16x16x32_bf16 v[78:81], v[146:149], v[212:215], v[78:81]
	v_mfma_f32_16x16x32_bf16 v[74:77], v[162:165], v[212:215], v[74:77]
	v_mfma_f32_16x16x32_bf16 v[126:129], v[158:161], v[192:195], v[126:129]
	v_mfma_f32_16x16x32_bf16 v[122:125], v[166:169], v[192:195], v[122:125]
	v_mfma_f32_16x16x32_bf16 v[110:113], v[158:161], v[200:203], v[110:113]
	v_mfma_f32_16x16x32_bf16 v[106:109], v[166:169], v[200:203], v[106:109]
	v_mfma_f32_16x16x32_bf16 v[94:97], v[158:161], v[208:211], v[94:97]
	v_mfma_f32_16x16x32_bf16 v[90:93], v[166:169], v[208:211], v[90:93]
	v_mfma_f32_16x16x32_bf16 v[78:81], v[158:161], v[216:219], v[78:81]
	v_mfma_f32_16x16x32_bf16 v[74:77], v[166:169], v[216:219], v[74:77]
	v_mfma_f32_16x16x32_bf16 v[118:121], v[170:173], v[186:189], v[118:121]
	v_mfma_f32_16x16x32_bf16 v[114:117], v[178:181], v[186:189], v[114:117]
	v_mfma_f32_16x16x32_bf16 v[102:105], v[170:173], v[196:199], v[102:105]
	v_mfma_f32_16x16x32_bf16 v[98:101], v[178:181], v[196:199], v[98:101]
	v_mfma_f32_16x16x32_bf16 v[86:89], v[170:173], v[204:207], v[86:89]
	v_mfma_f32_16x16x32_bf16 v[82:85], v[178:181], v[204:207], v[82:85]
	v_mfma_f32_16x16x32_bf16 v[70:73], v[170:173], v[212:215], v[70:73]
	v_mfma_f32_16x16x32_bf16 v[66:69], v[178:181], v[212:215], v[66:69]
	v_mfma_f32_16x16x32_bf16 v[118:121], v[174:177], v[192:195], v[118:121]
	v_mfma_f32_16x16x32_bf16 v[114:117], v[182:185], v[192:195], v[114:117]
	v_mfma_f32_16x16x32_bf16 v[102:105], v[174:177], v[200:203], v[102:105]
	v_mfma_f32_16x16x32_bf16 v[98:101], v[182:185], v[200:203], v[98:101]
	v_mfma_f32_16x16x32_bf16 v[86:89], v[174:177], v[208:211], v[86:89]
	v_mfma_f32_16x16x32_bf16 v[82:85], v[182:185], v[208:211], v[82:85]
	v_mfma_f32_16x16x32_bf16 v[70:73], v[174:177], v[216:219], v[70:73]
	v_mfma_f32_16x16x32_bf16 v[66:69], v[182:185], v[216:219], v[66:69]
	s_barrier
	s_add_i32 s56, s48, s34
	v_lshl_add_u64 v[220:221], s[28:29], 0, v[132:133]
	s_mov_b32 m0, s56
	ds_read_b128 v[186:189], v155 offset:16384
	ds_read_b128 v[192:195], v155 offset:17408
	ds_read_b128 v[196:199], v155 offset:18432
	ds_read_b128 v[200:203], v155 offset:19456
	ds_read_b128 v[204:207], v155 offset:20480
	ds_read_b128 v[208:211], v155 offset:21504
	ds_read_b128 v[212:215], v155 offset:22528
	ds_read_b128 v[216:219], v155 offset:23552
	global_load_lds_dwordx4 v[220:221], off
	s_add_i32 m0, s56, 0x2000
	s_add_u32 s56, s28, 0x160000
	v_lshl_add_u64 v[222:223], s[28:29], 0, v[136:137]
	s_addc_u32 s57, s29, 0
	s_add_i32 s58, s49, s34
	global_load_lds_dwordx4 v[222:223], off
	v_lshl_add_u64 v[224:225], s[56:57], 0, v[132:133]
	s_mov_b32 m0, s58
	v_lshl_add_u64 v[226:227], s[30:31], 0, v[134:135]
	global_load_lds_dwordx4 v[224:225], off
	v_lshl_add_u64 v[224:225], s[56:57], 0, v[136:137]
	s_add_i32 m0, s58, 0x2000
	s_nop 0
	global_load_lds_dwordx4 v[224:225], off
	v_lshl_add_u64 v[224:225], s[30:31], 0, v[130:131]
	s_mov_b32 m0, s39
	s_nop 0
	global_load_lds_dwordx4 v[224:225], off
	s_mov_b32 m0, s40
	s_nop 0
	global_load_lds_dwordx4 v[226:227], off
	s_waitcnt vmcnt(8)
	s_waitcnt lgkmcnt(0)
	s_barrier
; #define PG8_STAGE(bufoff, gbase, voff) do { _Pragma("unroll") for (int _i = 0; _i < 2; ++_i) \
;         __builtin_amdgcn_global_load_lds((const unsigned*)((const char*)(gbase) + (voff)[_i]), (PG8_LAS unsigned*)(lds + (bufoff) + ldsw + _i * 8192), 16, 0, 0); } while (0)
; #define PG8_LDA(dst, b, h) do { _Pragma("unroll") for (int m = 0; m < 4; ++m) _Pragma("unroll") for (int k = 0; k < 2; ++k) dst[m][k] = *(const PG8_LAS bf16x8*)(lds + PG8_SA(b, h) + aoff + m * 2048 + k * 1024); } while (0)
; #define PG8_LDB(dst, b, h) do { _Pragma("unroll") for (int n = 0; n < 2; ++n) _Pragma("unroll") for (int k = 0; k < 2; ++k) dst[n][k] = *(const PG8_LAS bf16x8*)(lds + PG8_SB(b, h) + boff + n * 2048 + k * 1024); } while (0)
; #define PG8_MMA(ai, bj, At, Bt) do { __builtin_amdgcn_s_setprio(1); _Pragma("unroll") for (int m = 0; m < 4; ++m) _Pragma("unroll") for (int n = 0; n < 2; ++n) _Pragma("unroll") for (int k = 0; k < 2; ++k) \
;         acc[ai][bj][m][n] = __builtin_amdgcn_mfma_f32_16x16x32_bf16(Bt[n][k], At[m][k], acc[ai][bj][m][n], 0, 0, 0); __builtin_amdgcn_s_setprio(0); } while (0)
; #define PG8_WAIT_V(n) asm volatile("s_waitcnt vmcnt(" #n ")" ::: "memory")
; #define PG8_WAIT_L(n) asm volatile("s_waitcnt lgkmcnt(" #n ")" ::: "memory")
; #define PG8_BAR __builtin_amdgcn_s_barrier()
; #define PG8_SCHED __builtin_amdgcn_sched_barrier(0)
; template <class Epi, class Sched, bool ALIGN_EPI = false, bool SP2 = false>
; __device__ __forceinline__ void gemm_phase(PG8_LAS unsigned char* lds, const Gemm g, const Sched& S, const Epi& E) {
;     ...
;             PG8_WAIT_V(8); PG8_WAIT_L(0); PG8_BAR; PG8_MMA(1, 0, At, B0); PG8_MMA(1, 1, At, B1); PG8_BAR; PG8_SCHED;
;             PG8_LDB(B0, 1, 0); PG8_LDB(B1, 1, 1); PG8_SCHED; PG8_LDA(At, 1, 0); PG8_STAGE(PG8_SA(0, 1), a2 + hstep, voffA);
;             PG8_WAIT_V(8); PG8_WAIT_L(0); PG8_BAR; PG8_MMA(0, 0, At, B0); PG8_MMA(0, 1, At, B1); PG8_BAR; PG8_SCHED;
	s_waitcnt lgkmcnt(0)
	v_mfma_f32_16x16x32_bf16 v[62:65], v[146:149], v[186:189], v[62:65]
	v_mfma_f32_16x16x32_bf16 v[58:61], v[162:165], v[186:189], v[58:61]
	v_mfma_f32_16x16x32_bf16 v[46:49], v[146:149], v[196:199], v[46:49]
	v_mfma_f32_16x16x32_bf16 v[42:45], v[162:165], v[196:199], v[42:45]
	v_mfma_f32_16x16x32_bf16 v[30:33], v[146:149], v[204:207], v[30:33]
	v_mfma_f32_16x16x32_bf16 v[26:29], v[162:165], v[204:207], v[26:29]
	v_mfma_f32_16x16x32_bf16 v[14:17], v[146:149], v[212:215], v[14:17]
	v_mfma_f32_16x16x32_bf16 v[10:13], v[162:165], v[212:215], v[10:13]
	v_mfma_f32_16x16x32_bf16 v[62:65], v[158:161], v[192:195], v[62:65]
	v_mfma_f32_16x16x32_bf16 v[58:61], v[166:169], v[192:195], v[58:61]
	v_mfma_f32_16x16x32_bf16 v[46:49], v[158:161], v[200:203], v[46:49]
	v_mfma_f32_16x16x32_bf16 v[42:45], v[166:169], v[200:203], v[42:45]
	v_mfma_f32_16x16x32_bf16 v[30:33], v[158:161], v[208:211], v[30:33]
	v_mfma_f32_16x16x32_bf16 v[26:29], v[166:169], v[208:211], v[26:29]
	v_mfma_f32_16x16x32_bf16 v[14:17], v[158:161], v[216:219], v[14:17]
	v_mfma_f32_16x16x32_bf16 v[10:13], v[166:169], v[216:219], v[10:13]
	v_mfma_f32_16x16x32_bf16 v[54:57], v[170:173], v[186:189], v[54:57]
	v_mfma_f32_16x16x32_bf16 v[50:53], v[178:181], v[186:189], v[50:53]
	v_mfma_f32_16x16x32_bf16 v[38:41], v[170:173], v[196:199], v[38:41]
	v_mfma_f32_16x16x32_bf16 v[34:37], v[178:181], v[196:199], v[34:37]
	v_mfma_f32_16x16x32_bf16 v[22:25], v[170:173], v[204:207], v[22:25]
	v_mfma_f32_16x16x32_bf16 v[18:21], v[178:181], v[204:207], v[18:21]
	v_mfma_f32_16x16x32_bf16 v[6:9], v[170:173], v[212:215], v[6:9]
	v_mfma_f32_16x16x32_bf16 v[2:5], v[178:181], v[212:215], v[2:5]
	v_mfma_f32_16x16x32_bf16 v[54:57], v[174:177], v[192:195], v[54:57]
	v_mfma_f32_16x16x32_bf16 v[50:53], v[182:185], v[192:195], v[50:53]
	v_mfma_f32_16x16x32_bf16 v[38:41], v[174:177], v[200:203], v[38:41]
	v_mfma_f32_16x16x32_bf16 v[34:37], v[182:185], v[200:203], v[34:37]
	v_mfma_f32_16x16x32_bf16 v[22:25], v[174:177], v[208:211], v[22:25]
	v_mfma_f32_16x16x32_bf16 v[18:21], v[182:185], v[208:211], v[18:21]
	v_mfma_f32_16x16x32_bf16 v[6:9], v[174:177], v[216:219], v[6:9]
	v_mfma_f32_16x16x32_bf16 v[2:5], v[182:185], v[216:219], v[2:5]
	s_barrier
	s_add_i32 s56, 0, 0x18000
	v_add_u32_e32 v157, s56, v151
	s_add_i32 s57, 0, 0x1c000
	ds_read_b128 v[146:149], v157
	ds_read_b128 v[158:161], v157 offset:1024
	ds_read_b128 v[162:165], v157 offset:2048
	ds_read_b128 v[166:169], v157 offset:3072
	v_add_u32_e32 v157, s57, v151
	ds_read_b128 v[170:173], v157
	ds_read_b128 v[174:177], v157 offset:1024
	ds_read_b128 v[178:181], v157 offset:2048
	ds_read_b128 v[182:185], v157 offset:3072
	s_add_u32 s30, s30, 0x160000
	s_addc_u32 s31, s31, 0
	s_mov_b32 m0, s41
	v_lshl_add_u64 v[228:229], s[30:31], 0, v[130:131]
	ds_read_b128 v[186:189], v155 offset:32768
	ds_read_b128 v[192:195], v155 offset:33792
	ds_read_b128 v[196:199], v155 offset:34816
	ds_read_b128 v[200:203], v155 offset:35840
	ds_read_b128 v[204:207], v155 offset:36864
	ds_read_b128 v[208:211], v155 offset:37888
	ds_read_b128 v[212:215], v155 offset:38912
	ds_read_b128 v[216:219], v155 offset:39936
	global_load_lds_dwordx4 v[228:229], off
	v_lshl_add_u64 v[228:229], s[30:31], 0, v[134:135]
	s_mov_b32 m0, s42
	s_nop 0
	global_load_lds_dwordx4 v[228:229], off
	s_waitcnt vmcnt(8)
	s_waitcnt lgkmcnt(0)
	s_barrier
	s_waitcnt lgkmcnt(0)
	v_mfma_f32_16x16x32_bf16 v[126:129], v[146:149], v[186:189], v[126:129]
	v_mfma_f32_16x16x32_bf16 v[122:125], v[162:165], v[186:189], v[122:125]
	v_mfma_f32_16x16x32_bf16 v[110:113], v[146:149], v[196:199], v[110:113]
	v_mfma_f32_16x16x32_bf16 v[106:109], v[162:165], v[196:199], v[106:109]
	v_mfma_f32_16x16x32_bf16 v[94:97], v[146:149], v[204:207], v[94:97]
	v_mfma_f32_16x16x32_bf16 v[90:93], v[162:165], v[204:207], v[90:93]
	v_mfma_f32_16x16x32_bf16 v[78:81], v[146:149], v[212:215], v[78:81]
	v_mfma_f32_16x16x32_bf16 v[74:77], v[162:165], v[212:215], v[74:77]
	v_mfma_f32_16x16x32_bf16 v[126:129], v[158:161], v[192:195], v[126:129]
	v_mfma_f32_16x16x32_bf16 v[122:125], v[166:169], v[192:195], v[122:125]
	v_mfma_f32_16x16x32_bf16 v[110:113], v[158:161], v[200:203], v[110:113]
	v_mfma_f32_16x16x32_bf16 v[106:109], v[166:169], v[200:203], v[106:109]
	v_mfma_f32_16x16x32_bf16 v[94:97], v[158:161], v[208:211], v[94:97]
	v_mfma_f32_16x16x32_bf16 v[90:93], v[166:169], v[208:211], v[90:93]
	v_mfma_f32_16x16x32_bf16 v[78:81], v[158:161], v[216:219], v[78:81]
	v_mfma_f32_16x16x32_bf16 v[74:77], v[166:169], v[216:219], v[74:77]
	v_mfma_f32_16x16x32_bf16 v[118:121], v[170:173], v[186:189], v[118:121]
	v_mfma_f32_16x16x32_bf16 v[114:117], v[178:181], v[186:189], v[114:117]
	v_mfma_f32_16x16x32_bf16 v[102:105], v[170:173], v[196:199], v[102:105]
	v_mfma_f32_16x16x32_bf16 v[98:101], v[178:181], v[196:199], v[98:101]
	v_mfma_f32_16x16x32_bf16 v[86:89], v[170:173], v[204:207], v[86:89]
	v_mfma_f32_16x16x32_bf16 v[82:85], v[178:181], v[204:207], v[82:85]
	v_mfma_f32_16x16x32_bf16 v[70:73], v[170:173], v[212:215], v[70:73]
	v_mfma_f32_16x16x32_bf16 v[66:69], v[178:181], v[212:215], v[66:69]
	v_mfma_f32_16x16x32_bf16 v[118:121], v[174:177], v[192:195], v[118:121]
	v_mfma_f32_16x16x32_bf16 v[114:117], v[182:185], v[192:195], v[114:117]
	v_mfma_f32_16x16x32_bf16 v[102:105], v[174:177], v[200:203], v[102:105]
	v_mfma_f32_16x16x32_bf16 v[98:101], v[182:185], v[200:203], v[98:101]
	v_mfma_f32_16x16x32_bf16 v[86:89], v[174:177], v[208:211], v[86:89]
	v_mfma_f32_16x16x32_bf16 v[82:85], v[182:185], v[208:211], v[82:85]
	v_mfma_f32_16x16x32_bf16 v[70:73], v[174:177], v[216:219], v[70:73]
	v_mfma_f32_16x16x32_bf16 v[66:69], v[182:185], v[216:219], v[66:69]
	s_barrier
; #define PG8_STAGE(bufoff, gbase, voff) do { _Pragma("unroll") for (int _i = 0; _i < 2; ++_i) \
;         __builtin_amdgcn_global_load_lds((const unsigned*)((const char*)(gbase) + (voff)[_i]), (PG8_LAS unsigned*)(lds + (bufoff) + ldsw + _i * 8192), 16, 0, 0); } while (0)
; #define PG8_STAGEB(bufoff, gbase, voff) do { _Pragma("unroll") for (int _i = 0; _i < 2; ++_i) \
;         __builtin_amdgcn_global_load_lds((const unsigned*)((const char*)(gbase) + (voff)[_i]), (PG8_LAS unsigned*)(lds + (bufoff) + ldsw + _i * 8192), 16, 0, PG8_BAUX); } while (0)
; #define PG8_LDA(dst, b, h) do { _Pragma("unroll") for (int m = 0; m < 4; ++m) _Pragma("unroll") for (int k = 0; k < 2; ++k) dst[m][k] = *(const PG8_LAS bf16x8*)(lds + PG8_SA(b, h) + aoff + m * 2048 + k * 1024); } while (0)
; #define PG8_MMA(ai, bj, At, Bt) do { __builtin_amdgcn_s_setprio(1); _Pragma("unroll") for (int m = 0; m < 4; ++m) _Pragma("unroll") for (int n = 0; n < 2; ++n) _Pragma("unroll") for (int k = 0; k < 2; ++k) \
;         acc[ai][bj][m][n] = __builtin_amdgcn_mfma_f32_16x16x32_bf16(Bt[n][k], At[m][k], acc[ai][bj][m][n], 0, 0, 0); __builtin_amdgcn_s_setprio(0); } while (0)
; #define PG8_WAIT_V(n) asm volatile("s_waitcnt vmcnt(" #n ")" ::: "memory")
; #define PG8_WAIT_L(n) asm volatile("s_waitcnt lgkmcnt(" #n ")" ::: "memory")
; #define PG8_BAR __builtin_amdgcn_s_barrier()
; #define PG8_SCHED __builtin_amdgcn_sched_barrier(0)
; template <class Epi, class Sched, bool ALIGN_EPI = false, bool SP2 = false>
; __device__ __forceinline__ void gemm_phase(PG8_LAS unsigned char* lds, const Gemm g, const Sched& S, const Epi& E) {
;     ...
;             PG8_LDA(At, 1, 1); PG8_STAGEB(PG8_SB(1, 0), b3, voffB); PG8_STAGEB(PG8_SB(1, 1), b3 + hstep, voffB); PG8_STAGE(PG8_SA(1, 0), a3, voffA);
;             PG8_WAIT_V(8); PG8_WAIT_L(0); PG8_BAR; PG8_MMA(1, 0, At, B0); PG8_MMA(1, 1, At, B1); PG8_BAR; PG8_SCHED;
	s_add_i32 s30, s56, s34
	v_lshl_add_u64 v[220:221], v[220:221], 0, s[20:21]
	s_mov_b32 m0, s30
	ds_read_b128 v[186:189], v155 offset:49152
	ds_read_b128 v[192:195], v155 offset:50176
	ds_read_b128 v[196:199], v155 offset:51200
	ds_read_b128 v[200:203], v155 offset:52224
	ds_read_b128 v[204:207], v155 offset:53248
	ds_read_b128 v[208:211], v155 offset:54272
	ds_read_b128 v[212:215], v155 offset:55296
	ds_read_b128 v[216:219], v155 offset:56320
	global_load_lds_dwordx4 v[220:221], off
	s_add_i32 m0, s30, 0x2000
	s_add_u32 s28, s28, 0x160080
	v_lshl_add_u64 v[220:221], v[222:223], 0, s[20:21]
	s_addc_u32 s29, s29, 0
	s_add_i32 s30, s57, s34
	global_load_lds_dwordx4 v[220:221], off
	v_lshl_add_u64 v[220:221], s[28:29], 0, v[132:133]
	s_mov_b32 m0, s30
	s_nop 0
	global_load_lds_dwordx4 v[220:221], off
	v_lshl_add_u64 v[220:221], s[28:29], 0, v[136:137]
	s_add_i32 m0, s30, 0x2000
	s_nop 0
	global_load_lds_dwordx4 v[220:221], off
	v_lshl_add_u64 v[220:221], v[224:225], 0, s[20:21]
	s_mov_b32 m0, s44
	s_nop 0
	global_load_lds_dwordx4 v[220:221], off
	v_lshl_add_u64 v[220:221], v[226:227], 0, s[20:21]
	s_mov_b32 m0, s45
	s_nop 0
	global_load_lds_dwordx4 v[220:221], off
	s_waitcnt vmcnt(8)
	s_waitcnt lgkmcnt(0)
	s_barrier
	s_waitcnt lgkmcnt(0)
	v_mfma_f32_16x16x32_bf16 v[62:65], v[146:149], v[186:189], v[62:65]
	v_mfma_f32_16x16x32_bf16 v[58:61], v[162:165], v[186:189], v[58:61]
	v_mfma_f32_16x16x32_bf16 v[46:49], v[146:149], v[196:199], v[46:49]
	v_mfma_f32_16x16x32_bf16 v[42:45], v[162:165], v[196:199], v[42:45]
	v_mfma_f32_16x16x32_bf16 v[30:33], v[146:149], v[204:207], v[30:33]
	v_mfma_f32_16x16x32_bf16 v[26:29], v[162:165], v[204:207], v[26:29]
	v_mfma_f32_16x16x32_bf16 v[14:17], v[146:149], v[212:215], v[14:17]
	v_mfma_f32_16x16x32_bf16 v[10:13], v[162:165], v[212:215], v[10:13]
	v_mfma_f32_16x16x32_bf16 v[62:65], v[158:161], v[192:195], v[62:65]
	v_mfma_f32_16x16x32_bf16 v[58:61], v[166:169], v[192:195], v[58:61]
	v_mfma_f32_16x16x32_bf16 v[46:49], v[158:161], v[200:203], v[46:49]
	v_mfma_f32_16x16x32_bf16 v[42:45], v[166:169], v[200:203], v[42:45]
	v_mfma_f32_16x16x32_bf16 v[30:33], v[158:161], v[208:211], v[30:33]
	v_mfma_f32_16x16x32_bf16 v[26:29], v[166:169], v[208:211], v[26:29]
	v_mfma_f32_16x16x32_bf16 v[14:17], v[158:161], v[216:219], v[14:17]
	v_mfma_f32_16x16x32_bf16 v[10:13], v[166:169], v[216:219], v[10:13]
	v_mfma_f32_16x16x32_bf16 v[54:57], v[170:173], v[186:189], v[54:57]
	v_mfma_f32_16x16x32_bf16 v[50:53], v[178:181], v[186:189], v[50:53]
	v_mfma_f32_16x16x32_bf16 v[38:41], v[170:173], v[196:199], v[38:41]
	v_mfma_f32_16x16x32_bf16 v[34:37], v[178:181], v[196:199], v[34:37]
	v_mfma_f32_16x16x32_bf16 v[22:25], v[170:173], v[204:207], v[22:25]
	v_mfma_f32_16x16x32_bf16 v[18:21], v[178:181], v[204:207], v[18:21]
	v_mfma_f32_16x16x32_bf16 v[6:9], v[170:173], v[212:215], v[6:9]
	v_mfma_f32_16x16x32_bf16 v[2:5], v[178:181], v[212:215], v[2:5]
	v_mfma_f32_16x16x32_bf16 v[54:57], v[174:177], v[192:195], v[54:57]
	v_mfma_f32_16x16x32_bf16 v[50:53], v[182:185], v[192:195], v[50:53]
	v_mfma_f32_16x16x32_bf16 v[38:41], v[174:177], v[200:203], v[38:41]
	v_mfma_f32_16x16x32_bf16 v[34:37], v[182:185], v[200:203], v[34:37]
	v_mfma_f32_16x16x32_bf16 v[22:25], v[174:177], v[208:211], v[22:25]
	v_mfma_f32_16x16x32_bf16 v[18:21], v[182:185], v[208:211], v[18:21]
	v_mfma_f32_16x16x32_bf16 v[6:9], v[174:177], v[216:219], v[6:9]
	v_mfma_f32_16x16x32_bf16 v[2:5], v[182:185], v[216:219], v[2:5]
	s_barrier
	s_add_i32 s55, s55, 2
	s_add_u32 s26, s26, 0x100
	s_addc_u32 s27, s27, 0
	s_add_u32 s53, s53, 0x100
	s_addc_u32 s54, s54, 0
	s_cmpk_gt_u32 s55, 0x55
	s_cbranch_scc0 .LBB0_608
	s_and_b64 vcc, exec, s[22:23]
	s_cbranch_vccz .LBB0_611
	s_barrier

; #define PG8_STAGE(bufoff, gbase, voff) do { _Pragma("unroll") for (int _i = 0; _i < 2; ++_i) \
;         __builtin_amdgcn_global_load_lds((const unsigned*)((const char*)(gbase) + (voff)[_i]), (PG8_LAS unsigned*)(lds + (bufoff) + ldsw + _i * 8192), 16, 0, 0); } while (0)
; #define PG8_STAGEB(bufoff, gbase, voff) do { _Pragma("unroll") for (int _i = 0; _i < 2; ++_i) \
;         __builtin_amdgcn_global_load_lds((const unsigned*)((const char*)(gbase) + (voff)[_i]), (PG8_LAS unsigned*)(lds + (bufoff) + ldsw + _i * 8192), 16, 0, PG8_BAUX); } while (0)
; #define PG8_LDA(dst, b, h) do { _Pragma("unroll") for (int m = 0; m < 4; ++m) _Pragma("unroll") for (int k = 0; k < 2; ++k) dst[m][k] = *(const PG8_LAS bf16x8*)(lds + PG8_SA(b, h) + aoff + m * 2048 + k * 1024); } while (0)
; #define PG8_LDB(dst, b, h) do { _Pragma("unroll") for (int n = 0; n < 2; ++n) _Pragma("unroll") for (int k = 0; k < 2; ++k) dst[n][k] = *(const PG8_LAS bf16x8*)(lds + PG8_SB(b, h) + boff + n * 2048 + k * 1024); } while (0)
; #define PG8_MMA(ai, bj, At, Bt) do { __builtin_amdgcn_s_setprio(1); _Pragma("unroll") for (int m = 0; m < 4; ++m) _Pragma("unroll") for (int n = 0; n < 2; ++n) _Pragma("unroll") for (int k = 0; k < 2; ++k) \
;         acc[ai][bj][m][n] = __builtin_amdgcn_mfma_f32_16x16x32_bf16(Bt[n][k], At[m][k], acc[ai][bj][m][n], 0, 0, 0); __builtin_amdgcn_s_setprio(0); } while (0)
; #define PG8_WAIT_V(n) asm volatile("s_waitcnt vmcnt(" #n ")" ::: "memory")
; #define PG8_WAIT_L(n) asm volatile("s_waitcnt lgkmcnt(" #n ")" ::: "memory")
; #define PG8_BAR __builtin_amdgcn_s_barrier()
; #define PG8_SCHED __builtin_amdgcn_sched_barrier(0)
; template <class Epi, class Sched, bool ALIGN_EPI = false, bool SP2 = false>
; __device__ __forceinline__ void gemm_phase(PG8_LAS unsigned char* lds, const Gemm g, const Sched& S, const Epi& E) {
;     ...
;             PG8_LDB(B0, 0, 0); PG8_LDB(B1, 0, 1); PG8_SCHED; PG8_LDA(At, 0, 0); PG8_STAGE(PG8_SA(1, 1), a1 + hstep, voffA);
;             PG8_WAIT_V(8); PG8_WAIT_L(0); PG8_BAR; PG8_MMA(0, 0, At, B0); PG8_MMA(0, 1, At, B1); PG8_BAR; PG8_SCHED;
;             PG8_LDA(At, 0, 1); PG8_STAGEB(PG8_SB(0, 0), b2, voffB); PG8_STAGEB(PG8_SB(0, 1), b2 + hstep, voffB); PG8_STAGE(PG8_SA(0, 0), a2, voffA);
;             PG8_WAIT_V(8); PG8_WAIT_L(0); PG8_BAR; PG8_MMA(1, 0, At, B0); PG8_MMA(1, 1, At, B1); PG8_BAR; PG8_SCHED;
.LBB0_709:
	ds_read_b128 v[160:163], v141
	ds_read_b128 v[164:167], v141 offset:1024
	ds_read_b128 v[168:171], v141 offset:2048
	ds_read_b128 v[172:175], v141 offset:3072
	ds_read_b128 v[176:179], v196
	ds_read_b128 v[202:205], v196 offset:1024
	ds_read_b128 v[206:209], v196 offset:2048
	ds_read_b128 v[210:213], v196 offset:3072
	s_add_u32 s6, s4, 0xfff80080
	s_addc_u32 s7, s5, -1
	s_cmp_eq_u32 s50, 28
	s_cselect_b32 s9, s3, s7
	s_cselect_b32 s8, s15, s6
	s_cselect_b32 s7, s18, s45
	s_cselect_b32 s6, s33, s43
	v_lshl_add_u64 v[180:181], s[4:5], 0, v[156:157]
	s_add_i32 m0, s63, 0xc000
	ds_read_b128 v[214:217], v197
	ds_read_b128 v[218:221], v197 offset:1024
	ds_read_b128 v[222:225], v197 offset:2048
	ds_read_b128 v[226:229], v197 offset:3072
	ds_read_b128 v[230:233], v197 offset:4096
	ds_read_b128 v[234:237], v197 offset:5120
	ds_read_b128 v[238:241], v197 offset:6144
	ds_read_b128 v[242:245], v197 offset:7168
	global_load_lds_dwordx4 v[180:181], off
	v_lshl_add_u64 v[180:181], s[4:5], 0, v[158:159]
	s_add_i32 m0, s63, 0xe000
	s_nop 0
	global_load_lds_dwordx4 v[180:181], off
	s_waitcnt vmcnt(8)
	s_waitcnt lgkmcnt(0)
	s_barrier
	s_waitcnt lgkmcnt(0)
	v_mfma_f32_16x16x32_bf16 v[126:129], v[160:163], v[214:217], v[126:129]
	v_mfma_f32_16x16x32_bf16 v[122:125], v[168:171], v[214:217], v[122:125]
	v_mfma_f32_16x16x32_bf16 v[110:113], v[160:163], v[222:225], v[110:113]
	v_mfma_f32_16x16x32_bf16 v[106:109], v[168:171], v[222:225], v[106:109]
	v_mfma_f32_16x16x32_bf16 v[94:97], v[160:163], v[230:233], v[94:97]
	v_mfma_f32_16x16x32_bf16 v[90:93], v[168:171], v[230:233], v[90:93]
	v_mfma_f32_16x16x32_bf16 v[78:81], v[160:163], v[238:241], v[78:81]
	v_mfma_f32_16x16x32_bf16 v[74:77], v[168:171], v[238:241], v[74:77]
	v_mfma_f32_16x16x32_bf16 v[126:129], v[164:167], v[218:221], v[126:129]
	v_mfma_f32_16x16x32_bf16 v[122:125], v[172:175], v[218:221], v[122:125]
	v_mfma_f32_16x16x32_bf16 v[110:113], v[164:167], v[226:229], v[110:113]
	v_mfma_f32_16x16x32_bf16 v[106:109], v[172:175], v[226:229], v[106:109]
	v_mfma_f32_16x16x32_bf16 v[94:97], v[164:167], v[234:237], v[94:97]
	v_mfma_f32_16x16x32_bf16 v[90:93], v[172:175], v[234:237], v[90:93]
	v_mfma_f32_16x16x32_bf16 v[78:81], v[164:167], v[242:245], v[78:81]
	v_mfma_f32_16x16x32_bf16 v[74:77], v[172:175], v[242:245], v[74:77]
	v_mfma_f32_16x16x32_bf16 v[118:121], v[176:179], v[214:217], v[118:121]
	v_mfma_f32_16x16x32_bf16 v[114:117], v[206:209], v[214:217], v[114:117]
	v_mfma_f32_16x16x32_bf16 v[102:105], v[176:179], v[222:225], v[102:105]
	v_mfma_f32_16x16x32_bf16 v[98:101], v[206:209], v[222:225], v[98:101]
	v_mfma_f32_16x16x32_bf16 v[86:89], v[176:179], v[230:233], v[86:89]
	v_mfma_f32_16x16x32_bf16 v[82:85], v[206:209], v[230:233], v[82:85]
	v_mfma_f32_16x16x32_bf16 v[70:73], v[176:179], v[238:241], v[70:73]
	v_mfma_f32_16x16x32_bf16 v[66:69], v[206:209], v[238:241], v[66:69]
	v_mfma_f32_16x16x32_bf16 v[118:121], v[202:205], v[218:221], v[118:121]
	v_mfma_f32_16x16x32_bf16 v[114:117], v[210:213], v[218:221], v[114:117]
	v_mfma_f32_16x16x32_bf16 v[102:105], v[202:205], v[226:229], v[102:105]
	v_mfma_f32_16x16x32_bf16 v[98:101], v[210:213], v[226:229], v[98:101]
	v_mfma_f32_16x16x32_bf16 v[86:89], v[202:205], v[234:237], v[86:89]
	v_mfma_f32_16x16x32_bf16 v[82:85], v[210:213], v[234:237], v[82:85]
	v_mfma_f32_16x16x32_bf16 v[70:73], v[202:205], v[242:245], v[70:73]
	v_mfma_f32_16x16x32_bf16 v[66:69], v[210:213], v[242:245], v[66:69]
	s_barrier
	s_add_i32 s51, s77, s60
	v_lshl_add_u64 v[180:181], s[6:7], 0, v[132:133]
	s_mov_b32 m0, s51
	ds_read_b128 v[214:217], v197 offset:16384
	ds_read_b128 v[218:221], v197 offset:17408
	ds_read_b128 v[222:225], v197 offset:18432
	ds_read_b128 v[226:229], v197 offset:19456
	ds_read_b128 v[230:233], v197 offset:20480
	ds_read_b128 v[234:237], v197 offset:21504
	ds_read_b128 v[238:241], v197 offset:22528
	ds_read_b128 v[242:245], v197 offset:23552
	global_load_lds_dwordx4 v[180:181], off
	s_add_i32 m0, s51, 0x2000
	s_add_u32 s52, s6, 0x80000
	v_lshl_add_u64 v[246:247], s[6:7], 0, v[136:137]
	s_addc_u32 s53, s7, 0
	s_add_i32 s51, s78, s60
	global_load_lds_dwordx4 v[246:247], off
	v_lshl_add_u64 v[248:249], s[52:53], 0, v[132:133]
	s_mov_b32 m0, s51
	v_lshl_add_u64 v[250:251], s[8:9], 0, v[134:135]
	global_load_lds_dwordx4 v[248:249], off
	v_lshl_add_u64 v[248:249], s[52:53], 0, v[136:137]
	s_add_i32 m0, s51, 0x2000
	s_nop 0
	global_load_lds_dwordx4 v[248:249], off
	v_lshl_add_u64 v[248:249], s[8:9], 0, v[130:131]
	s_mov_b32 m0, s63
	s_nop 0
	global_load_lds_dwordx4 v[248:249], off
	s_mov_b32 m0, s64
	s_nop 0
	global_load_lds_dwordx4 v[250:251], off
	s_waitcnt vmcnt(8)
	s_waitcnt lgkmcnt(0)
	s_barrier
; #define PG8_STAGE(bufoff, gbase, voff) do { _Pragma("unroll") for (int _i = 0; _i < 2; ++_i) \
;         __builtin_amdgcn_global_load_lds((const unsigned*)((const char*)(gbase) + (voff)[_i]), (PG8_LAS unsigned*)(lds + (bufoff) + ldsw + _i * 8192), 16, 0, 0); } while (0)
; #define PG8_LDA(dst, b, h) do { _Pragma("unroll") for (int m = 0; m < 4; ++m) _Pragma("unroll") for (int k = 0; k < 2; ++k) dst[m][k] = *(const PG8_LAS bf16x8*)(lds + PG8_SA(b, h) + aoff + m * 2048 + k * 1024); } while (0)
; #define PG8_LDB(dst, b, h) do { _Pragma("unroll") for (int n = 0; n < 2; ++n) _Pragma("unroll") for (int k = 0; k < 2; ++k) dst[n][k] = *(const PG8_LAS bf16x8*)(lds + PG8_SB(b, h) + boff + n * 2048 + k * 1024); } while (0)
; #define PG8_MMA(ai, bj, At, Bt) do { __builtin_amdgcn_s_setprio(1); _Pragma("unroll") for (int m = 0; m < 4; ++m) _Pragma("unroll") for (int n = 0; n < 2; ++n) _Pragma("unroll") for (int k = 0; k < 2; ++k) \
;         acc[ai][bj][m][n] = __builtin_amdgcn_mfma_f32_16x16x32_bf16(Bt[n][k], At[m][k], acc[ai][bj][m][n], 0, 0, 0); __builtin_amdgcn_s_setprio(0); } while (0)
; #define PG8_WAIT_V(n) asm volatile("s_waitcnt vmcnt(" #n ")" ::: "memory")
; #define PG8_WAIT_L(n) asm volatile("s_waitcnt lgkmcnt(" #n ")" ::: "memory")
; #define PG8_BAR __builtin_amdgcn_s_barrier()
; #define PG8_SCHED __builtin_amdgcn_sched_barrier(0)
; template <class Epi, class Sched, bool ALIGN_EPI = false, bool SP2 = false>
; __device__ __forceinline__ void gemm_phase(PG8_LAS unsigned char* lds, const Gemm g, const Sched& S, const Epi& E) {
;     ...
;             PG8_WAIT_V(8); PG8_WAIT_L(0); PG8_BAR; PG8_MMA(1, 0, At, B0); PG8_MMA(1, 1, At, B1); PG8_BAR; PG8_SCHED;
;             PG8_LDB(B0, 1, 0); PG8_LDB(B1, 1, 1); PG8_SCHED; PG8_LDA(At, 1, 0); PG8_STAGE(PG8_SA(0, 1), a2 + hstep, voffA);
;             PG8_WAIT_V(8); PG8_WAIT_L(0); PG8_BAR; PG8_MMA(0, 0, At, B0); PG8_MMA(0, 1, At, B1); PG8_BAR; PG8_SCHED;
	s_waitcnt lgkmcnt(0)
	v_mfma_f32_16x16x32_bf16 v[62:65], v[160:163], v[214:217], v[62:65]
	v_mfma_f32_16x16x32_bf16 v[58:61], v[168:171], v[214:217], v[58:61]
	v_mfma_f32_16x16x32_bf16 v[46:49], v[160:163], v[222:225], v[46:49]
	v_mfma_f32_16x16x32_bf16 v[42:45], v[168:171], v[222:225], v[42:45]
	v_mfma_f32_16x16x32_bf16 v[30:33], v[160:163], v[230:233], v[30:33]
	v_mfma_f32_16x16x32_bf16 v[26:29], v[168:171], v[230:233], v[26:29]
	v_mfma_f32_16x16x32_bf16 v[14:17], v[160:163], v[238:241], v[14:17]
	v_mfma_f32_16x16x32_bf16 v[10:13], v[168:171], v[238:241], v[10:13]
	v_mfma_f32_16x16x32_bf16 v[62:65], v[164:167], v[218:221], v[62:65]
	v_mfma_f32_16x16x32_bf16 v[58:61], v[172:175], v[218:221], v[58:61]
	v_mfma_f32_16x16x32_bf16 v[46:49], v[164:167], v[226:229], v[46:49]
	v_mfma_f32_16x16x32_bf16 v[42:45], v[172:175], v[226:229], v[42:45]
	v_mfma_f32_16x16x32_bf16 v[30:33], v[164:167], v[234:237], v[30:33]
	v_mfma_f32_16x16x32_bf16 v[26:29], v[172:175], v[234:237], v[26:29]
	v_mfma_f32_16x16x32_bf16 v[14:17], v[164:167], v[242:245], v[14:17]
	v_mfma_f32_16x16x32_bf16 v[10:13], v[172:175], v[242:245], v[10:13]
	v_mfma_f32_16x16x32_bf16 v[54:57], v[176:179], v[214:217], v[54:57]
	v_mfma_f32_16x16x32_bf16 v[50:53], v[206:209], v[214:217], v[50:53]
	v_mfma_f32_16x16x32_bf16 v[38:41], v[176:179], v[222:225], v[38:41]
	v_mfma_f32_16x16x32_bf16 v[34:37], v[206:209], v[222:225], v[34:37]
	v_mfma_f32_16x16x32_bf16 v[22:25], v[176:179], v[230:233], v[22:25]
	v_mfma_f32_16x16x32_bf16 v[18:21], v[206:209], v[230:233], v[18:21]
	v_mfma_f32_16x16x32_bf16 v[6:9], v[176:179], v[238:241], v[6:9]
	v_mfma_f32_16x16x32_bf16 v[2:5], v[206:209], v[238:241], v[2:5]
	v_mfma_f32_16x16x32_bf16 v[54:57], v[202:205], v[218:221], v[54:57]
	v_mfma_f32_16x16x32_bf16 v[50:53], v[210:213], v[218:221], v[50:53]
	v_mfma_f32_16x16x32_bf16 v[38:41], v[202:205], v[226:229], v[38:41]
	v_mfma_f32_16x16x32_bf16 v[34:37], v[210:213], v[226:229], v[34:37]
	v_mfma_f32_16x16x32_bf16 v[22:25], v[202:205], v[234:237], v[22:25]
	v_mfma_f32_16x16x32_bf16 v[18:21], v[210:213], v[234:237], v[18:21]
	v_mfma_f32_16x16x32_bf16 v[6:9], v[202:205], v[242:245], v[6:9]
	v_mfma_f32_16x16x32_bf16 v[2:5], v[210:213], v[242:245], v[2:5]
	s_barrier
	s_add_i32 s51, 0, 0x18000
	v_add_u32_e32 v142, s51, v193
	s_add_i32 s52, 0, 0x1c000
	ds_read_b128 v[160:163], v142
	ds_read_b128 v[164:167], v142 offset:1024
	ds_read_b128 v[168:171], v142 offset:2048
	ds_read_b128 v[172:175], v142 offset:3072
	v_add_u32_e32 v142, s52, v193
	ds_read_b128 v[176:179], v142
	ds_read_b128 v[202:205], v142 offset:1024
	ds_read_b128 v[206:209], v142 offset:2048
	ds_read_b128 v[210:213], v142 offset:3072
	s_add_u32 s8, s8, 0x80000
	s_addc_u32 s9, s9, 0
	s_mov_b32 m0, s65
	v_lshl_add_u64 v[252:253], s[8:9], 0, v[130:131]
	ds_read_b128 v[214:217], v197 offset:32768
	ds_read_b128 v[218:221], v197 offset:33792
	ds_read_b128 v[222:225], v197 offset:34816
	ds_read_b128 v[226:229], v197 offset:35840
	ds_read_b128 v[230:233], v197 offset:36864
	ds_read_b128 v[234:237], v197 offset:37888
	ds_read_b128 v[238:241], v197 offset:38912
	ds_read_b128 v[242:245], v197 offset:39936
	global_load_lds_dwordx4 v[252:253], off
	v_lshl_add_u64 v[252:253], s[8:9], 0, v[134:135]
	s_mov_b32 m0, s66
	s_nop 0
	global_load_lds_dwordx4 v[252:253], off
	s_waitcnt vmcnt(8)
	s_waitcnt lgkmcnt(0)
	s_barrier
	s_waitcnt lgkmcnt(0)
	v_mfma_f32_16x16x32_bf16 v[126:129], v[160:163], v[214:217], v[126:129]
	v_mfma_f32_16x16x32_bf16 v[122:125], v[168:171], v[214:217], v[122:125]
	v_mfma_f32_16x16x32_bf16 v[110:113], v[160:163], v[222:225], v[110:113]
	v_mfma_f32_16x16x32_bf16 v[106:109], v[168:171], v[222:225], v[106:109]
	v_mfma_f32_16x16x32_bf16 v[94:97], v[160:163], v[230:233], v[94:97]
	v_mfma_f32_16x16x32_bf16 v[90:93], v[168:171], v[230:233], v[90:93]
	v_mfma_f32_16x16x32_bf16 v[78:81], v[160:163], v[238:241], v[78:81]
	v_mfma_f32_16x16x32_bf16 v[74:77], v[168:171], v[238:241], v[74:77]
	v_mfma_f32_16x16x32_bf16 v[126:129], v[164:167], v[218:221], v[126:129]
	v_mfma_f32_16x16x32_bf16 v[122:125], v[172:175], v[218:221], v[122:125]
	v_mfma_f32_16x16x32_bf16 v[110:113], v[164:167], v[226:229], v[110:113]
	v_mfma_f32_16x16x32_bf16 v[106:109], v[172:175], v[226:229], v[106:109]
	v_mfma_f32_16x16x32_bf16 v[94:97], v[164:167], v[234:237], v[94:97]
	v_mfma_f32_16x16x32_bf16 v[90:93], v[172:175], v[234:237], v[90:93]
	v_mfma_f32_16x16x32_bf16 v[78:81], v[164:167], v[242:245], v[78:81]
	v_mfma_f32_16x16x32_bf16 v[74:77], v[172:175], v[242:245], v[74:77]
	v_mfma_f32_16x16x32_bf16 v[118:121], v[176:179], v[214:217], v[118:121]
	v_mfma_f32_16x16x32_bf16 v[114:117], v[206:209], v[214:217], v[114:117]
	v_mfma_f32_16x16x32_bf16 v[102:105], v[176:179], v[222:225], v[102:105]
	v_mfma_f32_16x16x32_bf16 v[98:101], v[206:209], v[222:225], v[98:101]
	v_mfma_f32_16x16x32_bf16 v[86:89], v[176:179], v[230:233], v[86:89]
	v_mfma_f32_16x16x32_bf16 v[82:85], v[206:209], v[230:233], v[82:85]
	v_mfma_f32_16x16x32_bf16 v[70:73], v[176:179], v[238:241], v[70:73]
	v_mfma_f32_16x16x32_bf16 v[66:69], v[206:209], v[238:241], v[66:69]
	v_mfma_f32_16x16x32_bf16 v[118:121], v[202:205], v[218:221], v[118:121]
	v_mfma_f32_16x16x32_bf16 v[114:117], v[210:213], v[218:221], v[114:117]
	v_mfma_f32_16x16x32_bf16 v[102:105], v[202:205], v[226:229], v[102:105]
	v_mfma_f32_16x16x32_bf16 v[98:101], v[210:213], v[226:229], v[98:101]
	v_mfma_f32_16x16x32_bf16 v[86:89], v[202:205], v[234:237], v[86:89]
	v_mfma_f32_16x16x32_bf16 v[82:85], v[210:213], v[234:237], v[82:85]
	v_mfma_f32_16x16x32_bf16 v[70:73], v[202:205], v[242:245], v[70:73]
	v_mfma_f32_16x16x32_bf16 v[66:69], v[210:213], v[242:245], v[66:69]
	s_barrier
; #define PG8_STAGE(bufoff, gbase, voff) do { _Pragma("unroll") for (int _i = 0; _i < 2; ++_i) \
;         __builtin_amdgcn_global_load_lds((const unsigned*)((const char*)(gbase) + (voff)[_i]), (PG8_LAS unsigned*)(lds + (bufoff) + ldsw + _i * 8192), 16, 0, 0); } while (0)
; #define PG8_STAGEB(bufoff, gbase, voff) do { _Pragma("unroll") for (int _i = 0; _i < 2; ++_i) \
;         __builtin_amdgcn_global_load_lds((const unsigned*)((const char*)(gbase) + (voff)[_i]), (PG8_LAS unsigned*)(lds + (bufoff) + ldsw + _i * 8192), 16, 0, PG8_BAUX); } while (0)
; #define PG8_LDA(dst, b, h) do { _Pragma("unroll") for (int m = 0; m < 4; ++m) _Pragma("unroll") for (int k = 0; k < 2; ++k) dst[m][k] = *(const PG8_LAS bf16x8*)(lds + PG8_SA(b, h) + aoff + m * 2048 + k * 1024); } while (0)
; #define PG8_MMA(ai, bj, At, Bt) do { __builtin_amdgcn_s_setprio(1); _Pragma("unroll") for (int m = 0; m < 4; ++m) _Pragma("unroll") for (int n = 0; n < 2; ++n) _Pragma("unroll") for (int k = 0; k < 2; ++k) \
;         acc[ai][bj][m][n] = __builtin_amdgcn_mfma_f32_16x16x32_bf16(Bt[n][k], At[m][k], acc[ai][bj][m][n], 0, 0, 0); __builtin_amdgcn_s_setprio(0); } while (0)
; #define PG8_WAIT_V(n) asm volatile("s_waitcnt vmcnt(" #n ")" ::: "memory")
; #define PG8_WAIT_L(n) asm volatile("s_waitcnt lgkmcnt(" #n ")" ::: "memory")
; #define PG8_BAR __builtin_amdgcn_s_barrier()
; #define PG8_SCHED __builtin_amdgcn_sched_barrier(0)
; template <class Epi, class Sched, bool ALIGN_EPI = false, bool SP2 = false>
; __device__ __forceinline__ void gemm_phase(PG8_LAS unsigned char* lds, const Gemm g, const Sched& S, const Epi& E) {
;     ...
;             PG8_LDA(At, 1, 1); PG8_STAGEB(PG8_SB(1, 0), b3, voffB); PG8_STAGEB(PG8_SB(1, 1), b3 + hstep, voffB); PG8_STAGE(PG8_SA(1, 0), a3, voffA);
;             PG8_WAIT_V(8); PG8_WAIT_L(0); PG8_BAR; PG8_MMA(1, 0, At, B0); PG8_MMA(1, 1, At, B1); PG8_BAR; PG8_SCHED;
	s_add_i32 s8, s51, s60
	v_lshl_add_u64 v[180:181], v[180:181], 0, s[22:23]
	s_mov_b32 m0, s8
	ds_read_b128 v[214:217], v197 offset:49152
	ds_read_b128 v[218:221], v197 offset:50176
	ds_read_b128 v[222:225], v197 offset:51200
	ds_read_b128 v[226:229], v197 offset:52224
	ds_read_b128 v[230:233], v197 offset:53248
	ds_read_b128 v[234:237], v197 offset:54272
	ds_read_b128 v[238:241], v197 offset:55296
	ds_read_b128 v[242:245], v197 offset:56320
	global_load_lds_dwordx4 v[180:181], off
	s_add_i32 m0, s8, 0x2000
	s_add_u32 s6, s6, 0x80080
	v_lshl_add_u64 v[180:181], v[246:247], 0, s[22:23]
	s_addc_u32 s7, s7, 0
	s_add_i32 s8, s52, s60
	global_load_lds_dwordx4 v[180:181], off
	v_lshl_add_u64 v[180:181], s[6:7], 0, v[132:133]
	s_mov_b32 m0, s8
	s_nop 0
	global_load_lds_dwordx4 v[180:181], off
	v_lshl_add_u64 v[180:181], s[6:7], 0, v[136:137]
	s_add_i32 m0, s8, 0x2000
	s_nop 0
	global_load_lds_dwordx4 v[180:181], off
	v_lshl_add_u64 v[180:181], v[248:249], 0, s[22:23]
	s_mov_b32 m0, s70
	s_nop 0
	global_load_lds_dwordx4 v[180:181], off
	v_lshl_add_u64 v[180:181], v[250:251], 0, s[22:23]
	s_mov_b32 m0, s71
	s_nop 0
	global_load_lds_dwordx4 v[180:181], off
	s_waitcnt vmcnt(8)
	s_waitcnt lgkmcnt(0)
	s_barrier
	s_waitcnt lgkmcnt(0)
	v_mfma_f32_16x16x32_bf16 v[62:65], v[160:163], v[214:217], v[62:65]
	v_mfma_f32_16x16x32_bf16 v[58:61], v[168:171], v[214:217], v[58:61]
	v_mfma_f32_16x16x32_bf16 v[46:49], v[160:163], v[222:225], v[46:49]
	v_mfma_f32_16x16x32_bf16 v[42:45], v[168:171], v[222:225], v[42:45]
	v_mfma_f32_16x16x32_bf16 v[30:33], v[160:163], v[230:233], v[30:33]
	v_mfma_f32_16x16x32_bf16 v[26:29], v[168:171], v[230:233], v[26:29]
	v_mfma_f32_16x16x32_bf16 v[14:17], v[160:163], v[238:241], v[14:17]
	v_mfma_f32_16x16x32_bf16 v[10:13], v[168:171], v[238:241], v[10:13]
	v_mfma_f32_16x16x32_bf16 v[62:65], v[164:167], v[218:221], v[62:65]
	v_mfma_f32_16x16x32_bf16 v[58:61], v[172:175], v[218:221], v[58:61]
	v_mfma_f32_16x16x32_bf16 v[46:49], v[164:167], v[226:229], v[46:49]
	v_mfma_f32_16x16x32_bf16 v[42:45], v[172:175], v[226:229], v[42:45]
	v_mfma_f32_16x16x32_bf16 v[30:33], v[164:167], v[234:237], v[30:33]
	v_mfma_f32_16x16x32_bf16 v[26:29], v[172:175], v[234:237], v[26:29]
	v_mfma_f32_16x16x32_bf16 v[14:17], v[164:167], v[242:245], v[14:17]
	v_mfma_f32_16x16x32_bf16 v[10:13], v[172:175], v[242:245], v[10:13]
	v_mfma_f32_16x16x32_bf16 v[54:57], v[176:179], v[214:217], v[54:57]
	v_mfma_f32_16x16x32_bf16 v[50:53], v[206:209], v[214:217], v[50:53]
	v_mfma_f32_16x16x32_bf16 v[38:41], v[176:179], v[222:225], v[38:41]
	v_mfma_f32_16x16x32_bf16 v[34:37], v[206:209], v[222:225], v[34:37]
	v_mfma_f32_16x16x32_bf16 v[22:25], v[176:179], v[230:233], v[22:25]
	v_mfma_f32_16x16x32_bf16 v[18:21], v[206:209], v[230:233], v[18:21]
	v_mfma_f32_16x16x32_bf16 v[6:9], v[176:179], v[238:241], v[6:9]
	v_mfma_f32_16x16x32_bf16 v[2:5], v[206:209], v[238:241], v[2:5]
	v_mfma_f32_16x16x32_bf16 v[54:57], v[202:205], v[218:221], v[54:57]
	v_mfma_f32_16x16x32_bf16 v[50:53], v[210:213], v[218:221], v[50:53]
	v_mfma_f32_16x16x32_bf16 v[38:41], v[202:205], v[226:229], v[38:41]
	v_mfma_f32_16x16x32_bf16 v[34:37], v[210:213], v[226:229], v[34:37]
	v_mfma_f32_16x16x32_bf16 v[22:25], v[202:205], v[234:237], v[22:25]
	v_mfma_f32_16x16x32_bf16 v[18:21], v[210:213], v[234:237], v[18:21]
	v_mfma_f32_16x16x32_bf16 v[6:9], v[202:205], v[242:245], v[6:9]
	v_mfma_f32_16x16x32_bf16 v[2:5], v[210:213], v[242:245], v[2:5]
	s_barrier
	s_add_i32 s50, s50, 2
	s_add_u32 s4, s4, 0x100
	s_addc_u32 s5, s5, 0
	s_add_u32 s43, s43, 0x100
	s_addc_u32 s45, s45, 0
	s_cmp_gt_u32 s50, 29
	s_cbranch_scc0 .LBB0_709
	s_and_b64 vcc, exec, s[24:25]
	s_cbranch_vccz .LBB0_712
	s_barrier

; #define PG8_STAGE(bufoff, gbase, voff) do { _Pragma("unroll") for (int _i = 0; _i < 2; ++_i) \
;         __builtin_amdgcn_global_load_lds((const unsigned*)((const char*)(gbase) + (voff)[_i]), (PG8_LAS unsigned*)(lds + (bufoff) + ldsw + _i * 8192), 16, 0, 0); } while (0)
; #define PG8_STAGEB(bufoff, gbase, voff) do { _Pragma("unroll") for (int _i = 0; _i < 2; ++_i) \
;         __builtin_amdgcn_global_load_lds((const unsigned*)((const char*)(gbase) + (voff)[_i]), (PG8_LAS unsigned*)(lds + (bufoff) + ldsw + _i * 8192), 16, 0, PG8_BAUX); } while (0)
; #define PG8_LDA(dst, b, h) do { _Pragma("unroll") for (int m = 0; m < 4; ++m) _Pragma("unroll") for (int k = 0; k < 2; ++k) dst[m][k] = *(const PG8_LAS bf16x8*)(lds + PG8_SA(b, h) + aoff + m * 2048 + k * 1024); } while (0)
; #define PG8_LDB(dst, b, h) do { _Pragma("unroll") for (int n = 0; n < 2; ++n) _Pragma("unroll") for (int k = 0; k < 2; ++k) dst[n][k] = *(const PG8_LAS bf16x8*)(lds + PG8_SB(b, h) + boff + n * 2048 + k * 1024); } while (0)
; #define PG8_MMA(ai, bj, At, Bt) do { __builtin_amdgcn_s_setprio(1); _Pragma("unroll") for (int m = 0; m < 4; ++m) _Pragma("unroll") for (int n = 0; n < 2; ++n) _Pragma("unroll") for (int k = 0; k < 2; ++k) \
;         acc[ai][bj][m][n] = __builtin_amdgcn_mfma_f32_16x16x32_bf16(Bt[n][k], At[m][k], acc[ai][bj][m][n], 0, 0, 0); __builtin_amdgcn_s_setprio(0); } while (0)
; #define PG8_WAIT_V(n) asm volatile("s_waitcnt vmcnt(" #n ")" ::: "memory")
; #define PG8_WAIT_L(n) asm volatile("s_waitcnt lgkmcnt(" #n ")" ::: "memory")
; #define PG8_BAR __builtin_amdgcn_s_barrier()
; #define PG8_SCHED __builtin_amdgcn_sched_barrier(0)
; template <class Epi, class Sched, bool ALIGN_EPI = false, bool SP2 = false>
; __device__ __forceinline__ void gemm_phase(PG8_LAS unsigned char* lds, const Gemm g, const Sched& S, const Epi& E) {
;     ...
;             PG8_LDB(B0, 0, 0); PG8_LDB(B1, 0, 1); PG8_SCHED; PG8_LDA(At, 0, 0); PG8_STAGE(PG8_SA(1, 1), a1 + hstep, voffA);
;             PG8_WAIT_V(8); PG8_WAIT_L(0); PG8_BAR; PG8_MMA(0, 0, At, B0); PG8_MMA(0, 1, At, B1); PG8_BAR; PG8_SCHED;
;             PG8_LDA(At, 0, 1); PG8_STAGEB(PG8_SB(0, 0), b2, voffB); PG8_STAGEB(PG8_SB(0, 1), b2 + hstep, voffB); PG8_STAGE(PG8_SA(0, 0), a2, voffA);
.LBB0_952:
	ds_read_b128 v[150:153], v139
	ds_read_b128 v[154:157], v139 offset:1024
	ds_read_b128 v[158:161], v139 offset:2048
	ds_read_b128 v[162:165], v139 offset:3072
	ds_read_b128 v[166:169], v145
	ds_read_b128 v[170:173], v145 offset:1024
	ds_read_b128 v[174:177], v145 offset:2048
	ds_read_b128 v[178:181], v145 offset:3072
	s_add_u32 s10, s6, s8
	s_addc_u32 s11, s7, s9
	s_add_u32 s10, s10, 0x8700100
	s_addc_u32 s11, s11, 0
	s_add_u32 s45, s29, s8
	s_addc_u32 s46, s30, s9
	s_cmpk_eq_i32 s8, 0x300
	s_cselect_b32 s15, s3, s11
	s_cselect_b32 s14, s2, s10
	s_cselect_b32 s11, s1, s46
	s_cselect_b32 s10, s0, s45
	s_mov_b32 m0, s33
	v_lshl_add_u64 v[216:217], v[140:141], 0, s[8:9]
	ds_read_b128 v[182:185], v146
	ds_read_b128 v[186:189], v146 offset:1024
	ds_read_b128 v[192:195], v146 offset:2048
	ds_read_b128 v[196:199], v146 offset:3072
	ds_read_b128 v[200:203], v146 offset:4096
	ds_read_b128 v[204:207], v146 offset:5120
	ds_read_b128 v[208:211], v146 offset:6144
	ds_read_b128 v[212:215], v146 offset:7168
	global_load_lds_dwordx4 v[216:217], off
	v_lshl_add_u64 v[216:217], v[142:143], 0, s[8:9]
	s_mov_b32 m0, s34
	s_nop 0
	global_load_lds_dwordx4 v[216:217], off
	s_waitcnt vmcnt(8)
	s_waitcnt lgkmcnt(0)
	s_barrier
	s_waitcnt lgkmcnt(0)
	v_mfma_f32_16x16x32_bf16 v[126:129], v[150:153], v[182:185], v[126:129]
	v_mfma_f32_16x16x32_bf16 v[122:125], v[158:161], v[182:185], v[122:125]
	v_mfma_f32_16x16x32_bf16 v[118:121], v[150:153], v[192:195], v[118:121]
	v_mfma_f32_16x16x32_bf16 v[114:117], v[158:161], v[192:195], v[114:117]
	v_mfma_f32_16x16x32_bf16 v[102:105], v[150:153], v[200:203], v[102:105]
	v_mfma_f32_16x16x32_bf16 v[98:101], v[158:161], v[200:203], v[98:101]
	v_mfma_f32_16x16x32_bf16 v[86:89], v[150:153], v[208:211], v[86:89]
	v_mfma_f32_16x16x32_bf16 v[82:85], v[158:161], v[208:211], v[82:85]
	v_mfma_f32_16x16x32_bf16 v[126:129], v[154:157], v[186:189], v[126:129]
	v_mfma_f32_16x16x32_bf16 v[122:125], v[162:165], v[186:189], v[122:125]
	v_mfma_f32_16x16x32_bf16 v[118:121], v[154:157], v[196:199], v[118:121]
	v_mfma_f32_16x16x32_bf16 v[114:117], v[162:165], v[196:199], v[114:117]
	v_mfma_f32_16x16x32_bf16 v[102:105], v[154:157], v[204:207], v[102:105]
	v_mfma_f32_16x16x32_bf16 v[98:101], v[162:165], v[204:207], v[98:101]
	v_mfma_f32_16x16x32_bf16 v[86:89], v[154:157], v[212:215], v[86:89]
	v_mfma_f32_16x16x32_bf16 v[82:85], v[162:165], v[212:215], v[82:85]
	v_mfma_f32_16x16x32_bf16 v[110:113], v[166:169], v[182:185], v[110:113]
	v_mfma_f32_16x16x32_bf16 v[106:109], v[174:177], v[182:185], v[106:109]
	v_mfma_f32_16x16x32_bf16 v[94:97], v[166:169], v[192:195], v[94:97]
	v_mfma_f32_16x16x32_bf16 v[90:93], v[174:177], v[192:195], v[90:93]
	v_mfma_f32_16x16x32_bf16 v[78:81], v[166:169], v[200:203], v[78:81]
	v_mfma_f32_16x16x32_bf16 v[74:77], v[174:177], v[200:203], v[74:77]
	v_mfma_f32_16x16x32_bf16 v[70:73], v[166:169], v[208:211], v[70:73]
	v_mfma_f32_16x16x32_bf16 v[66:69], v[174:177], v[208:211], v[66:69]
	v_mfma_f32_16x16x32_bf16 v[110:113], v[170:173], v[186:189], v[110:113]
	v_mfma_f32_16x16x32_bf16 v[106:109], v[178:181], v[186:189], v[106:109]
	v_mfma_f32_16x16x32_bf16 v[94:97], v[170:173], v[196:199], v[94:97]
	v_mfma_f32_16x16x32_bf16 v[90:93], v[178:181], v[196:199], v[90:93]
	v_mfma_f32_16x16x32_bf16 v[78:81], v[170:173], v[204:207], v[78:81]
	v_mfma_f32_16x16x32_bf16 v[74:77], v[178:181], v[204:207], v[74:77]
	v_mfma_f32_16x16x32_bf16 v[70:73], v[170:173], v[212:215], v[70:73]
	v_mfma_f32_16x16x32_bf16 v[66:69], v[178:181], v[212:215], v[66:69]
	s_barrier
	s_mov_b32 m0, s35
	v_lshl_add_u64 v[216:217], s[10:11], 0, v[134:135]
	s_add_u32 s46, s10, 0x20000
	ds_read_b128 v[182:185], v146 offset:16384
	ds_read_b128 v[186:189], v146 offset:17408
	ds_read_b128 v[192:195], v146 offset:18432
	ds_read_b128 v[196:199], v146 offset:19456
	ds_read_b128 v[200:203], v146 offset:20480
	ds_read_b128 v[204:207], v146 offset:21504
	ds_read_b128 v[208:211], v146 offset:22528
	ds_read_b128 v[212:215], v146 offset:23552
	global_load_lds_dwordx4 v[216:217], off
	v_lshl_add_u64 v[218:219], s[10:11], 0, v[130:131]
	s_mov_b32 m0, s38
	s_addc_u32 s47, s11, 0
	global_load_lds_dwordx4 v[218:219], off
	v_lshl_add_u64 v[220:221], s[46:47], 0, v[134:135]
	s_mov_b32 m0, s39
	v_lshl_add_u64 v[222:223], s[14:15], 0, v[132:133]
	global_load_lds_dwordx4 v[220:221], off
	v_lshl_add_u64 v[220:221], s[46:47], 0, v[130:131]
	s_mov_b32 m0, s40
	s_nop 0
	global_load_lds_dwordx4 v[220:221], off
	v_lshl_add_u64 v[220:221], s[14:15], 0, v[136:137]
	s_mov_b32 m0, s22
	s_nop 0
	global_load_lds_dwordx4 v[220:221], off
	s_mov_b32 m0, s23
	s_nop 0
	global_load_lds_dwordx4 v[222:223], off
	s_waitcnt vmcnt(8)
	s_waitcnt lgkmcnt(0)
	s_barrier
; #define PG8_STAGE(bufoff, gbase, voff) do { _Pragma("unroll") for (int _i = 0; _i < 2; ++_i) \
;         __builtin_amdgcn_global_load_lds((const unsigned*)((const char*)(gbase) + (voff)[_i]), (PG8_LAS unsigned*)(lds + (bufoff) + ldsw + _i * 8192), 16, 0, 0); } while (0)
; #define PG8_LDA(dst, b, h) do { _Pragma("unroll") for (int m = 0; m < 4; ++m) _Pragma("unroll") for (int k = 0; k < 2; ++k) dst[m][k] = *(const PG8_LAS bf16x8*)(lds + PG8_SA(b, h) + aoff + m * 2048 + k * 1024); } while (0)
; #define PG8_LDB(dst, b, h) do { _Pragma("unroll") for (int n = 0; n < 2; ++n) _Pragma("unroll") for (int k = 0; k < 2; ++k) dst[n][k] = *(const PG8_LAS bf16x8*)(lds + PG8_SB(b, h) + boff + n * 2048 + k * 1024); } while (0)
; #define PG8_MMA(ai, bj, At, Bt) do { __builtin_amdgcn_s_setprio(1); _Pragma("unroll") for (int m = 0; m < 4; ++m) _Pragma("unroll") for (int n = 0; n < 2; ++n) _Pragma("unroll") for (int k = 0; k < 2; ++k) \
;         acc[ai][bj][m][n] = __builtin_amdgcn_mfma_f32_16x16x32_bf16(Bt[n][k], At[m][k], acc[ai][bj][m][n], 0, 0, 0); __builtin_amdgcn_s_setprio(0); } while (0)
; #define PG8_WAIT_V(n) asm volatile("s_waitcnt vmcnt(" #n ")" ::: "memory")
; #define PG8_WAIT_L(n) asm volatile("s_waitcnt lgkmcnt(" #n ")" ::: "memory")
; #define PG8_BAR __builtin_amdgcn_s_barrier()
; #define PG8_SCHED __builtin_amdgcn_sched_barrier(0)
; template <class Epi, class Sched, bool ALIGN_EPI = false, bool SP2 = false>
; __device__ __forceinline__ void gemm_phase(PG8_LAS unsigned char* lds, const Gemm g, const Sched& S, const Epi& E) {
;     ...
;             PG8_WAIT_V(8); PG8_WAIT_L(0); PG8_BAR; PG8_MMA(1, 0, At, B0); PG8_MMA(1, 1, At, B1); PG8_BAR; PG8_SCHED;
;             PG8_LDB(B0, 1, 0); PG8_LDB(B1, 1, 1); PG8_SCHED; PG8_LDA(At, 1, 0); PG8_STAGE(PG8_SA(0, 1), a2 + hstep, voffA);
;             PG8_WAIT_V(8); PG8_WAIT_L(0); PG8_BAR; PG8_MMA(0, 0, At, B0); PG8_MMA(0, 1, At, B1); PG8_BAR; PG8_SCHED;
	s_waitcnt lgkmcnt(0)
	v_mfma_f32_16x16x32_bf16 v[62:65], v[150:153], v[182:185], v[62:65]
	v_mfma_f32_16x16x32_bf16 v[58:61], v[158:161], v[182:185], v[58:61]
	v_mfma_f32_16x16x32_bf16 v[54:57], v[150:153], v[192:195], v[54:57]
	v_mfma_f32_16x16x32_bf16 v[50:53], v[158:161], v[192:195], v[50:53]
	v_mfma_f32_16x16x32_bf16 v[38:41], v[150:153], v[200:203], v[38:41]
	v_mfma_f32_16x16x32_bf16 v[34:37], v[158:161], v[200:203], v[34:37]
	v_mfma_f32_16x16x32_bf16 v[22:25], v[150:153], v[208:211], v[22:25]
	v_mfma_f32_16x16x32_bf16 v[18:21], v[158:161], v[208:211], v[18:21]
	v_mfma_f32_16x16x32_bf16 v[62:65], v[154:157], v[186:189], v[62:65]
	v_mfma_f32_16x16x32_bf16 v[58:61], v[162:165], v[186:189], v[58:61]
	v_mfma_f32_16x16x32_bf16 v[54:57], v[154:157], v[196:199], v[54:57]
	v_mfma_f32_16x16x32_bf16 v[50:53], v[162:165], v[196:199], v[50:53]
	v_mfma_f32_16x16x32_bf16 v[38:41], v[154:157], v[204:207], v[38:41]
	v_mfma_f32_16x16x32_bf16 v[34:37], v[162:165], v[204:207], v[34:37]
	v_mfma_f32_16x16x32_bf16 v[22:25], v[154:157], v[212:215], v[22:25]
	v_mfma_f32_16x16x32_bf16 v[18:21], v[162:165], v[212:215], v[18:21]
	v_mfma_f32_16x16x32_bf16 v[46:49], v[166:169], v[182:185], v[46:49]
	v_mfma_f32_16x16x32_bf16 v[42:45], v[174:177], v[182:185], v[42:45]
	v_mfma_f32_16x16x32_bf16 v[30:33], v[166:169], v[192:195], v[30:33]
	v_mfma_f32_16x16x32_bf16 v[26:29], v[174:177], v[192:195], v[26:29]
	v_mfma_f32_16x16x32_bf16 v[14:17], v[166:169], v[200:203], v[14:17]
	v_mfma_f32_16x16x32_bf16 v[10:13], v[174:177], v[200:203], v[10:13]
	v_mfma_f32_16x16x32_bf16 v[6:9], v[166:169], v[208:211], v[6:9]
	v_mfma_f32_16x16x32_bf16 v[2:5], v[174:177], v[208:211], v[2:5]
	v_mfma_f32_16x16x32_bf16 v[46:49], v[170:173], v[186:189], v[46:49]
	v_mfma_f32_16x16x32_bf16 v[42:45], v[178:181], v[186:189], v[42:45]
	v_mfma_f32_16x16x32_bf16 v[30:33], v[170:173], v[196:199], v[30:33]
	v_mfma_f32_16x16x32_bf16 v[26:29], v[178:181], v[196:199], v[26:29]
	v_mfma_f32_16x16x32_bf16 v[14:17], v[170:173], v[204:207], v[14:17]
	v_mfma_f32_16x16x32_bf16 v[10:13], v[178:181], v[204:207], v[10:13]
	v_mfma_f32_16x16x32_bf16 v[6:9], v[170:173], v[212:215], v[6:9]
	v_mfma_f32_16x16x32_bf16 v[2:5], v[178:181], v[212:215], v[2:5]
	s_barrier
	ds_read_b128 v[150:153], v147
	ds_read_b128 v[154:157], v147 offset:1024
	ds_read_b128 v[158:161], v147 offset:2048
	ds_read_b128 v[162:165], v147 offset:3072
	ds_read_b128 v[166:169], v148
	ds_read_b128 v[170:173], v148 offset:1024
	ds_read_b128 v[174:177], v148 offset:2048
	ds_read_b128 v[178:181], v148 offset:3072
	s_add_u32 s14, s14, 0x20000
	s_addc_u32 s15, s15, 0
	s_mov_b32 m0, s24
	v_lshl_add_u64 v[224:225], s[14:15], 0, v[136:137]
	ds_read_b128 v[182:185], v146 offset:32768
	ds_read_b128 v[186:189], v146 offset:33792
	ds_read_b128 v[192:195], v146 offset:34816
	ds_read_b128 v[196:199], v146 offset:35840
	ds_read_b128 v[200:203], v146 offset:36864
	ds_read_b128 v[204:207], v146 offset:37888
	ds_read_b128 v[208:211], v146 offset:38912
	ds_read_b128 v[212:215], v146 offset:39936
	global_load_lds_dwordx4 v[224:225], off
	v_lshl_add_u64 v[224:225], s[14:15], 0, v[132:133]
	s_mov_b32 m0, s25
	s_nop 0
	global_load_lds_dwordx4 v[224:225], off
	s_waitcnt vmcnt(8)
	s_waitcnt lgkmcnt(0)
	s_barrier
	s_waitcnt lgkmcnt(0)
	v_mfma_f32_16x16x32_bf16 v[126:129], v[150:153], v[182:185], v[126:129]
	v_mfma_f32_16x16x32_bf16 v[122:125], v[158:161], v[182:185], v[122:125]
	v_mfma_f32_16x16x32_bf16 v[118:121], v[150:153], v[192:195], v[118:121]
	v_mfma_f32_16x16x32_bf16 v[114:117], v[158:161], v[192:195], v[114:117]
	v_mfma_f32_16x16x32_bf16 v[102:105], v[150:153], v[200:203], v[102:105]
	v_mfma_f32_16x16x32_bf16 v[98:101], v[158:161], v[200:203], v[98:101]
	v_mfma_f32_16x16x32_bf16 v[86:89], v[150:153], v[208:211], v[86:89]
	v_mfma_f32_16x16x32_bf16 v[82:85], v[158:161], v[208:211], v[82:85]
	v_mfma_f32_16x16x32_bf16 v[126:129], v[154:157], v[186:189], v[126:129]
	v_mfma_f32_16x16x32_bf16 v[122:125], v[162:165], v[186:189], v[122:125]
	v_mfma_f32_16x16x32_bf16 v[118:121], v[154:157], v[196:199], v[118:121]
	v_mfma_f32_16x16x32_bf16 v[114:117], v[162:165], v[196:199], v[114:117]
	v_mfma_f32_16x16x32_bf16 v[102:105], v[154:157], v[204:207], v[102:105]
	v_mfma_f32_16x16x32_bf16 v[98:101], v[162:165], v[204:207], v[98:101]
	v_mfma_f32_16x16x32_bf16 v[86:89], v[154:157], v[212:215], v[86:89]
	v_mfma_f32_16x16x32_bf16 v[82:85], v[162:165], v[212:215], v[82:85]
	v_mfma_f32_16x16x32_bf16 v[110:113], v[166:169], v[182:185], v[110:113]
	v_mfma_f32_16x16x32_bf16 v[106:109], v[174:177], v[182:185], v[106:109]
	v_mfma_f32_16x16x32_bf16 v[94:97], v[166:169], v[192:195], v[94:97]
	v_mfma_f32_16x16x32_bf16 v[90:93], v[174:177], v[192:195], v[90:93]
	v_mfma_f32_16x16x32_bf16 v[78:81], v[166:169], v[200:203], v[78:81]
	v_mfma_f32_16x16x32_bf16 v[74:77], v[174:177], v[200:203], v[74:77]
	v_mfma_f32_16x16x32_bf16 v[70:73], v[166:169], v[208:211], v[70:73]
	v_mfma_f32_16x16x32_bf16 v[66:69], v[174:177], v[208:211], v[66:69]
	v_mfma_f32_16x16x32_bf16 v[110:113], v[170:173], v[186:189], v[110:113]
	v_mfma_f32_16x16x32_bf16 v[106:109], v[178:181], v[186:189], v[106:109]
	v_mfma_f32_16x16x32_bf16 v[94:97], v[170:173], v[196:199], v[94:97]
	v_mfma_f32_16x16x32_bf16 v[90:93], v[178:181], v[196:199], v[90:93]
	v_mfma_f32_16x16x32_bf16 v[78:81], v[170:173], v[204:207], v[78:81]
	v_mfma_f32_16x16x32_bf16 v[74:77], v[178:181], v[204:207], v[74:77]
	v_mfma_f32_16x16x32_bf16 v[70:73], v[170:173], v[212:215], v[70:73]
	v_mfma_f32_16x16x32_bf16 v[66:69], v[178:181], v[212:215], v[66:69]
	s_barrier
; #define PG8_STAGE(bufoff, gbase, voff) do { _Pragma("unroll") for (int _i = 0; _i < 2; ++_i) \
;         __builtin_amdgcn_global_load_lds((const unsigned*)((const char*)(gbase) + (voff)[_i]), (PG8_LAS unsigned*)(lds + (bufoff) + ldsw + _i * 8192), 16, 0, 0); } while (0)
; #define PG8_STAGEB(bufoff, gbase, voff) do { _Pragma("unroll") for (int _i = 0; _i < 2; ++_i) \
;         __builtin_amdgcn_global_load_lds((const unsigned*)((const char*)(gbase) + (voff)[_i]), (PG8_LAS unsigned*)(lds + (bufoff) + ldsw + _i * 8192), 16, 0, PG8_BAUX); } while (0)
; #define PG8_LDA(dst, b, h) do { _Pragma("unroll") for (int m = 0; m < 4; ++m) _Pragma("unroll") for (int k = 0; k < 2; ++k) dst[m][k] = *(const PG8_LAS bf16x8*)(lds + PG8_SA(b, h) + aoff + m * 2048 + k * 1024); } while (0)
; #define PG8_MMA(ai, bj, At, Bt) do { __builtin_amdgcn_s_setprio(1); _Pragma("unroll") for (int m = 0; m < 4; ++m) _Pragma("unroll") for (int n = 0; n < 2; ++n) _Pragma("unroll") for (int k = 0; k < 2; ++k) \
;         acc[ai][bj][m][n] = __builtin_amdgcn_mfma_f32_16x16x32_bf16(Bt[n][k], At[m][k], acc[ai][bj][m][n], 0, 0, 0); __builtin_amdgcn_s_setprio(0); } while (0)
; #define PG8_WAIT_V(n) asm volatile("s_waitcnt vmcnt(" #n ")" ::: "memory")
; #define PG8_WAIT_L(n) asm volatile("s_waitcnt lgkmcnt(" #n ")" ::: "memory")
; #define PG8_BAR __builtin_amdgcn_s_barrier()
; #define PG8_SCHED __builtin_amdgcn_sched_barrier(0)
; template <class Epi, class Sched, bool ALIGN_EPI = false, bool SP2 = false>
; __device__ __forceinline__ void gemm_phase(PG8_LAS unsigned char* lds, const Gemm g, const Sched& S, const Epi& E) {
;     ...
;             PG8_LDA(At, 1, 1); PG8_STAGEB(PG8_SB(1, 0), b3, voffB); PG8_STAGEB(PG8_SB(1, 1), b3 + hstep, voffB); PG8_STAGE(PG8_SA(1, 0), a3, voffA);
;             PG8_WAIT_V(8); PG8_WAIT_L(0); PG8_BAR; PG8_MMA(1, 0, At, B0); PG8_MMA(1, 1, At, B1); PG8_BAR; PG8_SCHED;
	s_mov_b32 m0, s41
	v_lshl_add_u64 v[216:217], v[216:217], 0, s[4:5]
	s_add_u32 s10, s10, 0x20080
	ds_read_b128 v[182:185], v146 offset:49152
	ds_read_b128 v[186:189], v146 offset:50176
	ds_read_b128 v[192:195], v146 offset:51200
	ds_read_b128 v[196:199], v146 offset:52224
	ds_read_b128 v[200:203], v146 offset:53248
	ds_read_b128 v[204:207], v146 offset:54272
	ds_read_b128 v[208:211], v146 offset:55296
	ds_read_b128 v[212:215], v146 offset:56320
	global_load_lds_dwordx4 v[216:217], off
	v_lshl_add_u64 v[216:217], v[218:219], 0, s[4:5]
	s_mov_b32 m0, s42
	s_addc_u32 s11, s11, 0
	global_load_lds_dwordx4 v[216:217], off
	v_lshl_add_u64 v[216:217], s[10:11], 0, v[134:135]
	s_mov_b32 m0, s43
	s_nop 0
	global_load_lds_dwordx4 v[216:217], off
	v_lshl_add_u64 v[216:217], s[10:11], 0, v[130:131]
	s_mov_b32 m0, s44
	s_nop 0
	global_load_lds_dwordx4 v[216:217], off
	v_lshl_add_u64 v[216:217], v[220:221], 0, s[4:5]
	s_mov_b32 m0, s27
	s_nop 0
	global_load_lds_dwordx4 v[216:217], off
	v_lshl_add_u64 v[216:217], v[222:223], 0, s[4:5]
	s_mov_b32 m0, s28
	s_nop 0
	global_load_lds_dwordx4 v[216:217], off
	s_waitcnt vmcnt(8)
	s_waitcnt lgkmcnt(0)
	s_barrier
	s_waitcnt lgkmcnt(0)
	v_mfma_f32_16x16x32_bf16 v[62:65], v[150:153], v[182:185], v[62:65]
	v_mfma_f32_16x16x32_bf16 v[58:61], v[158:161], v[182:185], v[58:61]
	v_mfma_f32_16x16x32_bf16 v[54:57], v[150:153], v[192:195], v[54:57]
	v_mfma_f32_16x16x32_bf16 v[50:53], v[158:161], v[192:195], v[50:53]
	v_mfma_f32_16x16x32_bf16 v[38:41], v[150:153], v[200:203], v[38:41]
	v_mfma_f32_16x16x32_bf16 v[34:37], v[158:161], v[200:203], v[34:37]
	v_mfma_f32_16x16x32_bf16 v[22:25], v[150:153], v[208:211], v[22:25]
	v_mfma_f32_16x16x32_bf16 v[18:21], v[158:161], v[208:211], v[18:21]
	v_mfma_f32_16x16x32_bf16 v[62:65], v[154:157], v[186:189], v[62:65]
	v_mfma_f32_16x16x32_bf16 v[58:61], v[162:165], v[186:189], v[58:61]
	v_mfma_f32_16x16x32_bf16 v[54:57], v[154:157], v[196:199], v[54:57]
	v_mfma_f32_16x16x32_bf16 v[50:53], v[162:165], v[196:199], v[50:53]
	v_mfma_f32_16x16x32_bf16 v[38:41], v[154:157], v[204:207], v[38:41]
	v_mfma_f32_16x16x32_bf16 v[34:37], v[162:165], v[204:207], v[34:37]
	v_mfma_f32_16x16x32_bf16 v[22:25], v[154:157], v[212:215], v[22:25]
	v_mfma_f32_16x16x32_bf16 v[18:21], v[162:165], v[212:215], v[18:21]
	v_mfma_f32_16x16x32_bf16 v[46:49], v[166:169], v[182:185], v[46:49]
	v_mfma_f32_16x16x32_bf16 v[42:45], v[174:177], v[182:185], v[42:45]
	v_mfma_f32_16x16x32_bf16 v[30:33], v[166:169], v[192:195], v[30:33]
	v_mfma_f32_16x16x32_bf16 v[26:29], v[174:177], v[192:195], v[26:29]
	v_mfma_f32_16x16x32_bf16 v[14:17], v[166:169], v[200:203], v[14:17]
	v_mfma_f32_16x16x32_bf16 v[10:13], v[174:177], v[200:203], v[10:13]
	v_mfma_f32_16x16x32_bf16 v[6:9], v[166:169], v[208:211], v[6:9]
	v_mfma_f32_16x16x32_bf16 v[2:5], v[174:177], v[208:211], v[2:5]
	v_mfma_f32_16x16x32_bf16 v[46:49], v[170:173], v[186:189], v[46:49]
	v_mfma_f32_16x16x32_bf16 v[42:45], v[178:181], v[186:189], v[42:45]
	v_mfma_f32_16x16x32_bf16 v[30:33], v[170:173], v[196:199], v[30:33]
	v_mfma_f32_16x16x32_bf16 v[26:29], v[178:181], v[196:199], v[26:29]
	v_mfma_f32_16x16x32_bf16 v[14:17], v[170:173], v[204:207], v[14:17]
	v_mfma_f32_16x16x32_bf16 v[10:13], v[178:181], v[204:207], v[10:13]
	v_mfma_f32_16x16x32_bf16 v[6:9], v[170:173], v[212:215], v[6:9]
	v_mfma_f32_16x16x32_bf16 v[2:5], v[178:181], v[212:215], v[2:5]
	s_barrier
	s_add_i32 s31, s31, 2
	s_add_u32 s8, s8, 0x100
	s_addc_u32 s9, s9, 0
	s_cmp_gt_u32 s31, 5
	s_cbranch_scc0 .LBB0_952
	s_cmpk_lt_u32 s20, 0x100
	s_cbranch_scc0 .LBB0_955
	s_barrier

; #define PG8_STAGE(bufoff, gbase, voff) do { _Pragma("unroll") for (int _i = 0; _i < 2; ++_i) \
;         __builtin_amdgcn_global_load_lds((const unsigned*)((const char*)(gbase) + (voff)[_i]), (PG8_LAS unsigned*)(lds + (bufoff) + ldsw + _i * 8192), 16, 0, 0); } while (0)
; #define PG8_STAGEB(bufoff, gbase, voff) do { _Pragma("unroll") for (int _i = 0; _i < 2; ++_i) \
;         __builtin_amdgcn_global_load_lds((const unsigned*)((const char*)(gbase) + (voff)[_i]), (PG8_LAS unsigned*)(lds + (bufoff) + ldsw + _i * 8192), 16, 0, PG8_BAUX); } while (0)
; #define PG8_LDA(dst, b, h) do { _Pragma("unroll") for (int m = 0; m < 4; ++m) _Pragma("unroll") for (int k = 0; k < 2; ++k) dst[m][k] = *(const PG8_LAS bf16x8*)(lds + PG8_SA(b, h) + aoff + m * 2048 + k * 1024); } while (0)
; #define PG8_LDB(dst, b, h) do { _Pragma("unroll") for (int n = 0; n < 2; ++n) _Pragma("unroll") for (int k = 0; k < 2; ++k) dst[n][k] = *(const PG8_LAS bf16x8*)(lds + PG8_SB(b, h) + boff + n * 2048 + k * 1024); } while (0)
; #define PG8_MMA(ai, bj, At, Bt) do { __builtin_amdgcn_s_setprio(1); _Pragma("unroll") for (int m = 0; m < 4; ++m) _Pragma("unroll") for (int n = 0; n < 2; ++n) _Pragma("unroll") for (int k = 0; k < 2; ++k) \
;         acc[ai][bj][m][n] = __builtin_amdgcn_mfma_f32_16x16x32_bf16(Bt[n][k], At[m][k], acc[ai][bj][m][n], 0, 0, 0); __builtin_amdgcn_s_setprio(0); } while (0)
; #define PG8_WAIT_V(n) asm volatile("s_waitcnt vmcnt(" #n ")" ::: "memory")
; #define PG8_WAIT_L(n) asm volatile("s_waitcnt lgkmcnt(" #n ")" ::: "memory")
; #define PG8_BAR __builtin_amdgcn_s_barrier()
; #define PG8_SCHED __builtin_amdgcn_sched_barrier(0)
; template <class Epi, class Sched, bool ALIGN_EPI = false, bool SP2 = false>
; __device__ __forceinline__ void gemm_phase(PG8_LAS unsigned char* lds, const Gemm g, const Sched& S, const Epi& E) {
;     ...
;             PG8_LDB(B0, 0, 0); PG8_LDB(B1, 0, 1); PG8_SCHED; PG8_LDA(At, 0, 0); PG8_STAGE(PG8_SA(1, 1), a1 + hstep, voffA);
;             PG8_WAIT_V(8); PG8_WAIT_L(0); PG8_BAR; PG8_MMA(0, 0, At, B0); PG8_MMA(0, 1, At, B1); PG8_BAR; PG8_SCHED;
;             PG8_LDA(At, 0, 1); PG8_STAGEB(PG8_SB(0, 0), b2, voffB); PG8_STAGEB(PG8_SB(0, 1), b2 + hstep, voffB); PG8_STAGE(PG8_SA(0, 0), a2, voffA);
.LBB0_1330:
	ds_read_b128 v[160:163], v155
	ds_read_b128 v[164:167], v155 offset:1024
	ds_read_b128 v[168:171], v155 offset:2048
	ds_read_b128 v[172:175], v155 offset:3072
	ds_read_b128 v[180:183], v156
	ds_read_b128 v[184:187], v156 offset:1024
	ds_read_b128 v[192:195], v156 offset:2048
	ds_read_b128 v[196:199], v156 offset:3072
	s_add_u32 s30, s28, 0xfff80080
	s_addc_u32 s31, s29, -1
	s_cmp_eq_u32 s55, 28
	s_cselect_b32 s35, s19, s31
	s_cselect_b32 s34, s25, s30
	s_cselect_b32 s31, s17, s54
	s_cselect_b32 s30, s52, s53
	v_lshl_add_u64 v[148:149], s[28:29], 0, v[140:141]
	s_add_i32 m0, s27, 0xc000
	ds_read_b128 v[200:203], v157
	ds_read_b128 v[204:207], v157 offset:1024
	ds_read_b128 v[208:211], v157 offset:2048
	ds_read_b128 v[212:215], v157 offset:3072
	ds_read_b128 v[216:219], v157 offset:4096
	ds_read_b128 v[220:223], v157 offset:5120
	ds_read_b128 v[224:227], v157 offset:6144
	ds_read_b128 v[228:231], v157 offset:7168
	global_load_lds_dwordx4 v[148:149], off
	v_lshl_add_u64 v[148:149], s[28:29], 0, v[142:143]
	s_add_i32 m0, s27, 0xe000
	s_nop 0
	global_load_lds_dwordx4 v[148:149], off
	s_waitcnt vmcnt(8)
	s_waitcnt lgkmcnt(0)
	s_barrier
	s_waitcnt lgkmcnt(0)
	v_mfma_f32_16x16x32_bf16 v[126:129], v[160:163], v[200:203], v[126:129]
	v_mfma_f32_16x16x32_bf16 v[122:125], v[168:171], v[200:203], v[122:125]
	v_mfma_f32_16x16x32_bf16 v[110:113], v[160:163], v[208:211], v[110:113]
	v_mfma_f32_16x16x32_bf16 v[106:109], v[168:171], v[208:211], v[106:109]
	v_mfma_f32_16x16x32_bf16 v[94:97], v[160:163], v[216:219], v[94:97]
	v_mfma_f32_16x16x32_bf16 v[90:93], v[168:171], v[216:219], v[90:93]
	v_mfma_f32_16x16x32_bf16 v[78:81], v[160:163], v[224:227], v[78:81]
	v_mfma_f32_16x16x32_bf16 v[74:77], v[168:171], v[224:227], v[74:77]
	v_mfma_f32_16x16x32_bf16 v[126:129], v[164:167], v[204:207], v[126:129]
	v_mfma_f32_16x16x32_bf16 v[122:125], v[172:175], v[204:207], v[122:125]
	v_mfma_f32_16x16x32_bf16 v[110:113], v[164:167], v[212:215], v[110:113]
	v_mfma_f32_16x16x32_bf16 v[106:109], v[172:175], v[212:215], v[106:109]
	v_mfma_f32_16x16x32_bf16 v[94:97], v[164:167], v[220:223], v[94:97]
	v_mfma_f32_16x16x32_bf16 v[90:93], v[172:175], v[220:223], v[90:93]
	v_mfma_f32_16x16x32_bf16 v[78:81], v[164:167], v[228:231], v[78:81]
	v_mfma_f32_16x16x32_bf16 v[74:77], v[172:175], v[228:231], v[74:77]
	v_mfma_f32_16x16x32_bf16 v[118:121], v[180:183], v[200:203], v[118:121]
	v_mfma_f32_16x16x32_bf16 v[114:117], v[192:195], v[200:203], v[114:117]
	v_mfma_f32_16x16x32_bf16 v[102:105], v[180:183], v[208:211], v[102:105]
	v_mfma_f32_16x16x32_bf16 v[98:101], v[192:195], v[208:211], v[98:101]
	v_mfma_f32_16x16x32_bf16 v[86:89], v[180:183], v[216:219], v[86:89]
	v_mfma_f32_16x16x32_bf16 v[82:85], v[192:195], v[216:219], v[82:85]
	v_mfma_f32_16x16x32_bf16 v[70:73], v[180:183], v[224:227], v[70:73]
	v_mfma_f32_16x16x32_bf16 v[66:69], v[192:195], v[224:227], v[66:69]
	v_mfma_f32_16x16x32_bf16 v[118:121], v[184:187], v[204:207], v[118:121]
	v_mfma_f32_16x16x32_bf16 v[114:117], v[196:199], v[204:207], v[114:117]
	v_mfma_f32_16x16x32_bf16 v[102:105], v[184:187], v[212:215], v[102:105]
	v_mfma_f32_16x16x32_bf16 v[98:101], v[196:199], v[212:215], v[98:101]
	v_mfma_f32_16x16x32_bf16 v[86:89], v[184:187], v[220:223], v[86:89]
	v_mfma_f32_16x16x32_bf16 v[82:85], v[196:199], v[220:223], v[82:85]
	v_mfma_f32_16x16x32_bf16 v[70:73], v[184:187], v[228:231], v[70:73]
	v_mfma_f32_16x16x32_bf16 v[66:69], v[196:199], v[228:231], v[66:69]
	s_barrier
	s_add_i32 s56, s50, s33
	v_lshl_add_u64 v[148:149], s[30:31], 0, v[132:133]
	s_mov_b32 m0, s56
	ds_read_b128 v[200:203], v157 offset:16384
	ds_read_b128 v[204:207], v157 offset:17408
	ds_read_b128 v[208:211], v157 offset:18432
	ds_read_b128 v[212:215], v157 offset:19456
	ds_read_b128 v[216:219], v157 offset:20480
	ds_read_b128 v[220:223], v157 offset:21504
	ds_read_b128 v[224:227], v157 offset:22528
	ds_read_b128 v[228:231], v157 offset:23552
	global_load_lds_dwordx4 v[148:149], off
	s_add_i32 m0, s56, 0x2000
	s_add_u32 s56, s30, 0x80000
	v_lshl_add_u64 v[176:177], s[30:31], 0, v[136:137]
	s_addc_u32 s57, s31, 0
	s_add_i32 s58, s51, s33
	global_load_lds_dwordx4 v[176:177], off
	v_lshl_add_u64 v[188:189], s[56:57], 0, v[132:133]
	s_mov_b32 m0, s58
	v_lshl_add_u64 v[232:233], s[34:35], 0, v[134:135]
	global_load_lds_dwordx4 v[188:189], off
	v_lshl_add_u64 v[188:189], s[56:57], 0, v[136:137]
	s_add_i32 m0, s58, 0x2000
	s_nop 0
	global_load_lds_dwordx4 v[188:189], off
	v_lshl_add_u64 v[188:189], s[34:35], 0, v[130:131]
	s_mov_b32 m0, s27
	s_nop 0
	global_load_lds_dwordx4 v[188:189], off
	s_mov_b32 m0, s42
	s_nop 0
	global_load_lds_dwordx4 v[232:233], off
	s_waitcnt vmcnt(8)
	s_waitcnt lgkmcnt(0)
	s_barrier
; #define PG8_STAGE(bufoff, gbase, voff) do { _Pragma("unroll") for (int _i = 0; _i < 2; ++_i) \
;         __builtin_amdgcn_global_load_lds((const unsigned*)((const char*)(gbase) + (voff)[_i]), (PG8_LAS unsigned*)(lds + (bufoff) + ldsw + _i * 8192), 16, 0, 0); } while (0)
; #define PG8_LDA(dst, b, h) do { _Pragma("unroll") for (int m = 0; m < 4; ++m) _Pragma("unroll") for (int k = 0; k < 2; ++k) dst[m][k] = *(const PG8_LAS bf16x8*)(lds + PG8_SA(b, h) + aoff + m * 2048 + k * 1024); } while (0)
; #define PG8_LDB(dst, b, h) do { _Pragma("unroll") for (int n = 0; n < 2; ++n) _Pragma("unroll") for (int k = 0; k < 2; ++k) dst[n][k] = *(const PG8_LAS bf16x8*)(lds + PG8_SB(b, h) + boff + n * 2048 + k * 1024); } while (0)
; #define PG8_MMA(ai, bj, At, Bt) do { __builtin_amdgcn_s_setprio(1); _Pragma("unroll") for (int m = 0; m < 4; ++m) _Pragma("unroll") for (int n = 0; n < 2; ++n) _Pragma("unroll") for (int k = 0; k < 2; ++k) \
;         acc[ai][bj][m][n] = __builtin_amdgcn_mfma_f32_16x16x32_bf16(Bt[n][k], At[m][k], acc[ai][bj][m][n], 0, 0, 0); __builtin_amdgcn_s_setprio(0); } while (0)
; #define PG8_WAIT_V(n) asm volatile("s_waitcnt vmcnt(" #n ")" ::: "memory")
; #define PG8_WAIT_L(n) asm volatile("s_waitcnt lgkmcnt(" #n ")" ::: "memory")
; #define PG8_BAR __builtin_amdgcn_s_barrier()
; #define PG8_SCHED __builtin_amdgcn_sched_barrier(0)
; template <class Epi, class Sched, bool ALIGN_EPI = false, bool SP2 = false>
; __device__ __forceinline__ void gemm_phase(PG8_LAS unsigned char* lds, const Gemm g, const Sched& S, const Epi& E) {
;     ...
;             PG8_WAIT_V(8); PG8_WAIT_L(0); PG8_BAR; PG8_MMA(1, 0, At, B0); PG8_MMA(1, 1, At, B1); PG8_BAR; PG8_SCHED;
;             PG8_LDB(B0, 1, 0); PG8_LDB(B1, 1, 1); PG8_SCHED; PG8_LDA(At, 1, 0); PG8_STAGE(PG8_SA(0, 1), a2 + hstep, voffA);
;             PG8_WAIT_V(8); PG8_WAIT_L(0); PG8_BAR; PG8_MMA(0, 0, At, B0); PG8_MMA(0, 1, At, B1); PG8_BAR; PG8_SCHED;
	s_waitcnt lgkmcnt(0)
	v_mfma_f32_16x16x32_bf16 v[62:65], v[160:163], v[200:203], v[62:65]
	v_mfma_f32_16x16x32_bf16 v[58:61], v[168:171], v[200:203], v[58:61]
	v_mfma_f32_16x16x32_bf16 v[46:49], v[160:163], v[208:211], v[46:49]
	v_mfma_f32_16x16x32_bf16 v[42:45], v[168:171], v[208:211], v[42:45]
	v_mfma_f32_16x16x32_bf16 v[30:33], v[160:163], v[216:219], v[30:33]
	v_mfma_f32_16x16x32_bf16 v[26:29], v[168:171], v[216:219], v[26:29]
	v_mfma_f32_16x16x32_bf16 v[14:17], v[160:163], v[224:227], v[14:17]
	v_mfma_f32_16x16x32_bf16 v[10:13], v[168:171], v[224:227], v[10:13]
	v_mfma_f32_16x16x32_bf16 v[62:65], v[164:167], v[204:207], v[62:65]
	v_mfma_f32_16x16x32_bf16 v[58:61], v[172:175], v[204:207], v[58:61]
	v_mfma_f32_16x16x32_bf16 v[46:49], v[164:167], v[212:215], v[46:49]
	v_mfma_f32_16x16x32_bf16 v[42:45], v[172:175], v[212:215], v[42:45]
	v_mfma_f32_16x16x32_bf16 v[30:33], v[164:167], v[220:223], v[30:33]
	v_mfma_f32_16x16x32_bf16 v[26:29], v[172:175], v[220:223], v[26:29]
	v_mfma_f32_16x16x32_bf16 v[14:17], v[164:167], v[228:231], v[14:17]
	v_mfma_f32_16x16x32_bf16 v[10:13], v[172:175], v[228:231], v[10:13]
	v_mfma_f32_16x16x32_bf16 v[54:57], v[180:183], v[200:203], v[54:57]
	v_mfma_f32_16x16x32_bf16 v[50:53], v[192:195], v[200:203], v[50:53]
	v_mfma_f32_16x16x32_bf16 v[38:41], v[180:183], v[208:211], v[38:41]
	v_mfma_f32_16x16x32_bf16 v[34:37], v[192:195], v[208:211], v[34:37]
	v_mfma_f32_16x16x32_bf16 v[22:25], v[180:183], v[216:219], v[22:25]
	v_mfma_f32_16x16x32_bf16 v[18:21], v[192:195], v[216:219], v[18:21]
	v_mfma_f32_16x16x32_bf16 v[6:9], v[180:183], v[224:227], v[6:9]
	v_mfma_f32_16x16x32_bf16 v[2:5], v[192:195], v[224:227], v[2:5]
	v_mfma_f32_16x16x32_bf16 v[54:57], v[184:187], v[204:207], v[54:57]
	v_mfma_f32_16x16x32_bf16 v[50:53], v[196:199], v[204:207], v[50:53]
	v_mfma_f32_16x16x32_bf16 v[38:41], v[184:187], v[212:215], v[38:41]
	v_mfma_f32_16x16x32_bf16 v[34:37], v[196:199], v[212:215], v[34:37]
	v_mfma_f32_16x16x32_bf16 v[22:25], v[184:187], v[220:223], v[22:25]
	v_mfma_f32_16x16x32_bf16 v[18:21], v[196:199], v[220:223], v[18:21]
	v_mfma_f32_16x16x32_bf16 v[6:9], v[184:187], v[228:231], v[6:9]
	v_mfma_f32_16x16x32_bf16 v[2:5], v[196:199], v[228:231], v[2:5]
	s_barrier
	s_add_i32 s56, 0, 0x18000
	v_add_u32_e32 v138, s56, v153
	s_add_i32 s57, 0, 0x1c000
	ds_read_b128 v[160:163], v138
	ds_read_b128 v[164:167], v138 offset:1024
	ds_read_b128 v[168:171], v138 offset:2048
	ds_read_b128 v[172:175], v138 offset:3072
	v_add_u32_e32 v138, s57, v153
	ds_read_b128 v[180:183], v138
	ds_read_b128 v[184:187], v138 offset:1024
	ds_read_b128 v[192:195], v138 offset:2048
	ds_read_b128 v[196:199], v138 offset:3072
	s_add_u32 s34, s34, 0x80000
	s_addc_u32 s35, s35, 0
	s_mov_b32 m0, s43
	v_lshl_add_u64 v[234:235], s[34:35], 0, v[130:131]
	ds_read_b128 v[200:203], v157 offset:32768
	ds_read_b128 v[204:207], v157 offset:33792
	ds_read_b128 v[208:211], v157 offset:34816
	ds_read_b128 v[212:215], v157 offset:35840
	ds_read_b128 v[216:219], v157 offset:36864
	ds_read_b128 v[220:223], v157 offset:37888
	ds_read_b128 v[224:227], v157 offset:38912
	ds_read_b128 v[228:231], v157 offset:39936
	global_load_lds_dwordx4 v[234:235], off
	v_lshl_add_u64 v[234:235], s[34:35], 0, v[134:135]
	s_mov_b32 m0, s44
	s_nop 0
	global_load_lds_dwordx4 v[234:235], off
	s_waitcnt vmcnt(8)
	s_waitcnt lgkmcnt(0)
	s_barrier
	s_waitcnt lgkmcnt(0)
	v_mfma_f32_16x16x32_bf16 v[126:129], v[160:163], v[200:203], v[126:129]
	v_mfma_f32_16x16x32_bf16 v[122:125], v[168:171], v[200:203], v[122:125]
	v_mfma_f32_16x16x32_bf16 v[110:113], v[160:163], v[208:211], v[110:113]
	v_mfma_f32_16x16x32_bf16 v[106:109], v[168:171], v[208:211], v[106:109]
	v_mfma_f32_16x16x32_bf16 v[94:97], v[160:163], v[216:219], v[94:97]
	v_mfma_f32_16x16x32_bf16 v[90:93], v[168:171], v[216:219], v[90:93]
	v_mfma_f32_16x16x32_bf16 v[78:81], v[160:163], v[224:227], v[78:81]
	v_mfma_f32_16x16x32_bf16 v[74:77], v[168:171], v[224:227], v[74:77]
	v_mfma_f32_16x16x32_bf16 v[126:129], v[164:167], v[204:207], v[126:129]
	v_mfma_f32_16x16x32_bf16 v[122:125], v[172:175], v[204:207], v[122:125]
	v_mfma_f32_16x16x32_bf16 v[110:113], v[164:167], v[212:215], v[110:113]
	v_mfma_f32_16x16x32_bf16 v[106:109], v[172:175], v[212:215], v[106:109]
	v_mfma_f32_16x16x32_bf16 v[94:97], v[164:167], v[220:223], v[94:97]
	v_mfma_f32_16x16x32_bf16 v[90:93], v[172:175], v[220:223], v[90:93]
	v_mfma_f32_16x16x32_bf16 v[78:81], v[164:167], v[228:231], v[78:81]
	v_mfma_f32_16x16x32_bf16 v[74:77], v[172:175], v[228:231], v[74:77]
	v_mfma_f32_16x16x32_bf16 v[118:121], v[180:183], v[200:203], v[118:121]
	v_mfma_f32_16x16x32_bf16 v[114:117], v[192:195], v[200:203], v[114:117]
	v_mfma_f32_16x16x32_bf16 v[102:105], v[180:183], v[208:211], v[102:105]
	v_mfma_f32_16x16x32_bf16 v[98:101], v[192:195], v[208:211], v[98:101]
	v_mfma_f32_16x16x32_bf16 v[86:89], v[180:183], v[216:219], v[86:89]
	v_mfma_f32_16x16x32_bf16 v[82:85], v[192:195], v[216:219], v[82:85]
	v_mfma_f32_16x16x32_bf16 v[70:73], v[180:183], v[224:227], v[70:73]
	v_mfma_f32_16x16x32_bf16 v[66:69], v[192:195], v[224:227], v[66:69]
	v_mfma_f32_16x16x32_bf16 v[118:121], v[184:187], v[204:207], v[118:121]
	v_mfma_f32_16x16x32_bf16 v[114:117], v[196:199], v[204:207], v[114:117]
	v_mfma_f32_16x16x32_bf16 v[102:105], v[184:187], v[212:215], v[102:105]
	v_mfma_f32_16x16x32_bf16 v[98:101], v[196:199], v[212:215], v[98:101]
	v_mfma_f32_16x16x32_bf16 v[86:89], v[184:187], v[220:223], v[86:89]
	v_mfma_f32_16x16x32_bf16 v[82:85], v[196:199], v[220:223], v[82:85]
	v_mfma_f32_16x16x32_bf16 v[70:73], v[184:187], v[228:231], v[70:73]
	v_mfma_f32_16x16x32_bf16 v[66:69], v[196:199], v[228:231], v[66:69]
	s_barrier
; #define PG8_STAGE(bufoff, gbase, voff) do { _Pragma("unroll") for (int _i = 0; _i < 2; ++_i) \
;         __builtin_amdgcn_global_load_lds((const unsigned*)((const char*)(gbase) + (voff)[_i]), (PG8_LAS unsigned*)(lds + (bufoff) + ldsw + _i * 8192), 16, 0, 0); } while (0)
; #define PG8_STAGEB(bufoff, gbase, voff) do { _Pragma("unroll") for (int _i = 0; _i < 2; ++_i) \
;         __builtin_amdgcn_global_load_lds((const unsigned*)((const char*)(gbase) + (voff)[_i]), (PG8_LAS unsigned*)(lds + (bufoff) + ldsw + _i * 8192), 16, 0, PG8_BAUX); } while (0)
; #define PG8_LDA(dst, b, h) do { _Pragma("unroll") for (int m = 0; m < 4; ++m) _Pragma("unroll") for (int k = 0; k < 2; ++k) dst[m][k] = *(const PG8_LAS bf16x8*)(lds + PG8_SA(b, h) + aoff + m * 2048 + k * 1024); } while (0)
; #define PG8_MMA(ai, bj, At, Bt) do { __builtin_amdgcn_s_setprio(1); _Pragma("unroll") for (int m = 0; m < 4; ++m) _Pragma("unroll") for (int n = 0; n < 2; ++n) _Pragma("unroll") for (int k = 0; k < 2; ++k) \
;         acc[ai][bj][m][n] = __builtin_amdgcn_mfma_f32_16x16x32_bf16(Bt[n][k], At[m][k], acc[ai][bj][m][n], 0, 0, 0); __builtin_amdgcn_s_setprio(0); } while (0)
; #define PG8_WAIT_V(n) asm volatile("s_waitcnt vmcnt(" #n ")" ::: "memory")
; #define PG8_WAIT_L(n) asm volatile("s_waitcnt lgkmcnt(" #n ")" ::: "memory")
; #define PG8_BAR __builtin_amdgcn_s_barrier()
; #define PG8_SCHED __builtin_amdgcn_sched_barrier(0)
; template <class Epi, class Sched, bool ALIGN_EPI = false, bool SP2 = false>
; __device__ __forceinline__ void gemm_phase(PG8_LAS unsigned char* lds, const Gemm g, const Sched& S, const Epi& E) {
;     ...
;             PG8_LDA(At, 1, 1); PG8_STAGEB(PG8_SB(1, 0), b3, voffB); PG8_STAGEB(PG8_SB(1, 1), b3 + hstep, voffB); PG8_STAGE(PG8_SA(1, 0), a3, voffA);
;             PG8_WAIT_V(8); PG8_WAIT_L(0); PG8_BAR; PG8_MMA(1, 0, At, B0); PG8_MMA(1, 1, At, B1); PG8_BAR; PG8_SCHED;
	s_add_i32 s34, s56, s33
	v_lshl_add_u64 v[148:149], v[148:149], 0, s[12:13]
	s_mov_b32 m0, s34
	ds_read_b128 v[200:203], v157 offset:49152
	ds_read_b128 v[204:207], v157 offset:50176
	ds_read_b128 v[208:211], v157 offset:51200
	ds_read_b128 v[212:215], v157 offset:52224
	ds_read_b128 v[216:219], v157 offset:53248
	ds_read_b128 v[220:223], v157 offset:54272
	ds_read_b128 v[224:227], v157 offset:55296
	ds_read_b128 v[228:231], v157 offset:56320
	global_load_lds_dwordx4 v[148:149], off
	s_add_i32 m0, s34, 0x2000
	s_add_u32 s30, s30, 0x80080
	v_lshl_add_u64 v[148:149], v[176:177], 0, s[12:13]
	s_addc_u32 s31, s31, 0
	s_add_i32 s34, s57, s33
	global_load_lds_dwordx4 v[148:149], off
	v_lshl_add_u64 v[148:149], s[30:31], 0, v[132:133]
	s_mov_b32 m0, s34
	s_nop 0
	global_load_lds_dwordx4 v[148:149], off
	v_lshl_add_u64 v[148:149], s[30:31], 0, v[136:137]
	s_add_i32 m0, s34, 0x2000
	s_nop 0
	global_load_lds_dwordx4 v[148:149], off
	v_lshl_add_u64 v[148:149], v[188:189], 0, s[12:13]
	s_mov_b32 m0, s46
	s_nop 0
	global_load_lds_dwordx4 v[148:149], off
	v_lshl_add_u64 v[148:149], v[232:233], 0, s[12:13]
	s_mov_b32 m0, s47
	s_nop 0
	global_load_lds_dwordx4 v[148:149], off
	s_waitcnt vmcnt(8)
	s_waitcnt lgkmcnt(0)
	s_barrier
	s_waitcnt lgkmcnt(0)
	v_mfma_f32_16x16x32_bf16 v[62:65], v[160:163], v[200:203], v[62:65]
	v_mfma_f32_16x16x32_bf16 v[58:61], v[168:171], v[200:203], v[58:61]
	v_mfma_f32_16x16x32_bf16 v[46:49], v[160:163], v[208:211], v[46:49]
	v_mfma_f32_16x16x32_bf16 v[42:45], v[168:171], v[208:211], v[42:45]
	v_mfma_f32_16x16x32_bf16 v[30:33], v[160:163], v[216:219], v[30:33]
	v_mfma_f32_16x16x32_bf16 v[26:29], v[168:171], v[216:219], v[26:29]
	v_mfma_f32_16x16x32_bf16 v[14:17], v[160:163], v[224:227], v[14:17]
	v_mfma_f32_16x16x32_bf16 v[10:13], v[168:171], v[224:227], v[10:13]
	v_mfma_f32_16x16x32_bf16 v[62:65], v[164:167], v[204:207], v[62:65]
	v_mfma_f32_16x16x32_bf16 v[58:61], v[172:175], v[204:207], v[58:61]
	v_mfma_f32_16x16x32_bf16 v[46:49], v[164:167], v[212:215], v[46:49]
	v_mfma_f32_16x16x32_bf16 v[42:45], v[172:175], v[212:215], v[42:45]
	v_mfma_f32_16x16x32_bf16 v[30:33], v[164:167], v[220:223], v[30:33]
	v_mfma_f32_16x16x32_bf16 v[26:29], v[172:175], v[220:223], v[26:29]
	v_mfma_f32_16x16x32_bf16 v[14:17], v[164:167], v[228:231], v[14:17]
	v_mfma_f32_16x16x32_bf16 v[10:13], v[172:175], v[228:231], v[10:13]
	v_mfma_f32_16x16x32_bf16 v[54:57], v[180:183], v[200:203], v[54:57]
	v_mfma_f32_16x16x32_bf16 v[50:53], v[192:195], v[200:203], v[50:53]
	v_mfma_f32_16x16x32_bf16 v[38:41], v[180:183], v[208:211], v[38:41]
	v_mfma_f32_16x16x32_bf16 v[34:37], v[192:195], v[208:211], v[34:37]
	v_mfma_f32_16x16x32_bf16 v[22:25], v[180:183], v[216:219], v[22:25]
	v_mfma_f32_16x16x32_bf16 v[18:21], v[192:195], v[216:219], v[18:21]
	v_mfma_f32_16x16x32_bf16 v[6:9], v[180:183], v[224:227], v[6:9]
	v_mfma_f32_16x16x32_bf16 v[2:5], v[192:195], v[224:227], v[2:5]
	v_mfma_f32_16x16x32_bf16 v[54:57], v[184:187], v[204:207], v[54:57]
	v_mfma_f32_16x16x32_bf16 v[50:53], v[196:199], v[204:207], v[50:53]
	v_mfma_f32_16x16x32_bf16 v[38:41], v[184:187], v[212:215], v[38:41]
	v_mfma_f32_16x16x32_bf16 v[34:37], v[196:199], v[212:215], v[34:37]
	v_mfma_f32_16x16x32_bf16 v[22:25], v[184:187], v[220:223], v[22:25]
	v_mfma_f32_16x16x32_bf16 v[18:21], v[196:199], v[220:223], v[18:21]
	v_mfma_f32_16x16x32_bf16 v[6:9], v[184:187], v[228:231], v[6:9]
	v_mfma_f32_16x16x32_bf16 v[2:5], v[196:199], v[228:231], v[2:5]
	s_barrier
	s_add_i32 s55, s55, 2
	s_add_u32 s28, s28, 0x100
	s_addc_u32 s29, s29, 0
	s_add_u32 s53, s53, 0x100
	s_addc_u32 s54, s54, 0
	s_cmp_gt_u32 s55, 29
	s_cbranch_scc0 .LBB0_1330
	s_and_b64 vcc, exec, s[14:15]
	s_cbranch_vccz .LBB0_1333
	s_barrier

; #define PG8_STAGE(bufoff, gbase, voff) do { _Pragma("unroll") for (int _i = 0; _i < 2; ++_i) \
;         __builtin_amdgcn_global_load_lds((const unsigned*)((const char*)(gbase) + (voff)[_i]), (PG8_LAS unsigned*)(lds + (bufoff) + ldsw + _i * 8192), 16, 0, 0); } while (0)
; #define PG8_STAGEB(bufoff, gbase, voff) do { _Pragma("unroll") for (int _i = 0; _i < 2; ++_i) \
;         __builtin_amdgcn_global_load_lds((const unsigned*)((const char*)(gbase) + (voff)[_i]), (PG8_LAS unsigned*)(lds + (bufoff) + ldsw + _i * 8192), 16, 0, PG8_BAUX); } while (0)
; #define PG8_LDA(dst, b, h) do { _Pragma("unroll") for (int m = 0; m < 4; ++m) _Pragma("unroll") for (int k = 0; k < 2; ++k) dst[m][k] = *(const PG8_LAS bf16x8*)(lds + PG8_SA(b, h) + aoff + m * 2048 + k * 1024); } while (0)
; #define PG8_LDB(dst, b, h) do { _Pragma("unroll") for (int n = 0; n < 2; ++n) _Pragma("unroll") for (int k = 0; k < 2; ++k) dst[n][k] = *(const PG8_LAS bf16x8*)(lds + PG8_SB(b, h) + boff + n * 2048 + k * 1024); } while (0)
; #define PG8_MMA(ai, bj, At, Bt) do { __builtin_amdgcn_s_setprio(1); _Pragma("unroll") for (int m = 0; m < 4; ++m) _Pragma("unroll") for (int n = 0; n < 2; ++n) _Pragma("unroll") for (int k = 0; k < 2; ++k) \
;         acc[ai][bj][m][n] = __builtin_amdgcn_mfma_f32_16x16x32_bf16(Bt[n][k], At[m][k], acc[ai][bj][m][n], 0, 0, 0); __builtin_amdgcn_s_setprio(0); } while (0)
; #define PG8_WAIT_V(n) asm volatile("s_waitcnt vmcnt(" #n ")" ::: "memory")
; #define PG8_WAIT_L(n) asm volatile("s_waitcnt lgkmcnt(" #n ")" ::: "memory")
; #define PG8_BAR __builtin_amdgcn_s_barrier()
; #define PG8_SCHED __builtin_amdgcn_sched_barrier(0)
; template <class Epi, class Sched, bool ALIGN_EPI = false, bool SP2 = false>
; __device__ __forceinline__ void gemm_phase(PG8_LAS unsigned char* lds, const Gemm g, const Sched& S, const Epi& E) {
;     ...
;             PG8_LDB(B0, 0, 0); PG8_LDB(B1, 0, 1); PG8_SCHED; PG8_LDA(At, 0, 0); PG8_STAGE(PG8_SA(1, 1), a1 + hstep, voffA);
;             PG8_WAIT_V(8); PG8_WAIT_L(0); PG8_BAR; PG8_MMA(0, 0, At, B0); PG8_MMA(0, 1, At, B1); PG8_BAR; PG8_SCHED;
;             PG8_LDA(At, 0, 1); PG8_STAGEB(PG8_SB(0, 0), b2, voffB); PG8_STAGEB(PG8_SB(0, 1), b2 + hstep, voffB); PG8_STAGE(PG8_SA(0, 0), a2, voffA);
.LBB0_1437:
	ds_read_b128 v[156:159], v152
	ds_read_b128 v[160:163], v152 offset:1024
	ds_read_b128 v[164:167], v152 offset:2048
	ds_read_b128 v[168:171], v152 offset:3072
	ds_read_b128 v[172:175], v153
	ds_read_b128 v[180:183], v153 offset:1024
	ds_read_b128 v[184:187], v153 offset:2048
	ds_read_b128 v[192:195], v153 offset:3072
	s_add_u32 s24, s22, 0xfff80080
	s_addc_u32 s25, s23, -1
	s_cmp_eq_u32 s49, 28
	s_cselect_b32 s27, s15, s25
	s_cselect_b32 s26, s45, s24
	s_cselect_b32 s25, s13, s48
	s_cselect_b32 s24, s46, s47
	v_lshl_add_u64 v[176:177], s[22:23], 0, v[138:139]
	s_add_i32 m0, s17, 0xc000
	ds_read_b128 v[196:199], v154
	ds_read_b128 v[200:203], v154 offset:1024
	ds_read_b128 v[204:207], v154 offset:2048
	ds_read_b128 v[208:211], v154 offset:3072
	ds_read_b128 v[212:215], v154 offset:4096
	ds_read_b128 v[216:219], v154 offset:5120
	ds_read_b128 v[220:223], v154 offset:6144
	ds_read_b128 v[224:227], v154 offset:7168
	global_load_lds_dwordx4 v[176:177], off
	v_lshl_add_u64 v[176:177], s[22:23], 0, v[140:141]
	s_add_i32 m0, s17, 0xe000
	s_nop 0
	global_load_lds_dwordx4 v[176:177], off
	s_waitcnt vmcnt(8)
	s_waitcnt lgkmcnt(0)
	s_barrier
	s_waitcnt lgkmcnt(0)
	v_mfma_f32_16x16x32_bf16 v[126:129], v[156:159], v[196:199], v[126:129]
	v_mfma_f32_16x16x32_bf16 v[122:125], v[164:167], v[196:199], v[122:125]
	v_mfma_f32_16x16x32_bf16 v[118:121], v[156:159], v[204:207], v[118:121]
	v_mfma_f32_16x16x32_bf16 v[110:113], v[164:167], v[204:207], v[110:113]
	v_mfma_f32_16x16x32_bf16 v[98:101], v[156:159], v[212:215], v[98:101]
	v_mfma_f32_16x16x32_bf16 v[90:93], v[164:167], v[212:215], v[90:93]
	v_mfma_f32_16x16x32_bf16 v[86:89], v[156:159], v[220:223], v[86:89]
	v_mfma_f32_16x16x32_bf16 v[78:81], v[164:167], v[220:223], v[78:81]
	v_mfma_f32_16x16x32_bf16 v[126:129], v[160:163], v[200:203], v[126:129]
	v_mfma_f32_16x16x32_bf16 v[122:125], v[168:171], v[200:203], v[122:125]
	v_mfma_f32_16x16x32_bf16 v[118:121], v[160:163], v[208:211], v[118:121]
	v_mfma_f32_16x16x32_bf16 v[110:113], v[168:171], v[208:211], v[110:113]
	v_mfma_f32_16x16x32_bf16 v[98:101], v[160:163], v[216:219], v[98:101]
	v_mfma_f32_16x16x32_bf16 v[90:93], v[168:171], v[216:219], v[90:93]
	v_mfma_f32_16x16x32_bf16 v[86:89], v[160:163], v[224:227], v[86:89]
	v_mfma_f32_16x16x32_bf16 v[78:81], v[168:171], v[224:227], v[78:81]
	v_mfma_f32_16x16x32_bf16 v[114:117], v[172:175], v[196:199], v[114:117]
	v_mfma_f32_16x16x32_bf16 v[106:109], v[184:187], v[196:199], v[106:109]
	v_mfma_f32_16x16x32_bf16 v[102:105], v[172:175], v[204:207], v[102:105]
	v_mfma_f32_16x16x32_bf16 v[94:97], v[184:187], v[204:207], v[94:97]
	v_mfma_f32_16x16x32_bf16 v[82:85], v[172:175], v[212:215], v[82:85]
	v_mfma_f32_16x16x32_bf16 v[74:77], v[184:187], v[212:215], v[74:77]
	v_mfma_f32_16x16x32_bf16 v[70:73], v[172:175], v[220:223], v[70:73]
	v_mfma_f32_16x16x32_bf16 v[66:69], v[184:187], v[220:223], v[66:69]
	v_mfma_f32_16x16x32_bf16 v[114:117], v[180:183], v[200:203], v[114:117]
	v_mfma_f32_16x16x32_bf16 v[106:109], v[192:195], v[200:203], v[106:109]
	v_mfma_f32_16x16x32_bf16 v[102:105], v[180:183], v[208:211], v[102:105]
	v_mfma_f32_16x16x32_bf16 v[94:97], v[192:195], v[208:211], v[94:97]
	v_mfma_f32_16x16x32_bf16 v[82:85], v[180:183], v[216:219], v[82:85]
	v_mfma_f32_16x16x32_bf16 v[74:77], v[192:195], v[216:219], v[74:77]
	v_mfma_f32_16x16x32_bf16 v[70:73], v[180:183], v[224:227], v[70:73]
	v_mfma_f32_16x16x32_bf16 v[66:69], v[192:195], v[224:227], v[66:69]
	s_barrier
	s_add_i32 s50, s42, s29
	v_lshl_add_u64 v[176:177], s[24:25], 0, v[132:133]
	s_mov_b32 m0, s50
	ds_read_b128 v[196:199], v154 offset:16384
	ds_read_b128 v[200:203], v154 offset:17408
	ds_read_b128 v[204:207], v154 offset:18432
	ds_read_b128 v[208:211], v154 offset:19456
	ds_read_b128 v[212:215], v154 offset:20480
	ds_read_b128 v[216:219], v154 offset:21504
	ds_read_b128 v[220:223], v154 offset:22528
	ds_read_b128 v[224:227], v154 offset:23552
	global_load_lds_dwordx4 v[176:177], off
	s_add_i32 m0, s50, 0x2000
	s_add_u32 s50, s24, 0x80000
	v_lshl_add_u64 v[188:189], s[24:25], 0, v[136:137]
	s_addc_u32 s51, s25, 0
	s_add_i32 s52, s43, s29
	global_load_lds_dwordx4 v[188:189], off
	v_lshl_add_u64 v[228:229], s[50:51], 0, v[132:133]
	s_mov_b32 m0, s52
	v_lshl_add_u64 v[230:231], s[26:27], 0, v[134:135]
	global_load_lds_dwordx4 v[228:229], off
	v_lshl_add_u64 v[228:229], s[50:51], 0, v[136:137]
	s_add_i32 m0, s52, 0x2000
	s_nop 0
	global_load_lds_dwordx4 v[228:229], off
	v_lshl_add_u64 v[228:229], s[26:27], 0, v[130:131]
	s_mov_b32 m0, s17
	s_nop 0
	global_load_lds_dwordx4 v[228:229], off
	s_mov_b32 m0, s33
	s_nop 0
	global_load_lds_dwordx4 v[230:231], off
	s_waitcnt vmcnt(8)
	s_waitcnt lgkmcnt(0)
	s_barrier
; #define PG8_STAGE(bufoff, gbase, voff) do { _Pragma("unroll") for (int _i = 0; _i < 2; ++_i) \
;         __builtin_amdgcn_global_load_lds((const unsigned*)((const char*)(gbase) + (voff)[_i]), (PG8_LAS unsigned*)(lds + (bufoff) + ldsw + _i * 8192), 16, 0, 0); } while (0)
; #define PG8_LDA(dst, b, h) do { _Pragma("unroll") for (int m = 0; m < 4; ++m) _Pragma("unroll") for (int k = 0; k < 2; ++k) dst[m][k] = *(const PG8_LAS bf16x8*)(lds + PG8_SA(b, h) + aoff + m * 2048 + k * 1024); } while (0)
; #define PG8_LDB(dst, b, h) do { _Pragma("unroll") for (int n = 0; n < 2; ++n) _Pragma("unroll") for (int k = 0; k < 2; ++k) dst[n][k] = *(const PG8_LAS bf16x8*)(lds + PG8_SB(b, h) + boff + n * 2048 + k * 1024); } while (0)
; #define PG8_MMA(ai, bj, At, Bt) do { __builtin_amdgcn_s_setprio(1); _Pragma("unroll") for (int m = 0; m < 4; ++m) _Pragma("unroll") for (int n = 0; n < 2; ++n) _Pragma("unroll") for (int k = 0; k < 2; ++k) \
;         acc[ai][bj][m][n] = __builtin_amdgcn_mfma_f32_16x16x32_bf16(Bt[n][k], At[m][k], acc[ai][bj][m][n], 0, 0, 0); __builtin_amdgcn_s_setprio(0); } while (0)
; #define PG8_WAIT_V(n) asm volatile("s_waitcnt vmcnt(" #n ")" ::: "memory")
; #define PG8_WAIT_L(n) asm volatile("s_waitcnt lgkmcnt(" #n ")" ::: "memory")
; #define PG8_BAR __builtin_amdgcn_s_barrier()
; #define PG8_SCHED __builtin_amdgcn_sched_barrier(0)
; template <class Epi, class Sched, bool ALIGN_EPI = false, bool SP2 = false>
; __device__ __forceinline__ void gemm_phase(PG8_LAS unsigned char* lds, const Gemm g, const Sched& S, const Epi& E) {
;     ...
;             PG8_WAIT_V(8); PG8_WAIT_L(0); PG8_BAR; PG8_MMA(1, 0, At, B0); PG8_MMA(1, 1, At, B1); PG8_BAR; PG8_SCHED;
;             PG8_LDB(B0, 1, 0); PG8_LDB(B1, 1, 1); PG8_SCHED; PG8_LDA(At, 1, 0); PG8_STAGE(PG8_SA(0, 1), a2 + hstep, voffA);
;             PG8_WAIT_V(8); PG8_WAIT_L(0); PG8_BAR; PG8_MMA(0, 0, At, B0); PG8_MMA(0, 1, At, B1); PG8_BAR; PG8_SCHED;
	s_waitcnt lgkmcnt(0)
	v_mfma_f32_16x16x32_bf16 v[62:65], v[156:159], v[196:199], v[62:65]
	v_mfma_f32_16x16x32_bf16 v[58:61], v[164:167], v[196:199], v[58:61]
	v_mfma_f32_16x16x32_bf16 v[54:57], v[156:159], v[204:207], v[54:57]
	v_mfma_f32_16x16x32_bf16 v[46:49], v[164:167], v[204:207], v[46:49]
	v_mfma_f32_16x16x32_bf16 v[38:41], v[156:159], v[212:215], v[38:41]
	v_mfma_f32_16x16x32_bf16 v[30:33], v[164:167], v[212:215], v[30:33]
	v_mfma_f32_16x16x32_bf16 v[22:25], v[156:159], v[220:223], v[22:25]
	v_mfma_f32_16x16x32_bf16 v[14:17], v[164:167], v[220:223], v[14:17]
	v_mfma_f32_16x16x32_bf16 v[62:65], v[160:163], v[200:203], v[62:65]
	v_mfma_f32_16x16x32_bf16 v[58:61], v[168:171], v[200:203], v[58:61]
	v_mfma_f32_16x16x32_bf16 v[54:57], v[160:163], v[208:211], v[54:57]
	v_mfma_f32_16x16x32_bf16 v[46:49], v[168:171], v[208:211], v[46:49]
	v_mfma_f32_16x16x32_bf16 v[38:41], v[160:163], v[216:219], v[38:41]
	v_mfma_f32_16x16x32_bf16 v[30:33], v[168:171], v[216:219], v[30:33]
	v_mfma_f32_16x16x32_bf16 v[22:25], v[160:163], v[224:227], v[22:25]
	v_mfma_f32_16x16x32_bf16 v[14:17], v[168:171], v[224:227], v[14:17]
	v_mfma_f32_16x16x32_bf16 v[50:53], v[172:175], v[196:199], v[50:53]
	v_mfma_f32_16x16x32_bf16 v[42:45], v[184:187], v[196:199], v[42:45]
	v_mfma_f32_16x16x32_bf16 v[34:37], v[172:175], v[204:207], v[34:37]
	v_mfma_f32_16x16x32_bf16 v[26:29], v[184:187], v[204:207], v[26:29]
	v_mfma_f32_16x16x32_bf16 v[18:21], v[172:175], v[212:215], v[18:21]
	v_mfma_f32_16x16x32_bf16 v[10:13], v[184:187], v[212:215], v[10:13]
	v_mfma_f32_16x16x32_bf16 v[6:9], v[172:175], v[220:223], v[6:9]
	v_mfma_f32_16x16x32_bf16 v[2:5], v[184:187], v[220:223], v[2:5]
	v_mfma_f32_16x16x32_bf16 v[50:53], v[180:183], v[200:203], v[50:53]
	v_mfma_f32_16x16x32_bf16 v[42:45], v[192:195], v[200:203], v[42:45]
	v_mfma_f32_16x16x32_bf16 v[34:37], v[180:183], v[208:211], v[34:37]
	v_mfma_f32_16x16x32_bf16 v[26:29], v[192:195], v[208:211], v[26:29]
	v_mfma_f32_16x16x32_bf16 v[18:21], v[180:183], v[216:219], v[18:21]
	v_mfma_f32_16x16x32_bf16 v[10:13], v[192:195], v[216:219], v[10:13]
	v_mfma_f32_16x16x32_bf16 v[6:9], v[180:183], v[224:227], v[6:9]
	v_mfma_f32_16x16x32_bf16 v[2:5], v[192:195], v[224:227], v[2:5]
	s_barrier
	s_add_i32 s50, 0, 0x18000
	v_add_u32_e32 v155, s50, v147
	s_add_i32 s51, 0, 0x1c000
	ds_read_b128 v[156:159], v155
	ds_read_b128 v[160:163], v155 offset:1024
	ds_read_b128 v[164:167], v155 offset:2048
	ds_read_b128 v[168:171], v155 offset:3072
	v_add_u32_e32 v155, s51, v147
	ds_read_b128 v[172:175], v155
	ds_read_b128 v[180:183], v155 offset:1024
	ds_read_b128 v[184:187], v155 offset:2048
	ds_read_b128 v[192:195], v155 offset:3072
	s_add_u32 s26, s26, 0x80000
	s_addc_u32 s27, s27, 0
	s_mov_b32 m0, s34
	v_lshl_add_u64 v[232:233], s[26:27], 0, v[130:131]
	ds_read_b128 v[196:199], v154 offset:32768
	ds_read_b128 v[200:203], v154 offset:33792
	ds_read_b128 v[204:207], v154 offset:34816
	ds_read_b128 v[208:211], v154 offset:35840
	ds_read_b128 v[212:215], v154 offset:36864
	ds_read_b128 v[216:219], v154 offset:37888
	ds_read_b128 v[220:223], v154 offset:38912
	ds_read_b128 v[224:227], v154 offset:39936
	global_load_lds_dwordx4 v[232:233], off
	v_lshl_add_u64 v[232:233], s[26:27], 0, v[134:135]
	s_mov_b32 m0, s35
	s_nop 0
	global_load_lds_dwordx4 v[232:233], off
	s_waitcnt vmcnt(8)
	s_waitcnt lgkmcnt(0)
	s_barrier
	s_waitcnt lgkmcnt(0)
	v_mfma_f32_16x16x32_bf16 v[126:129], v[156:159], v[196:199], v[126:129]
	v_mfma_f32_16x16x32_bf16 v[122:125], v[164:167], v[196:199], v[122:125]
	v_mfma_f32_16x16x32_bf16 v[118:121], v[156:159], v[204:207], v[118:121]
	v_mfma_f32_16x16x32_bf16 v[110:113], v[164:167], v[204:207], v[110:113]
	v_mfma_f32_16x16x32_bf16 v[98:101], v[156:159], v[212:215], v[98:101]
	v_mfma_f32_16x16x32_bf16 v[90:93], v[164:167], v[212:215], v[90:93]
	v_mfma_f32_16x16x32_bf16 v[86:89], v[156:159], v[220:223], v[86:89]
	v_mfma_f32_16x16x32_bf16 v[78:81], v[164:167], v[220:223], v[78:81]
	v_mfma_f32_16x16x32_bf16 v[126:129], v[160:163], v[200:203], v[126:129]
	v_mfma_f32_16x16x32_bf16 v[122:125], v[168:171], v[200:203], v[122:125]
	v_mfma_f32_16x16x32_bf16 v[118:121], v[160:163], v[208:211], v[118:121]
	v_mfma_f32_16x16x32_bf16 v[110:113], v[168:171], v[208:211], v[110:113]
	v_mfma_f32_16x16x32_bf16 v[98:101], v[160:163], v[216:219], v[98:101]
	v_mfma_f32_16x16x32_bf16 v[90:93], v[168:171], v[216:219], v[90:93]
	v_mfma_f32_16x16x32_bf16 v[86:89], v[160:163], v[224:227], v[86:89]
	v_mfma_f32_16x16x32_bf16 v[78:81], v[168:171], v[224:227], v[78:81]
	v_mfma_f32_16x16x32_bf16 v[114:117], v[172:175], v[196:199], v[114:117]
	v_mfma_f32_16x16x32_bf16 v[106:109], v[184:187], v[196:199], v[106:109]
	v_mfma_f32_16x16x32_bf16 v[102:105], v[172:175], v[204:207], v[102:105]
	v_mfma_f32_16x16x32_bf16 v[94:97], v[184:187], v[204:207], v[94:97]
	v_mfma_f32_16x16x32_bf16 v[82:85], v[172:175], v[212:215], v[82:85]
	v_mfma_f32_16x16x32_bf16 v[74:77], v[184:187], v[212:215], v[74:77]
	v_mfma_f32_16x16x32_bf16 v[70:73], v[172:175], v[220:223], v[70:73]
	v_mfma_f32_16x16x32_bf16 v[66:69], v[184:187], v[220:223], v[66:69]
	v_mfma_f32_16x16x32_bf16 v[114:117], v[180:183], v[200:203], v[114:117]
	v_mfma_f32_16x16x32_bf16 v[106:109], v[192:195], v[200:203], v[106:109]
	v_mfma_f32_16x16x32_bf16 v[102:105], v[180:183], v[208:211], v[102:105]
	v_mfma_f32_16x16x32_bf16 v[94:97], v[192:195], v[208:211], v[94:97]
	v_mfma_f32_16x16x32_bf16 v[82:85], v[180:183], v[216:219], v[82:85]
	v_mfma_f32_16x16x32_bf16 v[74:77], v[192:195], v[216:219], v[74:77]
	v_mfma_f32_16x16x32_bf16 v[70:73], v[180:183], v[224:227], v[70:73]
	v_mfma_f32_16x16x32_bf16 v[66:69], v[192:195], v[224:227], v[66:69]
	s_barrier
; #define PG8_STAGE(bufoff, gbase, voff) do { _Pragma("unroll") for (int _i = 0; _i < 2; ++_i) \
;         __builtin_amdgcn_global_load_lds((const unsigned*)((const char*)(gbase) + (voff)[_i]), (PG8_LAS unsigned*)(lds + (bufoff) + ldsw + _i * 8192), 16, 0, 0); } while (0)
; #define PG8_STAGEB(bufoff, gbase, voff) do { _Pragma("unroll") for (int _i = 0; _i < 2; ++_i) \
;         __builtin_amdgcn_global_load_lds((const unsigned*)((const char*)(gbase) + (voff)[_i]), (PG8_LAS unsigned*)(lds + (bufoff) + ldsw + _i * 8192), 16, 0, PG8_BAUX); } while (0)
; #define PG8_LDA(dst, b, h) do { _Pragma("unroll") for (int m = 0; m < 4; ++m) _Pragma("unroll") for (int k = 0; k < 2; ++k) dst[m][k] = *(const PG8_LAS bf16x8*)(lds + PG8_SA(b, h) + aoff + m * 2048 + k * 1024); } while (0)
; #define PG8_MMA(ai, bj, At, Bt) do { __builtin_amdgcn_s_setprio(1); _Pragma("unroll") for (int m = 0; m < 4; ++m) _Pragma("unroll") for (int n = 0; n < 2; ++n) _Pragma("unroll") for (int k = 0; k < 2; ++k) \
;         acc[ai][bj][m][n] = __builtin_amdgcn_mfma_f32_16x16x32_bf16(Bt[n][k], At[m][k], acc[ai][bj][m][n], 0, 0, 0); __builtin_amdgcn_s_setprio(0); } while (0)
; #define PG8_WAIT_V(n) asm volatile("s_waitcnt vmcnt(" #n ")" ::: "memory")
; #define PG8_WAIT_L(n) asm volatile("s_waitcnt lgkmcnt(" #n ")" ::: "memory")
; #define PG8_BAR __builtin_amdgcn_s_barrier()
; #define PG8_SCHED __builtin_amdgcn_sched_barrier(0)
; template <class Epi, class Sched, bool ALIGN_EPI = false, bool SP2 = false>
; __device__ __forceinline__ void gemm_phase(PG8_LAS unsigned char* lds, const Gemm g, const Sched& S, const Epi& E) {
;     ...
;             PG8_LDA(At, 1, 1); PG8_STAGEB(PG8_SB(1, 0), b3, voffB); PG8_STAGEB(PG8_SB(1, 1), b3 + hstep, voffB); PG8_STAGE(PG8_SA(1, 0), a3, voffA);
;             PG8_WAIT_V(8); PG8_WAIT_L(0); PG8_BAR; PG8_MMA(1, 0, At, B0); PG8_MMA(1, 1, At, B1); PG8_BAR; PG8_SCHED;
	s_add_i32 s26, s50, s29
	v_lshl_add_u64 v[176:177], v[176:177], 0, s[8:9]
	s_mov_b32 m0, s26
	ds_read_b128 v[196:199], v154 offset:49152
	ds_read_b128 v[200:203], v154 offset:50176
	ds_read_b128 v[204:207], v154 offset:51200
	ds_read_b128 v[208:211], v154 offset:52224
	ds_read_b128 v[212:215], v154 offset:53248
	ds_read_b128 v[216:219], v154 offset:54272
	ds_read_b128 v[220:223], v154 offset:55296
	ds_read_b128 v[224:227], v154 offset:56320
	global_load_lds_dwordx4 v[176:177], off
	s_add_i32 m0, s26, 0x2000
	s_add_u32 s24, s24, 0x80080
	v_lshl_add_u64 v[176:177], v[188:189], 0, s[8:9]
	s_addc_u32 s25, s25, 0
	s_add_i32 s26, s51, s29
	global_load_lds_dwordx4 v[176:177], off
	v_lshl_add_u64 v[176:177], s[24:25], 0, v[132:133]
	s_mov_b32 m0, s26
	s_nop 0
	global_load_lds_dwordx4 v[176:177], off
	v_lshl_add_u64 v[176:177], s[24:25], 0, v[136:137]
	s_add_i32 m0, s26, 0x2000
	s_nop 0
	global_load_lds_dwordx4 v[176:177], off
	v_lshl_add_u64 v[176:177], v[228:229], 0, s[8:9]
	s_mov_b32 m0, s39
	s_nop 0
	global_load_lds_dwordx4 v[176:177], off
	v_lshl_add_u64 v[176:177], v[230:231], 0, s[8:9]
	s_mov_b32 m0, s40
	s_nop 0
	global_load_lds_dwordx4 v[176:177], off
	s_waitcnt vmcnt(8)
	s_waitcnt lgkmcnt(0)
	s_barrier
	s_waitcnt lgkmcnt(0)
	v_mfma_f32_16x16x32_bf16 v[62:65], v[156:159], v[196:199], v[62:65]
	v_mfma_f32_16x16x32_bf16 v[58:61], v[164:167], v[196:199], v[58:61]
	v_mfma_f32_16x16x32_bf16 v[54:57], v[156:159], v[204:207], v[54:57]
	v_mfma_f32_16x16x32_bf16 v[46:49], v[164:167], v[204:207], v[46:49]
	v_mfma_f32_16x16x32_bf16 v[38:41], v[156:159], v[212:215], v[38:41]
	v_mfma_f32_16x16x32_bf16 v[30:33], v[164:167], v[212:215], v[30:33]
	v_mfma_f32_16x16x32_bf16 v[22:25], v[156:159], v[220:223], v[22:25]
	v_mfma_f32_16x16x32_bf16 v[14:17], v[164:167], v[220:223], v[14:17]
	v_mfma_f32_16x16x32_bf16 v[62:65], v[160:163], v[200:203], v[62:65]
	v_mfma_f32_16x16x32_bf16 v[58:61], v[168:171], v[200:203], v[58:61]
	v_mfma_f32_16x16x32_bf16 v[54:57], v[160:163], v[208:211], v[54:57]
	v_mfma_f32_16x16x32_bf16 v[46:49], v[168:171], v[208:211], v[46:49]
	v_mfma_f32_16x16x32_bf16 v[38:41], v[160:163], v[216:219], v[38:41]
	v_mfma_f32_16x16x32_bf16 v[30:33], v[168:171], v[216:219], v[30:33]
	v_mfma_f32_16x16x32_bf16 v[22:25], v[160:163], v[224:227], v[22:25]
	v_mfma_f32_16x16x32_bf16 v[14:17], v[168:171], v[224:227], v[14:17]
	v_mfma_f32_16x16x32_bf16 v[50:53], v[172:175], v[196:199], v[50:53]
	v_mfma_f32_16x16x32_bf16 v[42:45], v[184:187], v[196:199], v[42:45]
	v_mfma_f32_16x16x32_bf16 v[34:37], v[172:175], v[204:207], v[34:37]
	v_mfma_f32_16x16x32_bf16 v[26:29], v[184:187], v[204:207], v[26:29]
	v_mfma_f32_16x16x32_bf16 v[18:21], v[172:175], v[212:215], v[18:21]
	v_mfma_f32_16x16x32_bf16 v[10:13], v[184:187], v[212:215], v[10:13]
	v_mfma_f32_16x16x32_bf16 v[6:9], v[172:175], v[220:223], v[6:9]
	v_mfma_f32_16x16x32_bf16 v[2:5], v[184:187], v[220:223], v[2:5]
	v_mfma_f32_16x16x32_bf16 v[50:53], v[180:183], v[200:203], v[50:53]
	v_mfma_f32_16x16x32_bf16 v[42:45], v[192:195], v[200:203], v[42:45]
	v_mfma_f32_16x16x32_bf16 v[34:37], v[180:183], v[208:211], v[34:37]
	v_mfma_f32_16x16x32_bf16 v[26:29], v[192:195], v[208:211], v[26:29]
	v_mfma_f32_16x16x32_bf16 v[18:21], v[180:183], v[216:219], v[18:21]
	v_mfma_f32_16x16x32_bf16 v[10:13], v[192:195], v[216:219], v[10:13]
	v_mfma_f32_16x16x32_bf16 v[6:9], v[180:183], v[224:227], v[6:9]
	v_mfma_f32_16x16x32_bf16 v[2:5], v[192:195], v[224:227], v[2:5]
	s_barrier
	s_add_i32 s49, s49, 2
	s_add_u32 s22, s22, 0x100
	s_addc_u32 s23, s23, 0
	s_add_u32 s47, s47, 0x100
	s_addc_u32 s48, s48, 0
	s_cmp_gt_u32 s49, 29
	s_cbranch_scc0 .LBB0_1437
	s_and_b64 vcc, exec, s[10:11]
	s_cbranch_vccz .LBB0_1440
	s_barrier

; #define PG8_STAGE(bufoff, gbase, voff) do { _Pragma("unroll") for (int _i = 0; _i < 2; ++_i) \
;         __builtin_amdgcn_global_load_lds((const unsigned*)((const char*)(gbase) + (voff)[_i]), (PG8_LAS unsigned*)(lds + (bufoff) + ldsw + _i * 8192), 16, 0, 0); } while (0)
; #define PG8_STAGEB(bufoff, gbase, voff) do { _Pragma("unroll") for (int _i = 0; _i < 2; ++_i) \
;         __builtin_amdgcn_global_load_lds((const unsigned*)((const char*)(gbase) + (voff)[_i]), (PG8_LAS unsigned*)(lds + (bufoff) + ldsw + _i * 8192), 16, 0, PG8_BAUX); } while (0)
; #define PG8_LDA(dst, b, h) do { _Pragma("unroll") for (int m = 0; m < 4; ++m) _Pragma("unroll") for (int k = 0; k < 2; ++k) dst[m][k] = *(const PG8_LAS bf16x8*)(lds + PG8_SA(b, h) + aoff + m * 2048 + k * 1024); } while (0)
; #define PG8_LDB(dst, b, h) do { _Pragma("unroll") for (int n = 0; n < 2; ++n) _Pragma("unroll") for (int k = 0; k < 2; ++k) dst[n][k] = *(const PG8_LAS bf16x8*)(lds + PG8_SB(b, h) + boff + n * 2048 + k * 1024); } while (0)
; #define PG8_MMA(ai, bj, At, Bt) do { __builtin_amdgcn_s_setprio(1); _Pragma("unroll") for (int m = 0; m < 4; ++m) _Pragma("unroll") for (int n = 0; n < 2; ++n) _Pragma("unroll") for (int k = 0; k < 2; ++k) \
;         acc[ai][bj][m][n] = __builtin_amdgcn_mfma_f32_16x16x32_bf16(Bt[n][k], At[m][k], acc[ai][bj][m][n], 0, 0, 0); __builtin_amdgcn_s_setprio(0); } while (0)
; #define PG8_WAIT_V(n) asm volatile("s_waitcnt vmcnt(" #n ")" ::: "memory")
; #define PG8_WAIT_L(n) asm volatile("s_waitcnt lgkmcnt(" #n ")" ::: "memory")
; #define PG8_BAR __builtin_amdgcn_s_barrier()
; #define PG8_SCHED __builtin_amdgcn_sched_barrier(0)
; template <class Epi, class Sched, bool ALIGN_EPI = false, bool SP2 = false>
; __device__ __forceinline__ void gemm_phase(PG8_LAS unsigned char* lds, const Gemm g, const Sched& S, const Epi& E) {
;     ...
;             PG8_LDB(B0, 0, 0); PG8_LDB(B1, 0, 1); PG8_SCHED; PG8_LDA(At, 0, 0); PG8_STAGE(PG8_SA(1, 1), a1 + hstep, voffA);
;             PG8_WAIT_V(8); PG8_WAIT_L(0); PG8_BAR; PG8_MMA(0, 0, At, B0); PG8_MMA(0, 1, At, B1); PG8_BAR; PG8_SCHED;
;             PG8_LDA(At, 0, 1); PG8_STAGEB(PG8_SB(0, 0), b2, voffB); PG8_STAGEB(PG8_SB(0, 1), b2 + hstep, voffB); PG8_STAGE(PG8_SA(0, 0), a2, voffA);
.LBB0_1604:
	ds_read_b128 v[158:161], v153
	ds_read_b128 v[162:165], v153 offset:1024
	ds_read_b128 v[166:169], v153 offset:2048
	ds_read_b128 v[170:173], v153 offset:3072
	ds_read_b128 v[174:177], v154
	ds_read_b128 v[178:181], v154 offset:1024
	ds_read_b128 v[182:185], v154 offset:2048
	ds_read_b128 v[186:189], v154 offset:3072
	s_add_u32 s30, s28, 0xfffc0080
	s_addc_u32 s31, s29, -1
	s_cmp_eq_u32 s53, 12
	s_cselect_b32 s35, s17, s31
	s_cselect_b32 s34, s25, s30
	s_cselect_b32 s31, s19, s52
	s_cselect_b32 s30, s50, s51
	v_lshl_add_u64 v[148:149], s[28:29], 0, v[140:141]
	s_add_i32 m0, s27, 0xc000
	ds_read_b128 v[192:195], v155
	ds_read_b128 v[196:199], v155 offset:1024
	ds_read_b128 v[200:203], v155 offset:2048
	ds_read_b128 v[204:207], v155 offset:3072
	ds_read_b128 v[208:211], v155 offset:4096
	ds_read_b128 v[212:215], v155 offset:5120
	ds_read_b128 v[216:219], v155 offset:6144
	ds_read_b128 v[220:223], v155 offset:7168
	global_load_lds_dwordx4 v[148:149], off
	v_lshl_add_u64 v[148:149], s[28:29], 0, v[142:143]
	s_add_i32 m0, s27, 0xe000
	s_nop 0
	global_load_lds_dwordx4 v[148:149], off
	s_waitcnt vmcnt(8)
	s_waitcnt lgkmcnt(0)
	s_barrier
	s_waitcnt lgkmcnt(0)
	v_mfma_f32_16x16x32_bf16 v[126:129], v[158:161], v[192:195], v[126:129]
	v_mfma_f32_16x16x32_bf16 v[122:125], v[166:169], v[192:195], v[122:125]
	v_mfma_f32_16x16x32_bf16 v[110:113], v[158:161], v[200:203], v[110:113]
	v_mfma_f32_16x16x32_bf16 v[106:109], v[166:169], v[200:203], v[106:109]
	v_mfma_f32_16x16x32_bf16 v[94:97], v[158:161], v[208:211], v[94:97]
	v_mfma_f32_16x16x32_bf16 v[90:93], v[166:169], v[208:211], v[90:93]
	v_mfma_f32_16x16x32_bf16 v[78:81], v[158:161], v[216:219], v[78:81]
	v_mfma_f32_16x16x32_bf16 v[74:77], v[166:169], v[216:219], v[74:77]
	v_mfma_f32_16x16x32_bf16 v[126:129], v[162:165], v[196:199], v[126:129]
	v_mfma_f32_16x16x32_bf16 v[122:125], v[170:173], v[196:199], v[122:125]
	v_mfma_f32_16x16x32_bf16 v[110:113], v[162:165], v[204:207], v[110:113]
	v_mfma_f32_16x16x32_bf16 v[106:109], v[170:173], v[204:207], v[106:109]
	v_mfma_f32_16x16x32_bf16 v[94:97], v[162:165], v[212:215], v[94:97]
	v_mfma_f32_16x16x32_bf16 v[90:93], v[170:173], v[212:215], v[90:93]
	v_mfma_f32_16x16x32_bf16 v[78:81], v[162:165], v[220:223], v[78:81]
	v_mfma_f32_16x16x32_bf16 v[74:77], v[170:173], v[220:223], v[74:77]
	v_mfma_f32_16x16x32_bf16 v[118:121], v[174:177], v[192:195], v[118:121]
	v_mfma_f32_16x16x32_bf16 v[114:117], v[182:185], v[192:195], v[114:117]
	v_mfma_f32_16x16x32_bf16 v[102:105], v[174:177], v[200:203], v[102:105]
	v_mfma_f32_16x16x32_bf16 v[98:101], v[182:185], v[200:203], v[98:101]
	v_mfma_f32_16x16x32_bf16 v[86:89], v[174:177], v[208:211], v[86:89]
	v_mfma_f32_16x16x32_bf16 v[82:85], v[182:185], v[208:211], v[82:85]
	v_mfma_f32_16x16x32_bf16 v[70:73], v[174:177], v[216:219], v[70:73]
	v_mfma_f32_16x16x32_bf16 v[66:69], v[182:185], v[216:219], v[66:69]
	v_mfma_f32_16x16x32_bf16 v[118:121], v[178:181], v[196:199], v[118:121]
	v_mfma_f32_16x16x32_bf16 v[114:117], v[186:189], v[196:199], v[114:117]
	v_mfma_f32_16x16x32_bf16 v[102:105], v[178:181], v[204:207], v[102:105]
	v_mfma_f32_16x16x32_bf16 v[98:101], v[186:189], v[204:207], v[98:101]
	v_mfma_f32_16x16x32_bf16 v[86:89], v[178:181], v[212:215], v[86:89]
	v_mfma_f32_16x16x32_bf16 v[82:85], v[186:189], v[212:215], v[82:85]
	v_mfma_f32_16x16x32_bf16 v[70:73], v[178:181], v[220:223], v[70:73]
	v_mfma_f32_16x16x32_bf16 v[66:69], v[186:189], v[220:223], v[66:69]
	s_barrier
	s_add_i32 s54, s48, s39
	v_lshl_add_u64 v[148:149], s[30:31], 0, v[132:133]
	s_mov_b32 m0, s54
	ds_read_b128 v[192:195], v155 offset:16384
	ds_read_b128 v[196:199], v155 offset:17408
	ds_read_b128 v[200:203], v155 offset:18432
	ds_read_b128 v[204:207], v155 offset:19456
	ds_read_b128 v[208:211], v155 offset:20480
	ds_read_b128 v[212:215], v155 offset:21504
	ds_read_b128 v[216:219], v155 offset:22528
	ds_read_b128 v[220:223], v155 offset:23552
	global_load_lds_dwordx4 v[148:149], off
	s_add_i32 m0, s54, 0x2000
	s_add_u32 s54, s30, 0x40000
	v_lshl_add_u64 v[224:225], s[30:31], 0, v[136:137]
	s_addc_u32 s55, s31, 0
	s_add_i32 s56, s49, s39
	global_load_lds_dwordx4 v[224:225], off
	v_lshl_add_u64 v[226:227], s[54:55], 0, v[132:133]
	s_mov_b32 m0, s56
	v_lshl_add_u64 v[228:229], s[34:35], 0, v[134:135]
	global_load_lds_dwordx4 v[226:227], off
	v_lshl_add_u64 v[226:227], s[54:55], 0, v[136:137]
	s_add_i32 m0, s56, 0x2000
	s_nop 0
	global_load_lds_dwordx4 v[226:227], off
	v_lshl_add_u64 v[226:227], s[34:35], 0, v[130:131]
	s_mov_b32 m0, s27
	s_nop 0
	global_load_lds_dwordx4 v[226:227], off
	s_mov_b32 m0, s40
	s_nop 0
	global_load_lds_dwordx4 v[228:229], off
	s_waitcnt vmcnt(8)
	s_waitcnt lgkmcnt(0)
	s_barrier
; #define PG8_STAGE(bufoff, gbase, voff) do { _Pragma("unroll") for (int _i = 0; _i < 2; ++_i) \
;         __builtin_amdgcn_global_load_lds((const unsigned*)((const char*)(gbase) + (voff)[_i]), (PG8_LAS unsigned*)(lds + (bufoff) + ldsw + _i * 8192), 16, 0, 0); } while (0)
; #define PG8_LDA(dst, b, h) do { _Pragma("unroll") for (int m = 0; m < 4; ++m) _Pragma("unroll") for (int k = 0; k < 2; ++k) dst[m][k] = *(const PG8_LAS bf16x8*)(lds + PG8_SA(b, h) + aoff + m * 2048 + k * 1024); } while (0)
; #define PG8_LDB(dst, b, h) do { _Pragma("unroll") for (int n = 0; n < 2; ++n) _Pragma("unroll") for (int k = 0; k < 2; ++k) dst[n][k] = *(const PG8_LAS bf16x8*)(lds + PG8_SB(b, h) + boff + n * 2048 + k * 1024); } while (0)
; #define PG8_MMA(ai, bj, At, Bt) do { __builtin_amdgcn_s_setprio(1); _Pragma("unroll") for (int m = 0; m < 4; ++m) _Pragma("unroll") for (int n = 0; n < 2; ++n) _Pragma("unroll") for (int k = 0; k < 2; ++k) \
;         acc[ai][bj][m][n] = __builtin_amdgcn_mfma_f32_16x16x32_bf16(Bt[n][k], At[m][k], acc[ai][bj][m][n], 0, 0, 0); __builtin_amdgcn_s_setprio(0); } while (0)
; #define PG8_WAIT_V(n) asm volatile("s_waitcnt vmcnt(" #n ")" ::: "memory")
; #define PG8_WAIT_L(n) asm volatile("s_waitcnt lgkmcnt(" #n ")" ::: "memory")
; #define PG8_BAR __builtin_amdgcn_s_barrier()
; #define PG8_SCHED __builtin_amdgcn_sched_barrier(0)
; template <class Epi, class Sched, bool ALIGN_EPI = false, bool SP2 = false>
; __device__ __forceinline__ void gemm_phase(PG8_LAS unsigned char* lds, const Gemm g, const Sched& S, const Epi& E) {
;     ...
;             PG8_WAIT_V(8); PG8_WAIT_L(0); PG8_BAR; PG8_MMA(1, 0, At, B0); PG8_MMA(1, 1, At, B1); PG8_BAR; PG8_SCHED;
;             PG8_LDB(B0, 1, 0); PG8_LDB(B1, 1, 1); PG8_SCHED; PG8_LDA(At, 1, 0); PG8_STAGE(PG8_SA(0, 1), a2 + hstep, voffA);
;             PG8_WAIT_V(8); PG8_WAIT_L(0); PG8_BAR; PG8_MMA(0, 0, At, B0); PG8_MMA(0, 1, At, B1); PG8_BAR; PG8_SCHED;
	s_waitcnt lgkmcnt(0)
	v_mfma_f32_16x16x32_bf16 v[62:65], v[158:161], v[192:195], v[62:65]
	v_mfma_f32_16x16x32_bf16 v[58:61], v[166:169], v[192:195], v[58:61]
	v_mfma_f32_16x16x32_bf16 v[46:49], v[158:161], v[200:203], v[46:49]
	v_mfma_f32_16x16x32_bf16 v[42:45], v[166:169], v[200:203], v[42:45]
	v_mfma_f32_16x16x32_bf16 v[30:33], v[158:161], v[208:211], v[30:33]
	v_mfma_f32_16x16x32_bf16 v[26:29], v[166:169], v[208:211], v[26:29]
	v_mfma_f32_16x16x32_bf16 v[14:17], v[158:161], v[216:219], v[14:17]
	v_mfma_f32_16x16x32_bf16 v[10:13], v[166:169], v[216:219], v[10:13]
	v_mfma_f32_16x16x32_bf16 v[62:65], v[162:165], v[196:199], v[62:65]
	v_mfma_f32_16x16x32_bf16 v[58:61], v[170:173], v[196:199], v[58:61]
	v_mfma_f32_16x16x32_bf16 v[46:49], v[162:165], v[204:207], v[46:49]
	v_mfma_f32_16x16x32_bf16 v[42:45], v[170:173], v[204:207], v[42:45]
	v_mfma_f32_16x16x32_bf16 v[30:33], v[162:165], v[212:215], v[30:33]
	v_mfma_f32_16x16x32_bf16 v[26:29], v[170:173], v[212:215], v[26:29]
	v_mfma_f32_16x16x32_bf16 v[14:17], v[162:165], v[220:223], v[14:17]
	v_mfma_f32_16x16x32_bf16 v[10:13], v[170:173], v[220:223], v[10:13]
	v_mfma_f32_16x16x32_bf16 v[54:57], v[174:177], v[192:195], v[54:57]
	v_mfma_f32_16x16x32_bf16 v[50:53], v[182:185], v[192:195], v[50:53]
	v_mfma_f32_16x16x32_bf16 v[38:41], v[174:177], v[200:203], v[38:41]
	v_mfma_f32_16x16x32_bf16 v[34:37], v[182:185], v[200:203], v[34:37]
	v_mfma_f32_16x16x32_bf16 v[22:25], v[174:177], v[208:211], v[22:25]
	v_mfma_f32_16x16x32_bf16 v[18:21], v[182:185], v[208:211], v[18:21]
	v_mfma_f32_16x16x32_bf16 v[6:9], v[174:177], v[216:219], v[6:9]
	v_mfma_f32_16x16x32_bf16 v[2:5], v[182:185], v[216:219], v[2:5]
	v_mfma_f32_16x16x32_bf16 v[54:57], v[178:181], v[196:199], v[54:57]
	v_mfma_f32_16x16x32_bf16 v[50:53], v[186:189], v[196:199], v[50:53]
	v_mfma_f32_16x16x32_bf16 v[38:41], v[178:181], v[204:207], v[38:41]
	v_mfma_f32_16x16x32_bf16 v[34:37], v[186:189], v[204:207], v[34:37]
	v_mfma_f32_16x16x32_bf16 v[22:25], v[178:181], v[212:215], v[22:25]
	v_mfma_f32_16x16x32_bf16 v[18:21], v[186:189], v[212:215], v[18:21]
	v_mfma_f32_16x16x32_bf16 v[6:9], v[178:181], v[220:223], v[6:9]
	v_mfma_f32_16x16x32_bf16 v[2:5], v[186:189], v[220:223], v[2:5]
	s_barrier
	s_add_i32 s54, 0, 0x18000
	v_add_u32_e32 v138, s54, v151
	s_add_i32 s55, 0, 0x1c000
	ds_read_b128 v[158:161], v138
	ds_read_b128 v[162:165], v138 offset:1024
	ds_read_b128 v[166:169], v138 offset:2048
	ds_read_b128 v[170:173], v138 offset:3072
	v_add_u32_e32 v138, s55, v151
	ds_read_b128 v[174:177], v138
	ds_read_b128 v[178:181], v138 offset:1024
	ds_read_b128 v[182:185], v138 offset:2048
	ds_read_b128 v[186:189], v138 offset:3072
	s_add_u32 s34, s34, 0x40000
	s_addc_u32 s35, s35, 0
	s_mov_b32 m0, s41
	v_lshl_add_u64 v[230:231], s[34:35], 0, v[130:131]
	ds_read_b128 v[192:195], v155 offset:32768
	ds_read_b128 v[196:199], v155 offset:33792
	ds_read_b128 v[200:203], v155 offset:34816
	ds_read_b128 v[204:207], v155 offset:35840
	ds_read_b128 v[208:211], v155 offset:36864
	ds_read_b128 v[212:215], v155 offset:37888
	ds_read_b128 v[216:219], v155 offset:38912
	ds_read_b128 v[220:223], v155 offset:39936
	global_load_lds_dwordx4 v[230:231], off
	v_lshl_add_u64 v[230:231], s[34:35], 0, v[134:135]
	s_mov_b32 m0, s42
	s_nop 0
	global_load_lds_dwordx4 v[230:231], off
	s_waitcnt vmcnt(8)
	s_waitcnt lgkmcnt(0)
	s_barrier
	s_waitcnt lgkmcnt(0)
	v_mfma_f32_16x16x32_bf16 v[126:129], v[158:161], v[192:195], v[126:129]
	v_mfma_f32_16x16x32_bf16 v[122:125], v[166:169], v[192:195], v[122:125]
	v_mfma_f32_16x16x32_bf16 v[110:113], v[158:161], v[200:203], v[110:113]
	v_mfma_f32_16x16x32_bf16 v[106:109], v[166:169], v[200:203], v[106:109]
	v_mfma_f32_16x16x32_bf16 v[94:97], v[158:161], v[208:211], v[94:97]
	v_mfma_f32_16x16x32_bf16 v[90:93], v[166:169], v[208:211], v[90:93]
	v_mfma_f32_16x16x32_bf16 v[78:81], v[158:161], v[216:219], v[78:81]
	v_mfma_f32_16x16x32_bf16 v[74:77], v[166:169], v[216:219], v[74:77]
	v_mfma_f32_16x16x32_bf16 v[126:129], v[162:165], v[196:199], v[126:129]
	v_mfma_f32_16x16x32_bf16 v[122:125], v[170:173], v[196:199], v[122:125]
	v_mfma_f32_16x16x32_bf16 v[110:113], v[162:165], v[204:207], v[110:113]
	v_mfma_f32_16x16x32_bf16 v[106:109], v[170:173], v[204:207], v[106:109]
	v_mfma_f32_16x16x32_bf16 v[94:97], v[162:165], v[212:215], v[94:97]
	v_mfma_f32_16x16x32_bf16 v[90:93], v[170:173], v[212:215], v[90:93]
	v_mfma_f32_16x16x32_bf16 v[78:81], v[162:165], v[220:223], v[78:81]
	v_mfma_f32_16x16x32_bf16 v[74:77], v[170:173], v[220:223], v[74:77]
	v_mfma_f32_16x16x32_bf16 v[118:121], v[174:177], v[192:195], v[118:121]
	v_mfma_f32_16x16x32_bf16 v[114:117], v[182:185], v[192:195], v[114:117]
	v_mfma_f32_16x16x32_bf16 v[102:105], v[174:177], v[200:203], v[102:105]
	v_mfma_f32_16x16x32_bf16 v[98:101], v[182:185], v[200:203], v[98:101]
	v_mfma_f32_16x16x32_bf16 v[86:89], v[174:177], v[208:211], v[86:89]
	v_mfma_f32_16x16x32_bf16 v[82:85], v[182:185], v[208:211], v[82:85]
	v_mfma_f32_16x16x32_bf16 v[70:73], v[174:177], v[216:219], v[70:73]
	v_mfma_f32_16x16x32_bf16 v[66:69], v[182:185], v[216:219], v[66:69]
	v_mfma_f32_16x16x32_bf16 v[118:121], v[178:181], v[196:199], v[118:121]
	v_mfma_f32_16x16x32_bf16 v[114:117], v[186:189], v[196:199], v[114:117]
	v_mfma_f32_16x16x32_bf16 v[102:105], v[178:181], v[204:207], v[102:105]
	v_mfma_f32_16x16x32_bf16 v[98:101], v[186:189], v[204:207], v[98:101]
	v_mfma_f32_16x16x32_bf16 v[86:89], v[178:181], v[212:215], v[86:89]
	v_mfma_f32_16x16x32_bf16 v[82:85], v[186:189], v[212:215], v[82:85]
	v_mfma_f32_16x16x32_bf16 v[70:73], v[178:181], v[220:223], v[70:73]
	v_mfma_f32_16x16x32_bf16 v[66:69], v[186:189], v[220:223], v[66:69]
	s_barrier
; #define PG8_STAGE(bufoff, gbase, voff) do { _Pragma("unroll") for (int _i = 0; _i < 2; ++_i) \
;         __builtin_amdgcn_global_load_lds((const unsigned*)((const char*)(gbase) + (voff)[_i]), (PG8_LAS unsigned*)(lds + (bufoff) + ldsw + _i * 8192), 16, 0, 0); } while (0)
; #define PG8_STAGEB(bufoff, gbase, voff) do { _Pragma("unroll") for (int _i = 0; _i < 2; ++_i) \
;         __builtin_amdgcn_global_load_lds((const unsigned*)((const char*)(gbase) + (voff)[_i]), (PG8_LAS unsigned*)(lds + (bufoff) + ldsw + _i * 8192), 16, 0, PG8_BAUX); } while (0)
; #define PG8_LDA(dst, b, h) do { _Pragma("unroll") for (int m = 0; m < 4; ++m) _Pragma("unroll") for (int k = 0; k < 2; ++k) dst[m][k] = *(const PG8_LAS bf16x8*)(lds + PG8_SA(b, h) + aoff + m * 2048 + k * 1024); } while (0)
; #define PG8_MMA(ai, bj, At, Bt) do { __builtin_amdgcn_s_setprio(1); _Pragma("unroll") for (int m = 0; m < 4; ++m) _Pragma("unroll") for (int n = 0; n < 2; ++n) _Pragma("unroll") for (int k = 0; k < 2; ++k) \
;         acc[ai][bj][m][n] = __builtin_amdgcn_mfma_f32_16x16x32_bf16(Bt[n][k], At[m][k], acc[ai][bj][m][n], 0, 0, 0); __builtin_amdgcn_s_setprio(0); } while (0)
; #define PG8_WAIT_V(n) asm volatile("s_waitcnt vmcnt(" #n ")" ::: "memory")
; #define PG8_WAIT_L(n) asm volatile("s_waitcnt lgkmcnt(" #n ")" ::: "memory")
; #define PG8_BAR __builtin_amdgcn_s_barrier()
; #define PG8_SCHED __builtin_amdgcn_sched_barrier(0)
; template <class Epi, class Sched, bool ALIGN_EPI = false, bool SP2 = false>
; __device__ __forceinline__ void gemm_phase(PG8_LAS unsigned char* lds, const Gemm g, const Sched& S, const Epi& E) {
;     ...
;             PG8_LDA(At, 1, 1); PG8_STAGEB(PG8_SB(1, 0), b3, voffB); PG8_STAGEB(PG8_SB(1, 1), b3 + hstep, voffB); PG8_STAGE(PG8_SA(1, 0), a3, voffA);
;             PG8_WAIT_V(8); PG8_WAIT_L(0); PG8_BAR; PG8_MMA(1, 0, At, B0); PG8_MMA(1, 1, At, B1); PG8_BAR; PG8_SCHED;
	s_add_i32 s34, s54, s39
	v_lshl_add_u64 v[148:149], v[148:149], 0, s[12:13]
	s_mov_b32 m0, s34
	ds_read_b128 v[192:195], v155 offset:49152
	ds_read_b128 v[196:199], v155 offset:50176
	ds_read_b128 v[200:203], v155 offset:51200
	ds_read_b128 v[204:207], v155 offset:52224
	ds_read_b128 v[208:211], v155 offset:53248
	ds_read_b128 v[212:215], v155 offset:54272
	ds_read_b128 v[216:219], v155 offset:55296
	ds_read_b128 v[220:223], v155 offset:56320
	global_load_lds_dwordx4 v[148:149], off
	s_add_i32 m0, s34, 0x2000
	s_add_u32 s30, s30, 0x40080
	v_lshl_add_u64 v[148:149], v[224:225], 0, s[12:13]
	s_addc_u32 s31, s31, 0
	s_add_i32 s34, s55, s39
	global_load_lds_dwordx4 v[148:149], off
	v_lshl_add_u64 v[148:149], s[30:31], 0, v[132:133]
	s_mov_b32 m0, s34
	s_nop 0
	global_load_lds_dwordx4 v[148:149], off
	v_lshl_add_u64 v[148:149], s[30:31], 0, v[136:137]
	s_add_i32 m0, s34, 0x2000
	s_nop 0
	global_load_lds_dwordx4 v[148:149], off
	v_lshl_add_u64 v[148:149], v[226:227], 0, s[12:13]
	s_mov_b32 m0, s44
	s_nop 0
	global_load_lds_dwordx4 v[148:149], off
	v_lshl_add_u64 v[148:149], v[228:229], 0, s[12:13]
	s_mov_b32 m0, s45
	s_nop 0
	global_load_lds_dwordx4 v[148:149], off
	s_waitcnt vmcnt(8)
	s_waitcnt lgkmcnt(0)
	s_barrier
	s_waitcnt lgkmcnt(0)
	v_mfma_f32_16x16x32_bf16 v[62:65], v[158:161], v[192:195], v[62:65]
	v_mfma_f32_16x16x32_bf16 v[58:61], v[166:169], v[192:195], v[58:61]
	v_mfma_f32_16x16x32_bf16 v[46:49], v[158:161], v[200:203], v[46:49]
	v_mfma_f32_16x16x32_bf16 v[42:45], v[166:169], v[200:203], v[42:45]
	v_mfma_f32_16x16x32_bf16 v[30:33], v[158:161], v[208:211], v[30:33]
	v_mfma_f32_16x16x32_bf16 v[26:29], v[166:169], v[208:211], v[26:29]
	v_mfma_f32_16x16x32_bf16 v[14:17], v[158:161], v[216:219], v[14:17]
	v_mfma_f32_16x16x32_bf16 v[10:13], v[166:169], v[216:219], v[10:13]
	v_mfma_f32_16x16x32_bf16 v[62:65], v[162:165], v[196:199], v[62:65]
	v_mfma_f32_16x16x32_bf16 v[58:61], v[170:173], v[196:199], v[58:61]
	v_mfma_f32_16x16x32_bf16 v[46:49], v[162:165], v[204:207], v[46:49]
	v_mfma_f32_16x16x32_bf16 v[42:45], v[170:173], v[204:207], v[42:45]
	v_mfma_f32_16x16x32_bf16 v[30:33], v[162:165], v[212:215], v[30:33]
	v_mfma_f32_16x16x32_bf16 v[26:29], v[170:173], v[212:215], v[26:29]
	v_mfma_f32_16x16x32_bf16 v[14:17], v[162:165], v[220:223], v[14:17]
	v_mfma_f32_16x16x32_bf16 v[10:13], v[170:173], v[220:223], v[10:13]
	v_mfma_f32_16x16x32_bf16 v[54:57], v[174:177], v[192:195], v[54:57]
	v_mfma_f32_16x16x32_bf16 v[50:53], v[182:185], v[192:195], v[50:53]
	v_mfma_f32_16x16x32_bf16 v[38:41], v[174:177], v[200:203], v[38:41]
	v_mfma_f32_16x16x32_bf16 v[34:37], v[182:185], v[200:203], v[34:37]
	v_mfma_f32_16x16x32_bf16 v[22:25], v[174:177], v[208:211], v[22:25]
	v_mfma_f32_16x16x32_bf16 v[18:21], v[182:185], v[208:211], v[18:21]
	v_mfma_f32_16x16x32_bf16 v[6:9], v[174:177], v[216:219], v[6:9]
	v_mfma_f32_16x16x32_bf16 v[2:5], v[182:185], v[216:219], v[2:5]
	v_mfma_f32_16x16x32_bf16 v[54:57], v[178:181], v[196:199], v[54:57]
	v_mfma_f32_16x16x32_bf16 v[50:53], v[186:189], v[196:199], v[50:53]
	v_mfma_f32_16x16x32_bf16 v[38:41], v[178:181], v[204:207], v[38:41]
	v_mfma_f32_16x16x32_bf16 v[34:37], v[186:189], v[204:207], v[34:37]
	v_mfma_f32_16x16x32_bf16 v[22:25], v[178:181], v[212:215], v[22:25]
	v_mfma_f32_16x16x32_bf16 v[18:21], v[186:189], v[212:215], v[18:21]
	v_mfma_f32_16x16x32_bf16 v[6:9], v[178:181], v[220:223], v[6:9]
	v_mfma_f32_16x16x32_bf16 v[2:5], v[186:189], v[220:223], v[2:5]
	s_barrier
	s_add_i32 s53, s53, 2
	s_add_u32 s28, s28, 0x100
	s_addc_u32 s29, s29, 0
	s_add_u32 s51, s51, 0x100
	s_addc_u32 s52, s52, 0
	s_cmp_gt_u32 s53, 13
	s_cbranch_scc0 .LBB0_1604
	s_and_b64 vcc, exec, s[14:15]
	s_cbranch_vccz .LBB0_1607
	s_barrier

; #define PG8_STAGE(bufoff, gbase, voff) do { _Pragma("unroll") for (int _i = 0; _i < 2; ++_i) \
;         __builtin_amdgcn_global_load_lds((const unsigned*)((const char*)(gbase) + (voff)[_i]), (PG8_LAS unsigned*)(lds + (bufoff) + ldsw + _i * 8192), 16, 0, 0); } while (0)
; #define PG8_STAGEB(bufoff, gbase, voff) do { _Pragma("unroll") for (int _i = 0; _i < 2; ++_i) \
;         __builtin_amdgcn_global_load_lds((const unsigned*)((const char*)(gbase) + (voff)[_i]), (PG8_LAS unsigned*)(lds + (bufoff) + ldsw + _i * 8192), 16, 0, PG8_BAUX); } while (0)
; #define PG8_LDA(dst, b, h) do { _Pragma("unroll") for (int m = 0; m < 4; ++m) _Pragma("unroll") for (int k = 0; k < 2; ++k) dst[m][k] = *(const PG8_LAS bf16x8*)(lds + PG8_SA(b, h) + aoff + m * 2048 + k * 1024); } while (0)
; #define PG8_LDB(dst, b, h) do { _Pragma("unroll") for (int n = 0; n < 2; ++n) _Pragma("unroll") for (int k = 0; k < 2; ++k) dst[n][k] = *(const PG8_LAS bf16x8*)(lds + PG8_SB(b, h) + boff + n * 2048 + k * 1024); } while (0)
; #define PG8_MMA(ai, bj, At, Bt) do { __builtin_amdgcn_s_setprio(1); _Pragma("unroll") for (int m = 0; m < 4; ++m) _Pragma("unroll") for (int n = 0; n < 2; ++n) _Pragma("unroll") for (int k = 0; k < 2; ++k) \
;         acc[ai][bj][m][n] = __builtin_amdgcn_mfma_f32_16x16x32_bf16(Bt[n][k], At[m][k], acc[ai][bj][m][n], 0, 0, 0); __builtin_amdgcn_s_setprio(0); } while (0)
; #define PG8_WAIT_V(n) asm volatile("s_waitcnt vmcnt(" #n ")" ::: "memory")
; #define PG8_WAIT_L(n) asm volatile("s_waitcnt lgkmcnt(" #n ")" ::: "memory")
; #define PG8_BAR __builtin_amdgcn_s_barrier()
; #define PG8_SCHED __builtin_amdgcn_sched_barrier(0)
; template <class Epi, class Sched, bool ALIGN_EPI = false, bool SP2 = false>
; __device__ __forceinline__ void gemm_phase(PG8_LAS unsigned char* lds, const Gemm g, const Sched& S, const Epi& E) {
;     ...
;             PG8_LDB(B0, 0, 0); PG8_LDB(B1, 0, 1); PG8_SCHED; PG8_LDA(At, 0, 0); PG8_STAGE(PG8_SA(1, 1), a1 + hstep, voffA);
;             PG8_WAIT_V(8); PG8_WAIT_L(0); PG8_BAR; PG8_MMA(0, 0, At, B0); PG8_MMA(0, 1, At, B1); PG8_BAR; PG8_SCHED;
;             PG8_LDA(At, 0, 1); PG8_STAGEB(PG8_SB(0, 0), b2, voffB); PG8_STAGEB(PG8_SB(0, 1), b2 + hstep, voffB); PG8_STAGE(PG8_SA(0, 0), a2, voffA);
.LBB0_1703:
	ds_read_b128 v[154:157], v150
	ds_read_b128 v[158:161], v150 offset:1024
	ds_read_b128 v[162:165], v150 offset:2048
	ds_read_b128 v[166:169], v150 offset:3072
	ds_read_b128 v[170:173], v151
	ds_read_b128 v[174:177], v151 offset:1024
	ds_read_b128 v[178:181], v151 offset:2048
	ds_read_b128 v[182:185], v151 offset:3072
	s_add_u32 s24, s22, 0xfff80080
	s_addc_u32 s25, s23, -1
	s_cmp_eq_u32 s51, 28
	s_cselect_b32 s27, s15, s25
	s_cselect_b32 s26, s47, s24
	s_cselect_b32 s25, s13, s50
	s_cselect_b32 s24, s48, s49
	v_lshl_add_u64 v[220:221], s[22:23], 0, v[138:139]
	s_add_i32 m0, s21, 0xc000
	ds_read_b128 v[186:189], v152
	ds_read_b128 v[192:195], v152 offset:1024
	ds_read_b128 v[196:199], v152 offset:2048
	ds_read_b128 v[200:203], v152 offset:3072
	ds_read_b128 v[204:207], v152 offset:4096
	ds_read_b128 v[208:211], v152 offset:5120
	ds_read_b128 v[212:215], v152 offset:6144
	ds_read_b128 v[216:219], v152 offset:7168
	global_load_lds_dwordx4 v[220:221], off
	v_lshl_add_u64 v[220:221], s[22:23], 0, v[140:141]
	s_add_i32 m0, s21, 0xe000
	s_nop 0
	global_load_lds_dwordx4 v[220:221], off
	s_waitcnt vmcnt(8)
	s_waitcnt lgkmcnt(0)
	s_barrier
	s_waitcnt lgkmcnt(0)
	v_mfma_f32_16x16x32_bf16 v[126:129], v[154:157], v[186:189], v[126:129]
	v_mfma_f32_16x16x32_bf16 v[118:121], v[162:165], v[186:189], v[118:121]
	v_mfma_f32_16x16x32_bf16 v[110:113], v[154:157], v[196:199], v[110:113]
	v_mfma_f32_16x16x32_bf16 v[102:105], v[162:165], v[196:199], v[102:105]
	v_mfma_f32_16x16x32_bf16 v[94:97], v[154:157], v[204:207], v[94:97]
	v_mfma_f32_16x16x32_bf16 v[86:89], v[162:165], v[204:207], v[86:89]
	v_mfma_f32_16x16x32_bf16 v[78:81], v[154:157], v[212:215], v[78:81]
	v_mfma_f32_16x16x32_bf16 v[70:73], v[162:165], v[212:215], v[70:73]
	v_mfma_f32_16x16x32_bf16 v[126:129], v[158:161], v[192:195], v[126:129]
	v_mfma_f32_16x16x32_bf16 v[118:121], v[166:169], v[192:195], v[118:121]
	v_mfma_f32_16x16x32_bf16 v[110:113], v[158:161], v[200:203], v[110:113]
	v_mfma_f32_16x16x32_bf16 v[102:105], v[166:169], v[200:203], v[102:105]
	v_mfma_f32_16x16x32_bf16 v[94:97], v[158:161], v[208:211], v[94:97]
	v_mfma_f32_16x16x32_bf16 v[86:89], v[166:169], v[208:211], v[86:89]
	v_mfma_f32_16x16x32_bf16 v[78:81], v[158:161], v[216:219], v[78:81]
	v_mfma_f32_16x16x32_bf16 v[70:73], v[166:169], v[216:219], v[70:73]
	v_mfma_f32_16x16x32_bf16 v[122:125], v[170:173], v[186:189], v[122:125]
	v_mfma_f32_16x16x32_bf16 v[114:117], v[178:181], v[186:189], v[114:117]
	v_mfma_f32_16x16x32_bf16 v[106:109], v[170:173], v[196:199], v[106:109]
	v_mfma_f32_16x16x32_bf16 v[98:101], v[178:181], v[196:199], v[98:101]
	v_mfma_f32_16x16x32_bf16 v[90:93], v[170:173], v[204:207], v[90:93]
	v_mfma_f32_16x16x32_bf16 v[82:85], v[178:181], v[204:207], v[82:85]
	v_mfma_f32_16x16x32_bf16 v[74:77], v[170:173], v[212:215], v[74:77]
	v_mfma_f32_16x16x32_bf16 v[66:69], v[178:181], v[212:215], v[66:69]
	v_mfma_f32_16x16x32_bf16 v[122:125], v[174:177], v[192:195], v[122:125]
	v_mfma_f32_16x16x32_bf16 v[114:117], v[182:185], v[192:195], v[114:117]
	v_mfma_f32_16x16x32_bf16 v[106:109], v[174:177], v[200:203], v[106:109]
	v_mfma_f32_16x16x32_bf16 v[98:101], v[182:185], v[200:203], v[98:101]
	v_mfma_f32_16x16x32_bf16 v[90:93], v[174:177], v[208:211], v[90:93]
	v_mfma_f32_16x16x32_bf16 v[82:85], v[182:185], v[208:211], v[82:85]
	v_mfma_f32_16x16x32_bf16 v[74:77], v[174:177], v[216:219], v[74:77]
	v_mfma_f32_16x16x32_bf16 v[66:69], v[182:185], v[216:219], v[66:69]
	s_barrier
	s_add_i32 s52, s43, s28
	v_lshl_add_u64 v[220:221], s[24:25], 0, v[134:135]
	s_mov_b32 m0, s52
	ds_read_b128 v[186:189], v152 offset:16384
	ds_read_b128 v[192:195], v152 offset:17408
	ds_read_b128 v[196:199], v152 offset:18432
	ds_read_b128 v[200:203], v152 offset:19456
	ds_read_b128 v[204:207], v152 offset:20480
	ds_read_b128 v[208:211], v152 offset:21504
	ds_read_b128 v[212:215], v152 offset:22528
	ds_read_b128 v[216:219], v152 offset:23552
	global_load_lds_dwordx4 v[220:221], off
	s_add_i32 m0, s52, 0x2000
	s_add_u32 s52, s24, 0x80000
	v_lshl_add_u64 v[222:223], s[24:25], 0, v[130:131]
	s_addc_u32 s53, s25, 0
	s_add_i32 s54, s44, s28
	global_load_lds_dwordx4 v[222:223], off
	v_lshl_add_u64 v[224:225], s[52:53], 0, v[134:135]
	s_mov_b32 m0, s54
	v_lshl_add_u64 v[226:227], s[26:27], 0, v[132:133]
	global_load_lds_dwordx4 v[224:225], off
	v_lshl_add_u64 v[224:225], s[52:53], 0, v[130:131]
	s_add_i32 m0, s54, 0x2000
	s_nop 0
	global_load_lds_dwordx4 v[224:225], off
	v_lshl_add_u64 v[224:225], s[26:27], 0, v[136:137]
	s_mov_b32 m0, s21
	s_nop 0
	global_load_lds_dwordx4 v[224:225], off
	s_mov_b32 m0, s34
	s_nop 0
	global_load_lds_dwordx4 v[226:227], off
	s_waitcnt vmcnt(8)
	s_waitcnt lgkmcnt(0)
	s_barrier
; #define PG8_STAGE(bufoff, gbase, voff) do { _Pragma("unroll") for (int _i = 0; _i < 2; ++_i) \
;         __builtin_amdgcn_global_load_lds((const unsigned*)((const char*)(gbase) + (voff)[_i]), (PG8_LAS unsigned*)(lds + (bufoff) + ldsw + _i * 8192), 16, 0, 0); } while (0)
; #define PG8_LDA(dst, b, h) do { _Pragma("unroll") for (int m = 0; m < 4; ++m) _Pragma("unroll") for (int k = 0; k < 2; ++k) dst[m][k] = *(const PG8_LAS bf16x8*)(lds + PG8_SA(b, h) + aoff + m * 2048 + k * 1024); } while (0)
; #define PG8_LDB(dst, b, h) do { _Pragma("unroll") for (int n = 0; n < 2; ++n) _Pragma("unroll") for (int k = 0; k < 2; ++k) dst[n][k] = *(const PG8_LAS bf16x8*)(lds + PG8_SB(b, h) + boff + n * 2048 + k * 1024); } while (0)
; #define PG8_MMA(ai, bj, At, Bt) do { __builtin_amdgcn_s_setprio(1); _Pragma("unroll") for (int m = 0; m < 4; ++m) _Pragma("unroll") for (int n = 0; n < 2; ++n) _Pragma("unroll") for (int k = 0; k < 2; ++k) \
;         acc[ai][bj][m][n] = __builtin_amdgcn_mfma_f32_16x16x32_bf16(Bt[n][k], At[m][k], acc[ai][bj][m][n], 0, 0, 0); __builtin_amdgcn_s_setprio(0); } while (0)
; #define PG8_WAIT_V(n) asm volatile("s_waitcnt vmcnt(" #n ")" ::: "memory")
; #define PG8_WAIT_L(n) asm volatile("s_waitcnt lgkmcnt(" #n ")" ::: "memory")
; #define PG8_BAR __builtin_amdgcn_s_barrier()
; #define PG8_SCHED __builtin_amdgcn_sched_barrier(0)
; template <class Epi, class Sched, bool ALIGN_EPI = false, bool SP2 = false>
; __device__ __forceinline__ void gemm_phase(PG8_LAS unsigned char* lds, const Gemm g, const Sched& S, const Epi& E) {
;     ...
;             PG8_WAIT_V(8); PG8_WAIT_L(0); PG8_BAR; PG8_MMA(1, 0, At, B0); PG8_MMA(1, 1, At, B1); PG8_BAR; PG8_SCHED;
;             PG8_LDB(B0, 1, 0); PG8_LDB(B1, 1, 1); PG8_SCHED; PG8_LDA(At, 1, 0); PG8_STAGE(PG8_SA(0, 1), a2 + hstep, voffA);
;             PG8_WAIT_V(8); PG8_WAIT_L(0); PG8_BAR; PG8_MMA(0, 0, At, B0); PG8_MMA(0, 1, At, B1); PG8_BAR; PG8_SCHED;
	s_waitcnt lgkmcnt(0)
	v_mfma_f32_16x16x32_bf16 v[62:65], v[154:157], v[186:189], v[62:65]
	v_mfma_f32_16x16x32_bf16 v[54:57], v[162:165], v[186:189], v[54:57]
	v_mfma_f32_16x16x32_bf16 v[46:49], v[154:157], v[196:199], v[46:49]
	v_mfma_f32_16x16x32_bf16 v[38:41], v[162:165], v[196:199], v[38:41]
	v_mfma_f32_16x16x32_bf16 v[30:33], v[154:157], v[204:207], v[30:33]
	v_mfma_f32_16x16x32_bf16 v[22:25], v[162:165], v[204:207], v[22:25]
	v_mfma_f32_16x16x32_bf16 v[14:17], v[154:157], v[212:215], v[14:17]
	v_mfma_f32_16x16x32_bf16 v[6:9], v[162:165], v[212:215], v[6:9]
	v_mfma_f32_16x16x32_bf16 v[62:65], v[158:161], v[192:195], v[62:65]
	v_mfma_f32_16x16x32_bf16 v[54:57], v[166:169], v[192:195], v[54:57]
	v_mfma_f32_16x16x32_bf16 v[46:49], v[158:161], v[200:203], v[46:49]
	v_mfma_f32_16x16x32_bf16 v[38:41], v[166:169], v[200:203], v[38:41]
	v_mfma_f32_16x16x32_bf16 v[30:33], v[158:161], v[208:211], v[30:33]
	v_mfma_f32_16x16x32_bf16 v[22:25], v[166:169], v[208:211], v[22:25]
	v_mfma_f32_16x16x32_bf16 v[14:17], v[158:161], v[216:219], v[14:17]
	v_mfma_f32_16x16x32_bf16 v[6:9], v[166:169], v[216:219], v[6:9]
	v_mfma_f32_16x16x32_bf16 v[58:61], v[170:173], v[186:189], v[58:61]
	v_mfma_f32_16x16x32_bf16 v[50:53], v[178:181], v[186:189], v[50:53]
	v_mfma_f32_16x16x32_bf16 v[42:45], v[170:173], v[196:199], v[42:45]
	v_mfma_f32_16x16x32_bf16 v[34:37], v[178:181], v[196:199], v[34:37]
	v_mfma_f32_16x16x32_bf16 v[26:29], v[170:173], v[204:207], v[26:29]
	v_mfma_f32_16x16x32_bf16 v[18:21], v[178:181], v[204:207], v[18:21]
	v_mfma_f32_16x16x32_bf16 v[10:13], v[170:173], v[212:215], v[10:13]
	v_mfma_f32_16x16x32_bf16 v[2:5], v[178:181], v[212:215], v[2:5]
	v_mfma_f32_16x16x32_bf16 v[58:61], v[174:177], v[192:195], v[58:61]
	v_mfma_f32_16x16x32_bf16 v[50:53], v[182:185], v[192:195], v[50:53]
	v_mfma_f32_16x16x32_bf16 v[42:45], v[174:177], v[200:203], v[42:45]
	v_mfma_f32_16x16x32_bf16 v[34:37], v[182:185], v[200:203], v[34:37]
	v_mfma_f32_16x16x32_bf16 v[26:29], v[174:177], v[208:211], v[26:29]
	v_mfma_f32_16x16x32_bf16 v[18:21], v[182:185], v[208:211], v[18:21]
	v_mfma_f32_16x16x32_bf16 v[10:13], v[174:177], v[216:219], v[10:13]
	v_mfma_f32_16x16x32_bf16 v[2:5], v[182:185], v[216:219], v[2:5]
	s_barrier
	s_add_i32 s52, 0, 0x18000
	v_add_u32_e32 v153, s52, v147
	s_add_i32 s53, 0, 0x1c000
	ds_read_b128 v[154:157], v153
	ds_read_b128 v[158:161], v153 offset:1024
	ds_read_b128 v[162:165], v153 offset:2048
	ds_read_b128 v[166:169], v153 offset:3072
	v_add_u32_e32 v153, s53, v147
	ds_read_b128 v[170:173], v153
	ds_read_b128 v[174:177], v153 offset:1024
	ds_read_b128 v[178:181], v153 offset:2048
	ds_read_b128 v[182:185], v153 offset:3072
	s_add_u32 s26, s26, 0x80000
	s_addc_u32 s27, s27, 0
	s_mov_b32 m0, s35
	v_lshl_add_u64 v[228:229], s[26:27], 0, v[136:137]
	ds_read_b128 v[186:189], v152 offset:32768
	ds_read_b128 v[192:195], v152 offset:33792
	ds_read_b128 v[196:199], v152 offset:34816
	ds_read_b128 v[200:203], v152 offset:35840
	ds_read_b128 v[204:207], v152 offset:36864
	ds_read_b128 v[208:211], v152 offset:37888
	ds_read_b128 v[212:215], v152 offset:38912
	ds_read_b128 v[216:219], v152 offset:39936
	global_load_lds_dwordx4 v[228:229], off
	v_lshl_add_u64 v[228:229], s[26:27], 0, v[132:133]
	s_mov_b32 m0, s38
	s_nop 0
	global_load_lds_dwordx4 v[228:229], off
	s_waitcnt vmcnt(8)
	s_waitcnt lgkmcnt(0)
	s_barrier
	s_waitcnt lgkmcnt(0)
	v_mfma_f32_16x16x32_bf16 v[126:129], v[154:157], v[186:189], v[126:129]
	v_mfma_f32_16x16x32_bf16 v[118:121], v[162:165], v[186:189], v[118:121]
	v_mfma_f32_16x16x32_bf16 v[110:113], v[154:157], v[196:199], v[110:113]
	v_mfma_f32_16x16x32_bf16 v[102:105], v[162:165], v[196:199], v[102:105]
	v_mfma_f32_16x16x32_bf16 v[94:97], v[154:157], v[204:207], v[94:97]
	v_mfma_f32_16x16x32_bf16 v[86:89], v[162:165], v[204:207], v[86:89]
	v_mfma_f32_16x16x32_bf16 v[78:81], v[154:157], v[212:215], v[78:81]
	v_mfma_f32_16x16x32_bf16 v[70:73], v[162:165], v[212:215], v[70:73]
	v_mfma_f32_16x16x32_bf16 v[126:129], v[158:161], v[192:195], v[126:129]
	v_mfma_f32_16x16x32_bf16 v[118:121], v[166:169], v[192:195], v[118:121]
	v_mfma_f32_16x16x32_bf16 v[110:113], v[158:161], v[200:203], v[110:113]
	v_mfma_f32_16x16x32_bf16 v[102:105], v[166:169], v[200:203], v[102:105]
	v_mfma_f32_16x16x32_bf16 v[94:97], v[158:161], v[208:211], v[94:97]
	v_mfma_f32_16x16x32_bf16 v[86:89], v[166:169], v[208:211], v[86:89]
	v_mfma_f32_16x16x32_bf16 v[78:81], v[158:161], v[216:219], v[78:81]
	v_mfma_f32_16x16x32_bf16 v[70:73], v[166:169], v[216:219], v[70:73]
	v_mfma_f32_16x16x32_bf16 v[122:125], v[170:173], v[186:189], v[122:125]
	v_mfma_f32_16x16x32_bf16 v[114:117], v[178:181], v[186:189], v[114:117]
	v_mfma_f32_16x16x32_bf16 v[106:109], v[170:173], v[196:199], v[106:109]
	v_mfma_f32_16x16x32_bf16 v[98:101], v[178:181], v[196:199], v[98:101]
	v_mfma_f32_16x16x32_bf16 v[90:93], v[170:173], v[204:207], v[90:93]
	v_mfma_f32_16x16x32_bf16 v[82:85], v[178:181], v[204:207], v[82:85]
	v_mfma_f32_16x16x32_bf16 v[74:77], v[170:173], v[212:215], v[74:77]
	v_mfma_f32_16x16x32_bf16 v[66:69], v[178:181], v[212:215], v[66:69]
	v_mfma_f32_16x16x32_bf16 v[122:125], v[174:177], v[192:195], v[122:125]
	v_mfma_f32_16x16x32_bf16 v[114:117], v[182:185], v[192:195], v[114:117]
	v_mfma_f32_16x16x32_bf16 v[106:109], v[174:177], v[200:203], v[106:109]
	v_mfma_f32_16x16x32_bf16 v[98:101], v[182:185], v[200:203], v[98:101]
	v_mfma_f32_16x16x32_bf16 v[90:93], v[174:177], v[208:211], v[90:93]
	v_mfma_f32_16x16x32_bf16 v[82:85], v[182:185], v[208:211], v[82:85]
	v_mfma_f32_16x16x32_bf16 v[74:77], v[174:177], v[216:219], v[74:77]
	v_mfma_f32_16x16x32_bf16 v[66:69], v[182:185], v[216:219], v[66:69]
	s_barrier
; #define PG8_STAGE(bufoff, gbase, voff) do { _Pragma("unroll") for (int _i = 0; _i < 2; ++_i) \
;         __builtin_amdgcn_global_load_lds((const unsigned*)((const char*)(gbase) + (voff)[_i]), (PG8_LAS unsigned*)(lds + (bufoff) + ldsw + _i * 8192), 16, 0, 0); } while (0)
; #define PG8_STAGEB(bufoff, gbase, voff) do { _Pragma("unroll") for (int _i = 0; _i < 2; ++_i) \
;         __builtin_amdgcn_global_load_lds((const unsigned*)((const char*)(gbase) + (voff)[_i]), (PG8_LAS unsigned*)(lds + (bufoff) + ldsw + _i * 8192), 16, 0, PG8_BAUX); } while (0)
; #define PG8_LDA(dst, b, h) do { _Pragma("unroll") for (int m = 0; m < 4; ++m) _Pragma("unroll") for (int k = 0; k < 2; ++k) dst[m][k] = *(const PG8_LAS bf16x8*)(lds + PG8_SA(b, h) + aoff + m * 2048 + k * 1024); } while (0)
; #define PG8_MMA(ai, bj, At, Bt) do { __builtin_amdgcn_s_setprio(1); _Pragma("unroll") for (int m = 0; m < 4; ++m) _Pragma("unroll") for (int n = 0; n < 2; ++n) _Pragma("unroll") for (int k = 0; k < 2; ++k) \
;         acc[ai][bj][m][n] = __builtin_amdgcn_mfma_f32_16x16x32_bf16(Bt[n][k], At[m][k], acc[ai][bj][m][n], 0, 0, 0); __builtin_amdgcn_s_setprio(0); } while (0)
; #define PG8_WAIT_V(n) asm volatile("s_waitcnt vmcnt(" #n ")" ::: "memory")
; #define PG8_WAIT_L(n) asm volatile("s_waitcnt lgkmcnt(" #n ")" ::: "memory")
; #define PG8_BAR __builtin_amdgcn_s_barrier()
; #define PG8_SCHED __builtin_amdgcn_sched_barrier(0)
; template <class Epi, class Sched, bool ALIGN_EPI = false, bool SP2 = false>
; __device__ __forceinline__ void gemm_phase(PG8_LAS unsigned char* lds, const Gemm g, const Sched& S, const Epi& E) {
;     ...
;             PG8_LDA(At, 1, 1); PG8_STAGEB(PG8_SB(1, 0), b3, voffB); PG8_STAGEB(PG8_SB(1, 1), b3 + hstep, voffB); PG8_STAGE(PG8_SA(1, 0), a3, voffA);
;             PG8_WAIT_V(8); PG8_WAIT_L(0); PG8_BAR; PG8_MMA(1, 0, At, B0); PG8_MMA(1, 1, At, B1); PG8_BAR; PG8_SCHED;
	s_add_i32 s26, s52, s28
	v_lshl_add_u64 v[220:221], v[220:221], 0, s[8:9]
	s_mov_b32 m0, s26
	ds_read_b128 v[186:189], v152 offset:49152
	ds_read_b128 v[192:195], v152 offset:50176
	ds_read_b128 v[196:199], v152 offset:51200
	ds_read_b128 v[200:203], v152 offset:52224
	ds_read_b128 v[204:207], v152 offset:53248
	ds_read_b128 v[208:211], v152 offset:54272
	ds_read_b128 v[212:215], v152 offset:55296
	ds_read_b128 v[216:219], v152 offset:56320
	global_load_lds_dwordx4 v[220:221], off
	s_add_i32 m0, s26, 0x2000
	s_add_u32 s24, s24, 0x80080
	v_lshl_add_u64 v[220:221], v[222:223], 0, s[8:9]
	s_addc_u32 s25, s25, 0
	s_add_i32 s26, s53, s28
	global_load_lds_dwordx4 v[220:221], off
	v_lshl_add_u64 v[220:221], s[24:25], 0, v[134:135]
	s_mov_b32 m0, s26
	s_nop 0
	global_load_lds_dwordx4 v[220:221], off
	v_lshl_add_u64 v[220:221], s[24:25], 0, v[130:131]
	s_add_i32 m0, s26, 0x2000
	s_nop 0
	global_load_lds_dwordx4 v[220:221], off
	v_lshl_add_u64 v[220:221], v[224:225], 0, s[8:9]
	s_mov_b32 m0, s40
	s_nop 0
	global_load_lds_dwordx4 v[220:221], off
	v_lshl_add_u64 v[220:221], v[226:227], 0, s[8:9]
	s_mov_b32 m0, s41
	s_nop 0
	global_load_lds_dwordx4 v[220:221], off
	s_waitcnt vmcnt(8)
	s_waitcnt lgkmcnt(0)
	s_barrier
	s_waitcnt lgkmcnt(0)
	v_mfma_f32_16x16x32_bf16 v[62:65], v[154:157], v[186:189], v[62:65]
	v_mfma_f32_16x16x32_bf16 v[54:57], v[162:165], v[186:189], v[54:57]
	v_mfma_f32_16x16x32_bf16 v[46:49], v[154:157], v[196:199], v[46:49]
	v_mfma_f32_16x16x32_bf16 v[38:41], v[162:165], v[196:199], v[38:41]
	v_mfma_f32_16x16x32_bf16 v[30:33], v[154:157], v[204:207], v[30:33]
	v_mfma_f32_16x16x32_bf16 v[22:25], v[162:165], v[204:207], v[22:25]
	v_mfma_f32_16x16x32_bf16 v[14:17], v[154:157], v[212:215], v[14:17]
	v_mfma_f32_16x16x32_bf16 v[6:9], v[162:165], v[212:215], v[6:9]
	v_mfma_f32_16x16x32_bf16 v[62:65], v[158:161], v[192:195], v[62:65]
	v_mfma_f32_16x16x32_bf16 v[54:57], v[166:169], v[192:195], v[54:57]
	v_mfma_f32_16x16x32_bf16 v[46:49], v[158:161], v[200:203], v[46:49]
	v_mfma_f32_16x16x32_bf16 v[38:41], v[166:169], v[200:203], v[38:41]
	v_mfma_f32_16x16x32_bf16 v[30:33], v[158:161], v[208:211], v[30:33]
	v_mfma_f32_16x16x32_bf16 v[22:25], v[166:169], v[208:211], v[22:25]
	v_mfma_f32_16x16x32_bf16 v[14:17], v[158:161], v[216:219], v[14:17]
	v_mfma_f32_16x16x32_bf16 v[6:9], v[166:169], v[216:219], v[6:9]
	v_mfma_f32_16x16x32_bf16 v[58:61], v[170:173], v[186:189], v[58:61]
	v_mfma_f32_16x16x32_bf16 v[50:53], v[178:181], v[186:189], v[50:53]
	v_mfma_f32_16x16x32_bf16 v[42:45], v[170:173], v[196:199], v[42:45]
	v_mfma_f32_16x16x32_bf16 v[34:37], v[178:181], v[196:199], v[34:37]
	v_mfma_f32_16x16x32_bf16 v[26:29], v[170:173], v[204:207], v[26:29]
	v_mfma_f32_16x16x32_bf16 v[18:21], v[178:181], v[204:207], v[18:21]
	v_mfma_f32_16x16x32_bf16 v[10:13], v[170:173], v[212:215], v[10:13]
	v_mfma_f32_16x16x32_bf16 v[2:5], v[178:181], v[212:215], v[2:5]
	v_mfma_f32_16x16x32_bf16 v[58:61], v[174:177], v[192:195], v[58:61]
	v_mfma_f32_16x16x32_bf16 v[50:53], v[182:185], v[192:195], v[50:53]
	v_mfma_f32_16x16x32_bf16 v[42:45], v[174:177], v[200:203], v[42:45]
	v_mfma_f32_16x16x32_bf16 v[34:37], v[182:185], v[200:203], v[34:37]
	v_mfma_f32_16x16x32_bf16 v[26:29], v[174:177], v[208:211], v[26:29]
	v_mfma_f32_16x16x32_bf16 v[18:21], v[182:185], v[208:211], v[18:21]
	v_mfma_f32_16x16x32_bf16 v[10:13], v[174:177], v[216:219], v[10:13]
	v_mfma_f32_16x16x32_bf16 v[2:5], v[182:185], v[216:219], v[2:5]
	s_barrier
	s_add_i32 s51, s51, 2
	s_add_u32 s22, s22, 0x100
	s_addc_u32 s23, s23, 0
	s_add_u32 s49, s49, 0x100
	s_addc_u32 s50, s50, 0
	s_cmp_gt_u32 s51, 29
	s_cbranch_scc0 .LBB0_1703
	s_and_b64 vcc, exec, s[10:11]
	s_cbranch_vccz .LBB0_1706
	s_barrier

; #define PG8_STAGE(bufoff, gbase, voff) do { _Pragma("unroll") for (int _i = 0; _i < 2; ++_i) \
;         __builtin_amdgcn_global_load_lds((const unsigned*)((const char*)(gbase) + (voff)[_i]), (PG8_LAS unsigned*)(lds + (bufoff) + ldsw + _i * 8192), 16, 0, 0); } while (0)
; #define PG8_STAGEB(bufoff, gbase, voff) do { _Pragma("unroll") for (int _i = 0; _i < 2; ++_i) \
;         __builtin_amdgcn_global_load_lds((const unsigned*)((const char*)(gbase) + (voff)[_i]), (PG8_LAS unsigned*)(lds + (bufoff) + ldsw + _i * 8192), 16, 0, PG8_BAUX); } while (0)
; #define PG8_LDA(dst, b, h) do { _Pragma("unroll") for (int m = 0; m < 4; ++m) _Pragma("unroll") for (int k = 0; k < 2; ++k) dst[m][k] = *(const PG8_LAS bf16x8*)(lds + PG8_SA(b, h) + aoff + m * 2048 + k * 1024); } while (0)
; #define PG8_LDB(dst, b, h) do { _Pragma("unroll") for (int n = 0; n < 2; ++n) _Pragma("unroll") for (int k = 0; k < 2; ++k) dst[n][k] = *(const PG8_LAS bf16x8*)(lds + PG8_SB(b, h) + boff + n * 2048 + k * 1024); } while (0)
; #define PG8_MMA(ai, bj, At, Bt) do { __builtin_amdgcn_s_setprio(1); _Pragma("unroll") for (int m = 0; m < 4; ++m) _Pragma("unroll") for (int n = 0; n < 2; ++n) _Pragma("unroll") for (int k = 0; k < 2; ++k) \
;         acc[ai][bj][m][n] = __builtin_amdgcn_mfma_f32_16x16x32_bf16(Bt[n][k], At[m][k], acc[ai][bj][m][n], 0, 0, 0); __builtin_amdgcn_s_setprio(0); } while (0)
; #define PG8_WAIT_V(n) asm volatile("s_waitcnt vmcnt(" #n ")" ::: "memory")
; #define PG8_WAIT_L(n) asm volatile("s_waitcnt lgkmcnt(" #n ")" ::: "memory")
; #define PG8_BAR __builtin_amdgcn_s_barrier()
; #define PG8_SCHED __builtin_amdgcn_sched_barrier(0)
; template <class Epi, class Sched, bool ALIGN_EPI = false, bool SP2 = false>
; __device__ __forceinline__ void gemm_phase(PG8_LAS unsigned char* lds, const Gemm g, const Sched& S, const Epi& E) {
;     ...
;             PG8_LDB(B0, 0, 0); PG8_LDB(B1, 0, 1); PG8_SCHED; PG8_LDA(At, 0, 0); PG8_STAGE(PG8_SA(1, 1), a1 + hstep, voffA);
;             PG8_WAIT_V(8); PG8_WAIT_L(0); PG8_BAR; PG8_MMA(0, 0, At, B0); PG8_MMA(0, 1, At, B1); PG8_BAR; PG8_SCHED;
;             PG8_LDA(At, 0, 1); PG8_STAGEB(PG8_SB(0, 0), b2, voffB); PG8_STAGEB(PG8_SB(0, 1), b2 + hstep, voffB); PG8_STAGE(PG8_SA(0, 0), a2, voffA);
.LBB0_1906:
	v_add_u32_e32 v153, s43, v151
	ds_read_b128 v[154:157], v153
	ds_read_b128 v[158:161], v153 offset:1024
	ds_read_b128 v[166:169], v153 offset:2048
	ds_read_b128 v[170:173], v153 offset:3072
	v_add_u32_e32 v153, s44, v151
	s_add_u32 s22, s12, s20
	ds_read_b128 v[174:177], v153
	ds_read_b128 v[178:181], v153 offset:1024
	ds_read_b128 v[182:185], v153 offset:2048
	ds_read_b128 v[186:189], v153 offset:3072
	s_addc_u32 s23, s13, s21
	s_add_u32 s22, s22, 0x100
	s_addc_u32 s23, s23, 0
	s_add_u32 s49, s17, s20
	s_addc_u32 s50, s47, s21
	s_cmpk_eq_i32 s20, 0x2b00
	s_cselect_b32 s25, s19, s23
	s_cselect_b32 s24, s18, s22
	s_cselect_b32 s23, s5, s50
	s_cselect_b32 s22, s4, s49
	v_lshl_add_u64 v[162:163], v[146:147], 0, s[20:21]
	s_add_i32 m0, s34, 0xc000
	ds_read_b128 v[192:195], v152
	ds_read_b128 v[196:199], v152 offset:1024
	ds_read_b128 v[200:203], v152 offset:2048
	ds_read_b128 v[204:207], v152 offset:3072
	ds_read_b128 v[208:211], v152 offset:4096
	ds_read_b128 v[212:215], v152 offset:5120
	ds_read_b128 v[216:219], v152 offset:6144
	ds_read_b128 v[220:223], v152 offset:7168
	global_load_lds_dwordx4 v[162:163], off
	v_lshl_add_u64 v[162:163], v[148:149], 0, s[20:21]
	s_add_i32 m0, s34, 0xe000
	s_nop 0
	global_load_lds_dwordx4 v[162:163], off
	s_waitcnt vmcnt(8)
	s_waitcnt lgkmcnt(0)
	s_barrier
	s_waitcnt lgkmcnt(0)
	v_mfma_f32_16x16x32_bf16 v[126:129], v[154:157], v[192:195], v[126:129]
	v_mfma_f32_16x16x32_bf16 v[122:125], v[166:169], v[192:195], v[122:125]
	v_mfma_f32_16x16x32_bf16 v[110:113], v[154:157], v[200:203], v[110:113]
	v_mfma_f32_16x16x32_bf16 v[106:109], v[166:169], v[200:203], v[106:109]
	v_mfma_f32_16x16x32_bf16 v[94:97], v[154:157], v[208:211], v[94:97]
	v_mfma_f32_16x16x32_bf16 v[90:93], v[166:169], v[208:211], v[90:93]
	v_mfma_f32_16x16x32_bf16 v[78:81], v[154:157], v[216:219], v[78:81]
	v_mfma_f32_16x16x32_bf16 v[74:77], v[166:169], v[216:219], v[74:77]
	v_mfma_f32_16x16x32_bf16 v[126:129], v[158:161], v[196:199], v[126:129]
	v_mfma_f32_16x16x32_bf16 v[122:125], v[170:173], v[196:199], v[122:125]
	v_mfma_f32_16x16x32_bf16 v[110:113], v[158:161], v[204:207], v[110:113]
	v_mfma_f32_16x16x32_bf16 v[106:109], v[170:173], v[204:207], v[106:109]
	v_mfma_f32_16x16x32_bf16 v[94:97], v[158:161], v[212:215], v[94:97]
	v_mfma_f32_16x16x32_bf16 v[90:93], v[170:173], v[212:215], v[90:93]
	v_mfma_f32_16x16x32_bf16 v[78:81], v[158:161], v[220:223], v[78:81]
	v_mfma_f32_16x16x32_bf16 v[74:77], v[170:173], v[220:223], v[74:77]
	v_mfma_f32_16x16x32_bf16 v[118:121], v[174:177], v[192:195], v[118:121]
	v_mfma_f32_16x16x32_bf16 v[114:117], v[182:185], v[192:195], v[114:117]
	v_mfma_f32_16x16x32_bf16 v[102:105], v[174:177], v[200:203], v[102:105]
	v_mfma_f32_16x16x32_bf16 v[98:101], v[182:185], v[200:203], v[98:101]
	v_mfma_f32_16x16x32_bf16 v[86:89], v[174:177], v[208:211], v[86:89]
	v_mfma_f32_16x16x32_bf16 v[82:85], v[182:185], v[208:211], v[82:85]
	v_mfma_f32_16x16x32_bf16 v[70:73], v[174:177], v[216:219], v[70:73]
	v_mfma_f32_16x16x32_bf16 v[66:69], v[182:185], v[216:219], v[66:69]
	v_mfma_f32_16x16x32_bf16 v[118:121], v[178:181], v[196:199], v[118:121]
	v_mfma_f32_16x16x32_bf16 v[114:117], v[186:189], v[196:199], v[114:117]
	v_mfma_f32_16x16x32_bf16 v[102:105], v[178:181], v[204:207], v[102:105]
	v_mfma_f32_16x16x32_bf16 v[98:101], v[186:189], v[204:207], v[98:101]
	v_mfma_f32_16x16x32_bf16 v[86:89], v[178:181], v[212:215], v[86:89]
	v_mfma_f32_16x16x32_bf16 v[82:85], v[186:189], v[212:215], v[82:85]
	v_mfma_f32_16x16x32_bf16 v[70:73], v[178:181], v[220:223], v[70:73]
	v_mfma_f32_16x16x32_bf16 v[66:69], v[186:189], v[220:223], v[66:69]
	s_barrier
	s_add_i32 s49, s43, s30
	v_lshl_add_u64 v[162:163], s[22:23], 0, v[132:133]
	s_mov_b32 m0, s49
	ds_read_b128 v[192:195], v152 offset:16384
	ds_read_b128 v[196:199], v152 offset:17408
	ds_read_b128 v[200:203], v152 offset:18432
	ds_read_b128 v[204:207], v152 offset:19456
	ds_read_b128 v[208:211], v152 offset:20480
	ds_read_b128 v[212:215], v152 offset:21504
	ds_read_b128 v[216:219], v152 offset:22528
	ds_read_b128 v[220:223], v152 offset:23552
	global_load_lds_dwordx4 v[162:163], off
	s_add_i32 m0, s49, 0x2000
	s_add_u32 s50, s22, 0x160000
	v_lshl_add_u64 v[224:225], s[22:23], 0, v[136:137]
	s_addc_u32 s51, s23, 0
	s_add_i32 s49, s44, s30
	global_load_lds_dwordx4 v[224:225], off
	v_lshl_add_u64 v[226:227], s[50:51], 0, v[132:133]
	s_mov_b32 m0, s49
	v_lshl_add_u64 v[228:229], s[24:25], 0, v[134:135]
	global_load_lds_dwordx4 v[226:227], off
	v_lshl_add_u64 v[226:227], s[50:51], 0, v[136:137]
	s_add_i32 m0, s49, 0x2000
	s_nop 0
	global_load_lds_dwordx4 v[226:227], off
	v_lshl_add_u64 v[226:227], s[24:25], 0, v[130:131]
	s_mov_b32 m0, s34
	s_nop 0
	global_load_lds_dwordx4 v[226:227], off
	s_mov_b32 m0, s35
	s_nop 0
	global_load_lds_dwordx4 v[228:229], off
	s_waitcnt vmcnt(8)
	s_waitcnt lgkmcnt(0)
	s_barrier
; #define PG8_STAGE(bufoff, gbase, voff) do { _Pragma("unroll") for (int _i = 0; _i < 2; ++_i) \
;         __builtin_amdgcn_global_load_lds((const unsigned*)((const char*)(gbase) + (voff)[_i]), (PG8_LAS unsigned*)(lds + (bufoff) + ldsw + _i * 8192), 16, 0, 0); } while (0)
; #define PG8_LDA(dst, b, h) do { _Pragma("unroll") for (int m = 0; m < 4; ++m) _Pragma("unroll") for (int k = 0; k < 2; ++k) dst[m][k] = *(const PG8_LAS bf16x8*)(lds + PG8_SA(b, h) + aoff + m * 2048 + k * 1024); } while (0)
; #define PG8_LDB(dst, b, h) do { _Pragma("unroll") for (int n = 0; n < 2; ++n) _Pragma("unroll") for (int k = 0; k < 2; ++k) dst[n][k] = *(const PG8_LAS bf16x8*)(lds + PG8_SB(b, h) + boff + n * 2048 + k * 1024); } while (0)
; #define PG8_MMA(ai, bj, At, Bt) do { __builtin_amdgcn_s_setprio(1); _Pragma("unroll") for (int m = 0; m < 4; ++m) _Pragma("unroll") for (int n = 0; n < 2; ++n) _Pragma("unroll") for (int k = 0; k < 2; ++k) \
;         acc[ai][bj][m][n] = __builtin_amdgcn_mfma_f32_16x16x32_bf16(Bt[n][k], At[m][k], acc[ai][bj][m][n], 0, 0, 0); __builtin_amdgcn_s_setprio(0); } while (0)
; #define PG8_WAIT_V(n) asm volatile("s_waitcnt vmcnt(" #n ")" ::: "memory")
; #define PG8_WAIT_L(n) asm volatile("s_waitcnt lgkmcnt(" #n ")" ::: "memory")
; #define PG8_BAR __builtin_amdgcn_s_barrier()
; #define PG8_SCHED __builtin_amdgcn_sched_barrier(0)
; template <class Epi, class Sched, bool ALIGN_EPI = false, bool SP2 = false>
; __device__ __forceinline__ void gemm_phase(PG8_LAS unsigned char* lds, const Gemm g, const Sched& S, const Epi& E) {
;     ...
;             PG8_WAIT_V(8); PG8_WAIT_L(0); PG8_BAR; PG8_MMA(1, 0, At, B0); PG8_MMA(1, 1, At, B1); PG8_BAR; PG8_SCHED;
;             PG8_LDB(B0, 1, 0); PG8_LDB(B1, 1, 1); PG8_SCHED; PG8_LDA(At, 1, 0); PG8_STAGE(PG8_SA(0, 1), a2 + hstep, voffA);
;             PG8_WAIT_V(8); PG8_WAIT_L(0); PG8_BAR; PG8_MMA(0, 0, At, B0); PG8_MMA(0, 1, At, B1); PG8_BAR; PG8_SCHED;
	s_waitcnt lgkmcnt(0)
	v_mfma_f32_16x16x32_bf16 v[62:65], v[154:157], v[192:195], v[62:65]
	v_mfma_f32_16x16x32_bf16 v[58:61], v[166:169], v[192:195], v[58:61]
	v_mfma_f32_16x16x32_bf16 v[46:49], v[154:157], v[200:203], v[46:49]
	v_mfma_f32_16x16x32_bf16 v[42:45], v[166:169], v[200:203], v[42:45]
	v_mfma_f32_16x16x32_bf16 v[30:33], v[154:157], v[208:211], v[30:33]
	v_mfma_f32_16x16x32_bf16 v[26:29], v[166:169], v[208:211], v[26:29]
	v_mfma_f32_16x16x32_bf16 v[14:17], v[154:157], v[216:219], v[14:17]
	v_mfma_f32_16x16x32_bf16 v[10:13], v[166:169], v[216:219], v[10:13]
	v_mfma_f32_16x16x32_bf16 v[62:65], v[158:161], v[196:199], v[62:65]
	v_mfma_f32_16x16x32_bf16 v[58:61], v[170:173], v[196:199], v[58:61]
	v_mfma_f32_16x16x32_bf16 v[46:49], v[158:161], v[204:207], v[46:49]
	v_mfma_f32_16x16x32_bf16 v[42:45], v[170:173], v[204:207], v[42:45]
	v_mfma_f32_16x16x32_bf16 v[30:33], v[158:161], v[212:215], v[30:33]
	v_mfma_f32_16x16x32_bf16 v[26:29], v[170:173], v[212:215], v[26:29]
	v_mfma_f32_16x16x32_bf16 v[14:17], v[158:161], v[220:223], v[14:17]
	v_mfma_f32_16x16x32_bf16 v[10:13], v[170:173], v[220:223], v[10:13]
	v_mfma_f32_16x16x32_bf16 v[54:57], v[174:177], v[192:195], v[54:57]
	v_mfma_f32_16x16x32_bf16 v[50:53], v[182:185], v[192:195], v[50:53]
	v_mfma_f32_16x16x32_bf16 v[38:41], v[174:177], v[200:203], v[38:41]
	v_mfma_f32_16x16x32_bf16 v[34:37], v[182:185], v[200:203], v[34:37]
	v_mfma_f32_16x16x32_bf16 v[22:25], v[174:177], v[208:211], v[22:25]
	v_mfma_f32_16x16x32_bf16 v[18:21], v[182:185], v[208:211], v[18:21]
	v_mfma_f32_16x16x32_bf16 v[6:9], v[174:177], v[216:219], v[6:9]
	v_mfma_f32_16x16x32_bf16 v[2:5], v[182:185], v[216:219], v[2:5]
	v_mfma_f32_16x16x32_bf16 v[54:57], v[178:181], v[196:199], v[54:57]
	v_mfma_f32_16x16x32_bf16 v[50:53], v[186:189], v[196:199], v[50:53]
	v_mfma_f32_16x16x32_bf16 v[38:41], v[178:181], v[204:207], v[38:41]
	v_mfma_f32_16x16x32_bf16 v[34:37], v[186:189], v[204:207], v[34:37]
	v_mfma_f32_16x16x32_bf16 v[22:25], v[178:181], v[212:215], v[22:25]
	v_mfma_f32_16x16x32_bf16 v[18:21], v[186:189], v[212:215], v[18:21]
	v_mfma_f32_16x16x32_bf16 v[6:9], v[178:181], v[220:223], v[6:9]
	v_mfma_f32_16x16x32_bf16 v[2:5], v[186:189], v[220:223], v[2:5]
	s_barrier
	s_add_i32 s49, 0, 0x18000
	v_add_u32_e32 v153, s49, v151
	s_add_i32 s50, 0, 0x1c000
	ds_read_b128 v[154:157], v153
	ds_read_b128 v[158:161], v153 offset:1024
	ds_read_b128 v[166:169], v153 offset:2048
	ds_read_b128 v[170:173], v153 offset:3072
	v_add_u32_e32 v153, s50, v151
	ds_read_b128 v[174:177], v153
	ds_read_b128 v[178:181], v153 offset:1024
	ds_read_b128 v[182:185], v153 offset:2048
	ds_read_b128 v[186:189], v153 offset:3072
	s_add_u32 s24, s24, 0x160000
	s_addc_u32 s25, s25, 0
	s_mov_b32 m0, s38
	v_lshl_add_u64 v[230:231], s[24:25], 0, v[130:131]
	ds_read_b128 v[192:195], v152 offset:32768
	ds_read_b128 v[196:199], v152 offset:33792
	ds_read_b128 v[200:203], v152 offset:34816
	ds_read_b128 v[204:207], v152 offset:35840
	ds_read_b128 v[208:211], v152 offset:36864
	ds_read_b128 v[212:215], v152 offset:37888
	ds_read_b128 v[216:219], v152 offset:38912
	ds_read_b128 v[220:223], v152 offset:39936
	global_load_lds_dwordx4 v[230:231], off
	v_lshl_add_u64 v[230:231], s[24:25], 0, v[134:135]
	s_mov_b32 m0, s39
	s_nop 0
	global_load_lds_dwordx4 v[230:231], off
	s_waitcnt vmcnt(8)
	s_waitcnt lgkmcnt(0)
	s_barrier
	s_waitcnt lgkmcnt(0)
	v_mfma_f32_16x16x32_bf16 v[126:129], v[154:157], v[192:195], v[126:129]
	v_mfma_f32_16x16x32_bf16 v[122:125], v[166:169], v[192:195], v[122:125]
	v_mfma_f32_16x16x32_bf16 v[110:113], v[154:157], v[200:203], v[110:113]
	v_mfma_f32_16x16x32_bf16 v[106:109], v[166:169], v[200:203], v[106:109]
	v_mfma_f32_16x16x32_bf16 v[94:97], v[154:157], v[208:211], v[94:97]
	v_mfma_f32_16x16x32_bf16 v[90:93], v[166:169], v[208:211], v[90:93]
	v_mfma_f32_16x16x32_bf16 v[78:81], v[154:157], v[216:219], v[78:81]
	v_mfma_f32_16x16x32_bf16 v[74:77], v[166:169], v[216:219], v[74:77]
	v_mfma_f32_16x16x32_bf16 v[126:129], v[158:161], v[196:199], v[126:129]
	v_mfma_f32_16x16x32_bf16 v[122:125], v[170:173], v[196:199], v[122:125]
	v_mfma_f32_16x16x32_bf16 v[110:113], v[158:161], v[204:207], v[110:113]
	v_mfma_f32_16x16x32_bf16 v[106:109], v[170:173], v[204:207], v[106:109]
	v_mfma_f32_16x16x32_bf16 v[94:97], v[158:161], v[212:215], v[94:97]
	v_mfma_f32_16x16x32_bf16 v[90:93], v[170:173], v[212:215], v[90:93]
	v_mfma_f32_16x16x32_bf16 v[78:81], v[158:161], v[220:223], v[78:81]
	v_mfma_f32_16x16x32_bf16 v[74:77], v[170:173], v[220:223], v[74:77]
	v_mfma_f32_16x16x32_bf16 v[118:121], v[174:177], v[192:195], v[118:121]
	v_mfma_f32_16x16x32_bf16 v[114:117], v[182:185], v[192:195], v[114:117]
	v_mfma_f32_16x16x32_bf16 v[102:105], v[174:177], v[200:203], v[102:105]
	v_mfma_f32_16x16x32_bf16 v[98:101], v[182:185], v[200:203], v[98:101]
	v_mfma_f32_16x16x32_bf16 v[86:89], v[174:177], v[208:211], v[86:89]
	v_mfma_f32_16x16x32_bf16 v[82:85], v[182:185], v[208:211], v[82:85]
	v_mfma_f32_16x16x32_bf16 v[70:73], v[174:177], v[216:219], v[70:73]
	v_mfma_f32_16x16x32_bf16 v[66:69], v[182:185], v[216:219], v[66:69]
	v_mfma_f32_16x16x32_bf16 v[118:121], v[178:181], v[196:199], v[118:121]
	v_mfma_f32_16x16x32_bf16 v[114:117], v[186:189], v[196:199], v[114:117]
	v_mfma_f32_16x16x32_bf16 v[102:105], v[178:181], v[204:207], v[102:105]
	v_mfma_f32_16x16x32_bf16 v[98:101], v[186:189], v[204:207], v[98:101]
	v_mfma_f32_16x16x32_bf16 v[86:89], v[178:181], v[212:215], v[86:89]
	v_mfma_f32_16x16x32_bf16 v[82:85], v[186:189], v[212:215], v[82:85]
	v_mfma_f32_16x16x32_bf16 v[70:73], v[178:181], v[220:223], v[70:73]
	v_mfma_f32_16x16x32_bf16 v[66:69], v[186:189], v[220:223], v[66:69]
	s_barrier
; #define PG8_STAGE(bufoff, gbase, voff) do { _Pragma("unroll") for (int _i = 0; _i < 2; ++_i) \
;         __builtin_amdgcn_global_load_lds((const unsigned*)((const char*)(gbase) + (voff)[_i]), (PG8_LAS unsigned*)(lds + (bufoff) + ldsw + _i * 8192), 16, 0, 0); } while (0)
; #define PG8_STAGEB(bufoff, gbase, voff) do { _Pragma("unroll") for (int _i = 0; _i < 2; ++_i) \
;         __builtin_amdgcn_global_load_lds((const unsigned*)((const char*)(gbase) + (voff)[_i]), (PG8_LAS unsigned*)(lds + (bufoff) + ldsw + _i * 8192), 16, 0, PG8_BAUX); } while (0)
; #define PG8_LDA(dst, b, h) do { _Pragma("unroll") for (int m = 0; m < 4; ++m) _Pragma("unroll") for (int k = 0; k < 2; ++k) dst[m][k] = *(const PG8_LAS bf16x8*)(lds + PG8_SA(b, h) + aoff + m * 2048 + k * 1024); } while (0)
; #define PG8_MMA(ai, bj, At, Bt) do { __builtin_amdgcn_s_setprio(1); _Pragma("unroll") for (int m = 0; m < 4; ++m) _Pragma("unroll") for (int n = 0; n < 2; ++n) _Pragma("unroll") for (int k = 0; k < 2; ++k) \
;         acc[ai][bj][m][n] = __builtin_amdgcn_mfma_f32_16x16x32_bf16(Bt[n][k], At[m][k], acc[ai][bj][m][n], 0, 0, 0); __builtin_amdgcn_s_setprio(0); } while (0)
; #define PG8_WAIT_V(n) asm volatile("s_waitcnt vmcnt(" #n ")" ::: "memory")
; #define PG8_WAIT_L(n) asm volatile("s_waitcnt lgkmcnt(" #n ")" ::: "memory")
; #define PG8_BAR __builtin_amdgcn_s_barrier()
; #define PG8_SCHED __builtin_amdgcn_sched_barrier(0)
; template <class Epi, class Sched, bool ALIGN_EPI = false, bool SP2 = false>
; __device__ __forceinline__ void gemm_phase(PG8_LAS unsigned char* lds, const Gemm g, const Sched& S, const Epi& E) {
;     ...
;             PG8_LDA(At, 1, 1); PG8_STAGEB(PG8_SB(1, 0), b3, voffB); PG8_STAGEB(PG8_SB(1, 1), b3 + hstep, voffB); PG8_STAGE(PG8_SA(1, 0), a3, voffA);
;             PG8_WAIT_V(8); PG8_WAIT_L(0); PG8_BAR; PG8_MMA(1, 0, At, B0); PG8_MMA(1, 1, At, B1); PG8_BAR; PG8_SCHED;
;     ...
;         if (!has_next) break;
; #pragma unroll
;         for (int a = 0; a < 2; ++a)
; #pragma unroll
;             for (int b = 0; b < 2; ++b)
; #pragma unroll
;                 for (int m = 0; m < 4; ++m)
; #pragma unroll
;                     for (int n = 0; n < 2; ++n) acc[a][b][m][n] = (f32x4){0.f, 0.f, 0.f, 0.f};
;         cur = nxt; cA = nA; cB = nB; ++ui;
	s_add_i32 s24, s49, s30
	v_lshl_add_u64 v[162:163], v[162:163], 0, s[14:15]
	s_mov_b32 m0, s24
	ds_read_b128 v[192:195], v152 offset:49152
	ds_read_b128 v[196:199], v152 offset:50176
	ds_read_b128 v[200:203], v152 offset:51200
	ds_read_b128 v[204:207], v152 offset:52224
	ds_read_b128 v[208:211], v152 offset:53248
	ds_read_b128 v[212:215], v152 offset:54272
	ds_read_b128 v[216:219], v152 offset:55296
	ds_read_b128 v[220:223], v152 offset:56320
	global_load_lds_dwordx4 v[162:163], off
	s_add_i32 m0, s24, 0x2000
	s_add_u32 s22, s22, 0x160080
	v_lshl_add_u64 v[162:163], v[224:225], 0, s[14:15]
	s_addc_u32 s23, s23, 0
	s_add_i32 s24, s50, s30
	global_load_lds_dwordx4 v[162:163], off
	v_lshl_add_u64 v[162:163], s[22:23], 0, v[132:133]
	s_mov_b32 m0, s24
	s_nop 0
	global_load_lds_dwordx4 v[162:163], off
	v_lshl_add_u64 v[162:163], s[22:23], 0, v[136:137]
	s_add_i32 m0, s24, 0x2000
	s_nop 0
	global_load_lds_dwordx4 v[162:163], off
	v_lshl_add_u64 v[162:163], v[226:227], 0, s[14:15]
	s_mov_b32 m0, s40
	s_nop 0
	global_load_lds_dwordx4 v[162:163], off
	v_lshl_add_u64 v[162:163], v[228:229], 0, s[14:15]
	s_mov_b32 m0, s41
	s_nop 0
	global_load_lds_dwordx4 v[162:163], off
	s_waitcnt vmcnt(8)
	s_waitcnt lgkmcnt(0)
	s_barrier
	s_waitcnt lgkmcnt(0)
	v_mfma_f32_16x16x32_bf16 v[62:65], v[154:157], v[192:195], v[62:65]
	v_mfma_f32_16x16x32_bf16 v[58:61], v[166:169], v[192:195], v[58:61]
	v_mfma_f32_16x16x32_bf16 v[46:49], v[154:157], v[200:203], v[46:49]
	v_mfma_f32_16x16x32_bf16 v[42:45], v[166:169], v[200:203], v[42:45]
	v_mfma_f32_16x16x32_bf16 v[30:33], v[154:157], v[208:211], v[30:33]
	v_mfma_f32_16x16x32_bf16 v[26:29], v[166:169], v[208:211], v[26:29]
	v_mfma_f32_16x16x32_bf16 v[14:17], v[154:157], v[216:219], v[14:17]
	v_mfma_f32_16x16x32_bf16 v[10:13], v[166:169], v[216:219], v[10:13]
	v_mfma_f32_16x16x32_bf16 v[62:65], v[158:161], v[196:199], v[62:65]
	v_mfma_f32_16x16x32_bf16 v[58:61], v[170:173], v[196:199], v[58:61]
	v_mfma_f32_16x16x32_bf16 v[46:49], v[158:161], v[204:207], v[46:49]
	v_mfma_f32_16x16x32_bf16 v[42:45], v[170:173], v[204:207], v[42:45]
	v_mfma_f32_16x16x32_bf16 v[30:33], v[158:161], v[212:215], v[30:33]
	v_mfma_f32_16x16x32_bf16 v[26:29], v[170:173], v[212:215], v[26:29]
	v_mfma_f32_16x16x32_bf16 v[14:17], v[158:161], v[220:223], v[14:17]
	v_mfma_f32_16x16x32_bf16 v[10:13], v[170:173], v[220:223], v[10:13]
	v_mfma_f32_16x16x32_bf16 v[54:57], v[174:177], v[192:195], v[54:57]
	v_mfma_f32_16x16x32_bf16 v[50:53], v[182:185], v[192:195], v[50:53]
	v_mfma_f32_16x16x32_bf16 v[38:41], v[174:177], v[200:203], v[38:41]
	v_mfma_f32_16x16x32_bf16 v[34:37], v[182:185], v[200:203], v[34:37]
	v_mfma_f32_16x16x32_bf16 v[22:25], v[174:177], v[208:211], v[22:25]
	v_mfma_f32_16x16x32_bf16 v[18:21], v[182:185], v[208:211], v[18:21]
	v_mfma_f32_16x16x32_bf16 v[6:9], v[174:177], v[216:219], v[6:9]
	v_mfma_f32_16x16x32_bf16 v[2:5], v[182:185], v[216:219], v[2:5]
	v_mfma_f32_16x16x32_bf16 v[54:57], v[178:181], v[196:199], v[54:57]
	v_mfma_f32_16x16x32_bf16 v[50:53], v[186:189], v[196:199], v[50:53]
	v_mfma_f32_16x16x32_bf16 v[38:41], v[178:181], v[204:207], v[38:41]
	v_mfma_f32_16x16x32_bf16 v[34:37], v[186:189], v[204:207], v[34:37]
	v_mfma_f32_16x16x32_bf16 v[22:25], v[178:181], v[212:215], v[22:25]
	v_mfma_f32_16x16x32_bf16 v[18:21], v[186:189], v[212:215], v[18:21]
	v_mfma_f32_16x16x32_bf16 v[6:9], v[178:181], v[220:223], v[6:9]
	v_mfma_f32_16x16x32_bf16 v[2:5], v[186:189], v[220:223], v[2:5]
	s_barrier
	s_add_i32 s48, s48, 2
	s_add_u32 s20, s20, 0x100
	s_addc_u32 s21, s21, 0
	s_cmpk_gt_u32 s48, 0x55
	s_cbranch_scc0 .LBB0_1906
	s_add_u32 s20, s17, 0xffffff00
	s_addc_u32 s21, s47, -1
	s_and_b64 vcc, exec, s[2:3]
	s_cbranch_vccnz .LBB0_1893
	v_mov_b32_e32 v2, 0
	s_mov_b32 s10, s45
	s_mov_b32 s27, s46
	s_mov_b64 s[12:13], s[18:19]
	s_mov_b32 s42, s16
	v_mov_b32_e32 v3, v2
	v_mov_b32_e32 v4, v2
	v_mov_b32_e32 v5, v2
	v_mov_b32_e32 v6, v2
	v_mov_b32_e32 v7, v2
	v_mov_b32_e32 v8, v2
	v_mov_b32_e32 v9, v2
	v_mov_b32_e32 v18, v2
	v_mov_b32_e32 v19, v2
	v_mov_b32_e32 v20, v2
	v_mov_b32_e32 v21, v2
	v_mov_b32_e32 v22, v2
	v_mov_b32_e32 v23, v2
	v_mov_b32_e32 v24, v2
	v_mov_b32_e32 v25, v2
	v_mov_b32_e32 v34, v2
	v_mov_b32_e32 v35, v2
	v_mov_b32_e32 v36, v2
	v_mov_b32_e32 v37, v2
	v_mov_b32_e32 v38, v2
	v_mov_b32_e32 v39, v2
	v_mov_b32_e32 v40, v2
	v_mov_b32_e32 v41, v2
	v_mov_b32_e32 v50, v2
	v_mov_b32_e32 v51, v2
	v_mov_b32_e32 v52, v2
	v_mov_b32_e32 v53, v2
	v_mov_b32_e32 v54, v2
	v_mov_b32_e32 v55, v2
	v_mov_b32_e32 v56, v2
	v_mov_b32_e32 v57, v2
	v_mov_b32_e32 v10, v2
	v_mov_b32_e32 v11, v2
	v_mov_b32_e32 v12, v2
	v_mov_b32_e32 v13, v2
	v_mov_b32_e32 v14, v2
	v_mov_b32_e32 v15, v2
	v_mov_b32_e32 v16, v2
	v_mov_b32_e32 v17, v2
	v_mov_b32_e32 v26, v2
	v_mov_b32_e32 v27, v2
	v_mov_b32_e32 v28, v2
	v_mov_b32_e32 v29, v2
	v_mov_b32_e32 v30, v2
	v_mov_b32_e32 v31, v2
	v_mov_b32_e32 v32, v2
	v_mov_b32_e32 v33, v2
	v_mov_b32_e32 v42, v2
	v_mov_b32_e32 v43, v2
	v_mov_b32_e32 v44, v2
	v_mov_b32_e32 v45, v2
	v_mov_b32_e32 v46, v2
	v_mov_b32_e32 v47, v2
	v_mov_b32_e32 v48, v2
	v_mov_b32_e32 v49, v2
	v_mov_b32_e32 v58, v2
	v_mov_b32_e32 v59, v2
	v_mov_b32_e32 v60, v2
	v_mov_b32_e32 v61, v2
	v_mov_b32_e32 v62, v2
	v_mov_b32_e32 v63, v2
	v_mov_b32_e32 v64, v2
	v_mov_b32_e32 v65, v2
	v_mov_b32_e32 v66, v2
	v_mov_b32_e32 v67, v2
	v_mov_b32_e32 v68, v2
	v_mov_b32_e32 v69, v2
	v_mov_b32_e32 v70, v2
	v_mov_b32_e32 v71, v2
	v_mov_b32_e32 v72, v2
	v_mov_b32_e32 v73, v2
	v_mov_b32_e32 v82, v2
	v_mov_b32_e32 v83, v2
	v_mov_b32_e32 v84, v2
	v_mov_b32_e32 v85, v2
	v_mov_b32_e32 v86, v2
	v_mov_b32_e32 v87, v2
	v_mov_b32_e32 v88, v2
	v_mov_b32_e32 v89, v2
	v_mov_b32_e32 v98, v2
	v_mov_b32_e32 v99, v2
	v_mov_b32_e32 v100, v2
	v_mov_b32_e32 v101, v2
	v_mov_b32_e32 v102, v2
	v_mov_b32_e32 v103, v2
	v_mov_b32_e32 v104, v2
	v_mov_b32_e32 v105, v2
	v_mov_b32_e32 v114, v2
	v_mov_b32_e32 v115, v2
	v_mov_b32_e32 v116, v2
	v_mov_b32_e32 v117, v2
	v_mov_b32_e32 v118, v2
	v_mov_b32_e32 v119, v2
	v_mov_b32_e32 v120, v2
	v_mov_b32_e32 v121, v2
	v_mov_b32_e32 v74, v2
	v_mov_b32_e32 v75, v2
	v_mov_b32_e32 v76, v2
	v_mov_b32_e32 v77, v2
	v_mov_b32_e32 v78, v2
	v_mov_b32_e32 v79, v2
	v_mov_b32_e32 v80, v2
	v_mov_b32_e32 v81, v2
	v_mov_b32_e32 v90, v2
	v_mov_b32_e32 v91, v2
	v_mov_b32_e32 v92, v2
	v_mov_b32_e32 v93, v2
	v_mov_b32_e32 v94, v2
	v_mov_b32_e32 v95, v2
	v_mov_b32_e32 v96, v2
	v_mov_b32_e32 v97, v2
	v_mov_b32_e32 v106, v2
	v_mov_b32_e32 v107, v2
	v_mov_b32_e32 v108, v2
	v_mov_b32_e32 v109, v2
	v_mov_b32_e32 v110, v2
	v_mov_b32_e32 v111, v2
	v_mov_b32_e32 v112, v2
	v_mov_b32_e32 v113, v2
	v_mov_b32_e32 v122, v2
	v_mov_b32_e32 v123, v2
	v_mov_b32_e32 v124, v2
	v_mov_b32_e32 v125, v2
	v_mov_b32_e32 v126, v2
	v_mov_b32_e32 v127, v2
	v_mov_b32_e32 v128, v2
	v_mov_b32_e32 v129, v2
	s_andn2_b64 vcc, exec, s[0:1]
	s_cbranch_vccnz .LBB0_1894
